# 16x16x32 attention + halved lgkmcnt waits, next-unit K/V/Q prefetch across unit seam, phase-0 queue claim hoisted, shiftw loops pipelined, rstd_prestep unrolled (loads first)
# speedup vs baseline: 1.0610x; 1.0089x over previous
.LBB0_26:
	s_and_saveexec_b64 s[80:81], s[4:5]
	v_mov_b32_e32 v120, 1
	v_mov_b32_e32 v121, 0
	global_atomic_add v120, v121, v120, s[10:11] sc0
	s_mov_b64 exec, s[80:81]
	s_cmpk_gt_i32 s94, 0x5f
	s_mov_b64 s[6:7], -1
	s_cbranch_scc0 .LBB0_73
	s_cmpk_gt_u32 s94, 0x55f
	s_cbranch_scc0 .LBB0_35
	s_cmpk_lg_i32 s94, 0x564
	s_cbranch_scc0 .LBB0_30
	s_lshl_b32 s6, s94, 6
	s_add_i32 s6, s6, 0xfffea800
	v_or_b32_e32 v56, s6, v78
	v_lshlrev_b32_e32 v2, 4, v56
	v_mul_lo_u32 v3, v2, v54
	v_add_u32_e32 v4, 0xc00, v3
	v_cndmask_b32_e64 v4, v4, v3, s[0:1]
	v_add_u32_e32 v3, v3, v2
	v_add_u32_e32 v5, 0xc00, v3
	v_cndmask_b32_e64 v5, v5, v3, s[0:1]
	v_add_u32_e32 v3, v3, v2
	v_add_u32_e32 v6, 0xc00, v3
	v_cndmask_b32_e64 v6, v6, v3, s[0:1]
	v_add_u32_e32 v3, v3, v2
	v_add_u32_e32 v7, 0xc00, v3
	v_cndmask_b32_e64 v7, v7, v3, s[0:1]
	v_add_u32_e32 v3, v3, v2
	v_add_u32_e32 v8, 0xc00, v3
	v_cndmask_b32_e64 v8, v8, v3, s[0:1]
	v_add_u32_e32 v3, v3, v2
	v_add_u32_e32 v9, 0xc00, v3
	v_cndmask_b32_e64 v9, v9, v3, s[0:1]
	v_add_u32_e32 v3, v3, v2
	v_add_u32_e32 v10, 0xc00, v3
	v_add_u32_e32 v2, v3, v2
	v_cndmask_b32_e64 v10, v10, v3, s[0:1]
	v_add_u32_e32 v3, 0xc00, v2
	v_and_b32_e32 v4, 0xf80, v4
	v_and_b32_e32 v5, 0xff0, v5
	v_and_b32_e32 v6, 0xfe0, v6
	v_and_b32_e32 v7, 0xff0, v7
	v_and_b32_e32 v8, 0xfc0, v8
	v_and_b32_e32 v9, 0xff0, v9
	v_cndmask_b32_e64 v2, v3, v2, s[0:1]
	v_lshl_add_u32 v4, v4, 2, s3
	v_lshl_add_u32 v5, v5, 2, s3
	v_lshl_add_u32 v6, v6, 2, s3
	v_lshl_add_u32 v7, v7, 2, s3
	v_lshl_add_u32 v8, v8, 2, s3
	v_lshl_add_u32 v9, v9, 2, s3
	v_and_b32_e32 v10, 0xfe0, v10
	v_and_b32_e32 v2, 0xff0, v2
	v_lshl_add_u32 v10, v10, 2, s3
	v_lshl_add_u32 v11, v2, 2, s3
	ds_read_b32 v2, v4
	ds_read_b32 v3, v5
	ds_read_b32 v4, v6
	ds_read_b32 v5, v7
	ds_read_b32 v6, v8
	ds_read_b32 v7, v9
	ds_read_b32 v8, v10
	ds_read_b32 v9, v11
	s_waitcnt lgkmcnt(6)
	v_pk_mul_f32 v[2:3], v[2:3], 4.0 op_sel_hi:[1,0]
	s_waitcnt lgkmcnt(4)
	v_pk_mul_f32 v[4:5], v[4:5], 4.0 op_sel_hi:[1,0]
	s_waitcnt lgkmcnt(2)
	v_pk_mul_f32 v[6:7], v[6:7], 4.0 op_sel_hi:[1,0]
	v_cvt_pk_bf16_f32 v2, v2, v3
	s_waitcnt lgkmcnt(0)
	v_pk_mul_f32 v[8:9], v[8:9], 4.0 op_sel_hi:[1,0]
	v_cvt_pk_bf16_f32 v3, v4, v5
	v_cvt_pk_bf16_f32 v4, v6, v7
	v_lshlrev_b64 v[6:7], 10, v[56:57]
	v_or_b32_e32 v56, s6, v83
	v_cvt_pk_bf16_f32 v5, v8, v9
	v_lshlrev_b32_e32 v8, 4, v56
	v_mul_lo_u32 v9, v8, v54
	v_add_u32_e32 v10, 0xc00, v9
	v_cndmask_b32_e64 v10, v10, v9, s[0:1]
	v_add_u32_e32 v9, v9, v8
	v_add_u32_e32 v11, 0xc00, v9
	v_cndmask_b32_e64 v11, v11, v9, s[0:1]
	v_add_u32_e32 v9, v9, v8
	v_add_u32_e32 v12, 0xc00, v9
	v_cndmask_b32_e64 v12, v12, v9, s[0:1]
	v_add_u32_e32 v9, v9, v8
	v_add_u32_e32 v13, 0xc00, v9
	v_cndmask_b32_e64 v13, v13, v9, s[0:1]
	v_add_u32_e32 v9, v9, v8
	v_add_u32_e32 v14, 0xc00, v9
	v_cndmask_b32_e64 v14, v14, v9, s[0:1]
	v_add_u32_e32 v9, v9, v8
	v_add_u32_e32 v15, 0xc00, v9
	v_cndmask_b32_e64 v15, v15, v9, s[0:1]
	v_add_u32_e32 v9, v9, v8
	v_add_u32_e32 v16, 0xc00, v9
	v_add_u32_e32 v8, v9, v8
	v_cndmask_b32_e64 v16, v16, v9, s[0:1]
	v_add_u32_e32 v9, 0xc00, v8
	v_and_b32_e32 v10, 0xf80, v10
	v_and_b32_e32 v11, 0xff0, v11
	v_and_b32_e32 v12, 0xfe0, v12
	v_and_b32_e32 v13, 0xff0, v13
	v_and_b32_e32 v14, 0xfc0, v14
	v_and_b32_e32 v15, 0xff0, v15
	v_cndmask_b32_e64 v8, v9, v8, s[0:1]
	v_lshl_add_u32 v10, v10, 2, s3
	v_lshl_add_u32 v11, v11, 2, s3
	v_lshl_add_u32 v12, v12, 2, s3
	v_lshl_add_u32 v13, v13, 2, s3
	v_lshl_add_u32 v14, v14, 2, s3
	v_lshl_add_u32 v15, v15, 2, s3
	v_and_b32_e32 v16, 0xfe0, v16
	v_and_b32_e32 v8, 0xff0, v8
	v_lshl_add_u32 v16, v16, 2, s3
	v_lshl_add_u32 v17, v8, 2, s3
	ds_read_b32 v8, v10
	ds_read_b32 v9, v11
	ds_read_b32 v10, v12
	ds_read_b32 v11, v13
	ds_read_b32 v12, v14
	ds_read_b32 v13, v15
	ds_read_b32 v14, v16
	ds_read_b32 v15, v17
	v_lshl_add_u64 v[6:7], v[58:59], 0, v[6:7]
	global_store_dwordx4 v[6:7], v[2:5], off
	s_waitcnt lgkmcnt(2)
	v_pk_mul_f32 v[6:7], v[12:13], 4.0 op_sel_hi:[1,0]
	v_pk_mul_f32 v[2:3], v[8:9], 4.0 op_sel_hi:[1,0]
	v_pk_mul_f32 v[4:5], v[10:11], 4.0 op_sel_hi:[1,0]
	s_waitcnt lgkmcnt(0)
	v_pk_mul_f32 v[8:9], v[14:15], 4.0 op_sel_hi:[1,0]
	v_cvt_pk_bf16_f32 v2, v2, v3
	v_cvt_pk_bf16_f32 v3, v4, v5
	v_cvt_pk_bf16_f32 v4, v6, v7
	v_lshlrev_b64 v[6:7], 10, v[56:57]
	v_or_b32_e32 v56, s6, v84
	v_cvt_pk_bf16_f32 v5, v8, v9
	v_lshlrev_b32_e32 v8, 4, v56
	v_mul_lo_u32 v9, v8, v54
	v_add_u32_e32 v10, 0xc00, v9
	v_cndmask_b32_e64 v10, v10, v9, s[0:1]
	v_add_u32_e32 v9, v9, v8
	v_add_u32_e32 v11, 0xc00, v9
	v_cndmask_b32_e64 v11, v11, v9, s[0:1]
	v_add_u32_e32 v9, v9, v8
	v_add_u32_e32 v12, 0xc00, v9
	v_cndmask_b32_e64 v12, v12, v9, s[0:1]
	v_add_u32_e32 v9, v9, v8
	v_add_u32_e32 v13, 0xc00, v9
	v_cndmask_b32_e64 v13, v13, v9, s[0:1]
	v_add_u32_e32 v9, v9, v8
	v_add_u32_e32 v14, 0xc00, v9
	v_cndmask_b32_e64 v14, v14, v9, s[0:1]
	v_add_u32_e32 v9, v9, v8
	v_add_u32_e32 v15, 0xc00, v9
	v_cndmask_b32_e64 v15, v15, v9, s[0:1]
	v_add_u32_e32 v9, v9, v8
	v_add_u32_e32 v16, 0xc00, v9
	v_add_u32_e32 v8, v9, v8
	v_cndmask_b32_e64 v16, v16, v9, s[0:1]
	v_add_u32_e32 v9, 0xc00, v8
	v_and_b32_e32 v10, 0xf80, v10
	v_and_b32_e32 v11, 0xff0, v11
	v_and_b32_e32 v12, 0xfe0, v12
	v_and_b32_e32 v13, 0xff0, v13
	v_and_b32_e32 v14, 0xfc0, v14
	v_and_b32_e32 v15, 0xff0, v15
	v_cndmask_b32_e64 v8, v9, v8, s[0:1]
	v_lshl_add_u32 v10, v10, 2, s3
	v_lshl_add_u32 v11, v11, 2, s3
	v_lshl_add_u32 v12, v12, 2, s3
	v_lshl_add_u32 v13, v13, 2, s3
	v_lshl_add_u32 v14, v14, 2, s3
	v_lshl_add_u32 v15, v15, 2, s3
	v_and_b32_e32 v16, 0xfe0, v16
	v_and_b32_e32 v8, 0xff0, v8
	v_lshl_add_u32 v16, v16, 2, s3
	v_lshl_add_u32 v17, v8, 2, s3
	ds_read_b32 v8, v10
	ds_read_b32 v9, v11
	ds_read_b32 v10, v12
	ds_read_b32 v11, v13
	ds_read_b32 v12, v14
	ds_read_b32 v13, v15
	ds_read_b32 v14, v16
	ds_read_b32 v15, v17
	v_lshl_add_u64 v[6:7], v[58:59], 0, v[6:7]
	global_store_dwordx4 v[6:7], v[2:5], off
	s_waitcnt lgkmcnt(2)
	v_pk_mul_f32 v[6:7], v[12:13], 4.0 op_sel_hi:[1,0]
	v_pk_mul_f32 v[2:3], v[8:9], 4.0 op_sel_hi:[1,0]
	v_pk_mul_f32 v[4:5], v[10:11], 4.0 op_sel_hi:[1,0]
	s_waitcnt lgkmcnt(0)
	v_pk_mul_f32 v[8:9], v[14:15], 4.0 op_sel_hi:[1,0]
	v_cvt_pk_bf16_f32 v2, v2, v3
	v_cvt_pk_bf16_f32 v3, v4, v5
	v_cvt_pk_bf16_f32 v4, v6, v7
	v_lshlrev_b64 v[6:7], 10, v[56:57]
	v_or_b32_e32 v56, s6, v85
	v_cvt_pk_bf16_f32 v5, v8, v9
	v_lshlrev_b32_e32 v8, 4, v56
	v_mul_lo_u32 v9, v8, v54
	v_add_u32_e32 v10, 0xc00, v9
	v_cndmask_b32_e64 v10, v10, v9, s[0:1]
	v_add_u32_e32 v9, v9, v8
	v_add_u32_e32 v11, 0xc00, v9
	v_cndmask_b32_e64 v11, v11, v9, s[0:1]
	v_add_u32_e32 v9, v9, v8
	v_add_u32_e32 v12, 0xc00, v9
	v_cndmask_b32_e64 v12, v12, v9, s[0:1]
	v_add_u32_e32 v9, v9, v8
	v_add_u32_e32 v13, 0xc00, v9
	v_cndmask_b32_e64 v13, v13, v9, s[0:1]
	v_add_u32_e32 v9, v9, v8
	v_add_u32_e32 v14, 0xc00, v9
	v_cndmask_b32_e64 v14, v14, v9, s[0:1]
	v_add_u32_e32 v9, v9, v8
	v_add_u32_e32 v15, 0xc00, v9
	v_cndmask_b32_e64 v15, v15, v9, s[0:1]
	v_add_u32_e32 v9, v9, v8
	v_add_u32_e32 v16, 0xc00, v9
	v_add_u32_e32 v8, v9, v8
	v_cndmask_b32_e64 v16, v16, v9, s[0:1]
	v_add_u32_e32 v9, 0xc00, v8
	v_and_b32_e32 v10, 0xf80, v10
	v_and_b32_e32 v11, 0xff0, v11
	v_and_b32_e32 v12, 0xfe0, v12
	v_and_b32_e32 v13, 0xff0, v13
	v_and_b32_e32 v14, 0xfc0, v14
	v_and_b32_e32 v15, 0xff0, v15
	v_cndmask_b32_e64 v8, v9, v8, s[0:1]
	v_lshl_add_u32 v10, v10, 2, s3
	v_lshl_add_u32 v11, v11, 2, s3
	v_lshl_add_u32 v12, v12, 2, s3
	v_lshl_add_u32 v13, v13, 2, s3
	v_lshl_add_u32 v14, v14, 2, s3
	v_lshl_add_u32 v15, v15, 2, s3
	v_and_b32_e32 v16, 0xfe0, v16
	v_and_b32_e32 v8, 0xff0, v8
	v_lshl_add_u32 v16, v16, 2, s3
	v_lshl_add_u32 v17, v8, 2, s3
	ds_read_b32 v8, v10
	ds_read_b32 v9, v11
	ds_read_b32 v10, v12
	ds_read_b32 v11, v13
	ds_read_b32 v12, v14
	ds_read_b32 v13, v15
	ds_read_b32 v14, v16
	ds_read_b32 v15, v17
	v_lshl_add_u64 v[6:7], v[58:59], 0, v[6:7]
	global_store_dwordx4 v[6:7], v[2:5], off
	s_waitcnt lgkmcnt(2)
	v_pk_mul_f32 v[6:7], v[12:13], 4.0 op_sel_hi:[1,0]
	v_pk_mul_f32 v[2:3], v[8:9], 4.0 op_sel_hi:[1,0]
	v_pk_mul_f32 v[4:5], v[10:11], 4.0 op_sel_hi:[1,0]
	s_waitcnt lgkmcnt(0)
	v_pk_mul_f32 v[8:9], v[14:15], 4.0 op_sel_hi:[1,0]
	v_cvt_pk_bf16_f32 v2, v2, v3
	v_cvt_pk_bf16_f32 v3, v4, v5
	v_cvt_pk_bf16_f32 v4, v6, v7
	v_lshlrev_b64 v[6:7], 10, v[56:57]
	v_or_b32_e32 v56, s6, v86
	v_cvt_pk_bf16_f32 v5, v8, v9
	v_lshlrev_b32_e32 v8, 4, v56
	v_mul_lo_u32 v9, v8, v54
	v_add_u32_e32 v10, 0xc00, v9
	v_cndmask_b32_e64 v10, v10, v9, s[0:1]
	v_add_u32_e32 v9, v9, v8
	v_add_u32_e32 v11, 0xc00, v9
	v_cndmask_b32_e64 v11, v11, v9, s[0:1]
	v_add_u32_e32 v9, v9, v8
	v_add_u32_e32 v12, 0xc00, v9
	v_cndmask_b32_e64 v12, v12, v9, s[0:1]
	v_add_u32_e32 v9, v9, v8
	v_add_u32_e32 v13, 0xc00, v9
	v_cndmask_b32_e64 v13, v13, v9, s[0:1]
	v_add_u32_e32 v9, v9, v8
	v_add_u32_e32 v14, 0xc00, v9
	v_cndmask_b32_e64 v14, v14, v9, s[0:1]
	v_add_u32_e32 v9, v9, v8
	v_add_u32_e32 v15, 0xc00, v9
	v_cndmask_b32_e64 v15, v15, v9, s[0:1]
	v_add_u32_e32 v9, v9, v8
	v_add_u32_e32 v16, 0xc00, v9
	v_add_u32_e32 v8, v9, v8
	v_cndmask_b32_e64 v16, v16, v9, s[0:1]
	v_add_u32_e32 v9, 0xc00, v8
	v_and_b32_e32 v10, 0xf80, v10
	v_and_b32_e32 v11, 0xff0, v11
	v_and_b32_e32 v12, 0xfe0, v12
	v_and_b32_e32 v13, 0xff0, v13
	v_and_b32_e32 v14, 0xfc0, v14
	v_and_b32_e32 v15, 0xff0, v15
	v_cndmask_b32_e64 v8, v9, v8, s[0:1]
	v_lshl_add_u32 v10, v10, 2, s3
	v_lshl_add_u32 v11, v11, 2, s3
	v_lshl_add_u32 v12, v12, 2, s3
	v_lshl_add_u32 v13, v13, 2, s3
	v_lshl_add_u32 v14, v14, 2, s3
	v_lshl_add_u32 v15, v15, 2, s3
	v_and_b32_e32 v16, 0xfe0, v16
	v_and_b32_e32 v8, 0xff0, v8
	v_lshl_add_u32 v16, v16, 2, s3
	v_lshl_add_u32 v17, v8, 2, s3
	ds_read_b32 v8, v10
	ds_read_b32 v9, v11
	ds_read_b32 v10, v12
	ds_read_b32 v11, v13
	ds_read_b32 v12, v14
	ds_read_b32 v13, v15
	ds_read_b32 v14, v16
	ds_read_b32 v15, v17
	v_lshl_add_u64 v[6:7], v[58:59], 0, v[6:7]
	global_store_dwordx4 v[6:7], v[2:5], off
	s_waitcnt lgkmcnt(2)
	v_pk_mul_f32 v[6:7], v[12:13], 4.0 op_sel_hi:[1,0]
	v_pk_mul_f32 v[2:3], v[8:9], 4.0 op_sel_hi:[1,0]
	v_pk_mul_f32 v[4:5], v[10:11], 4.0 op_sel_hi:[1,0]
	s_waitcnt lgkmcnt(0)
	v_pk_mul_f32 v[8:9], v[14:15], 4.0 op_sel_hi:[1,0]
	v_cvt_pk_bf16_f32 v2, v2, v3
	v_cvt_pk_bf16_f32 v3, v4, v5
	v_cvt_pk_bf16_f32 v4, v6, v7
	v_lshlrev_b64 v[6:7], 10, v[56:57]
	v_or_b32_e32 v56, s6, v87
	v_cvt_pk_bf16_f32 v5, v8, v9
	v_lshlrev_b32_e32 v8, 4, v56
	v_mul_lo_u32 v9, v8, v54
	v_add_u32_e32 v10, 0xc00, v9
	v_cndmask_b32_e64 v10, v10, v9, s[0:1]
	v_add_u32_e32 v9, v9, v8
	v_add_u32_e32 v11, 0xc00, v9
	v_cndmask_b32_e64 v11, v11, v9, s[0:1]
	v_add_u32_e32 v9, v9, v8
	v_add_u32_e32 v12, 0xc00, v9
	v_cndmask_b32_e64 v12, v12, v9, s[0:1]
	v_add_u32_e32 v9, v9, v8
	v_add_u32_e32 v13, 0xc00, v9
	v_cndmask_b32_e64 v13, v13, v9, s[0:1]
	v_add_u32_e32 v9, v9, v8
	v_add_u32_e32 v14, 0xc00, v9
	v_cndmask_b32_e64 v14, v14, v9, s[0:1]
	v_add_u32_e32 v9, v9, v8
	v_add_u32_e32 v15, 0xc00, v9
	v_cndmask_b32_e64 v15, v15, v9, s[0:1]
	v_add_u32_e32 v9, v9, v8
	v_add_u32_e32 v16, 0xc00, v9
	v_add_u32_e32 v8, v9, v8
	v_cndmask_b32_e64 v16, v16, v9, s[0:1]
	v_add_u32_e32 v9, 0xc00, v8
	v_and_b32_e32 v10, 0xf80, v10
	v_and_b32_e32 v11, 0xff0, v11
	v_and_b32_e32 v12, 0xfe0, v12
	v_and_b32_e32 v13, 0xff0, v13
	v_and_b32_e32 v14, 0xfc0, v14
	v_and_b32_e32 v15, 0xff0, v15
	v_cndmask_b32_e64 v8, v9, v8, s[0:1]
	v_lshl_add_u32 v10, v10, 2, s3
	v_lshl_add_u32 v11, v11, 2, s3
	v_lshl_add_u32 v12, v12, 2, s3
	v_lshl_add_u32 v13, v13, 2, s3
	v_lshl_add_u32 v14, v14, 2, s3
	v_lshl_add_u32 v15, v15, 2, s3
	v_and_b32_e32 v16, 0xfe0, v16
	v_and_b32_e32 v8, 0xff0, v8
	v_lshl_add_u32 v16, v16, 2, s3
	v_lshl_add_u32 v17, v8, 2, s3
	ds_read_b32 v8, v10
	ds_read_b32 v9, v11
	ds_read_b32 v10, v12
	ds_read_b32 v11, v13
	ds_read_b32 v12, v14
	ds_read_b32 v13, v15
	ds_read_b32 v14, v16
	ds_read_b32 v15, v17
	v_lshl_add_u64 v[6:7], v[58:59], 0, v[6:7]
	global_store_dwordx4 v[6:7], v[2:5], off
	s_waitcnt lgkmcnt(2)
	v_pk_mul_f32 v[6:7], v[12:13], 4.0 op_sel_hi:[1,0]
	v_pk_mul_f32 v[2:3], v[8:9], 4.0 op_sel_hi:[1,0]
	v_pk_mul_f32 v[4:5], v[10:11], 4.0 op_sel_hi:[1,0]
	s_waitcnt lgkmcnt(0)
	v_pk_mul_f32 v[8:9], v[14:15], 4.0 op_sel_hi:[1,0]
	v_cvt_pk_bf16_f32 v2, v2, v3
	v_cvt_pk_bf16_f32 v3, v4, v5
	v_cvt_pk_bf16_f32 v4, v6, v7
	v_lshlrev_b64 v[6:7], 10, v[56:57]
	v_or_b32_e32 v56, s6, v88
	v_cvt_pk_bf16_f32 v5, v8, v9
	v_lshlrev_b32_e32 v8, 4, v56
	v_mul_lo_u32 v9, v8, v54
	v_add_u32_e32 v10, 0xc00, v9
	v_cndmask_b32_e64 v10, v10, v9, s[0:1]
	v_add_u32_e32 v9, v9, v8
	v_add_u32_e32 v11, 0xc00, v9
	v_cndmask_b32_e64 v11, v11, v9, s[0:1]
	v_add_u32_e32 v9, v9, v8
	v_add_u32_e32 v12, 0xc00, v9
	v_cndmask_b32_e64 v12, v12, v9, s[0:1]
	v_add_u32_e32 v9, v9, v8
	v_add_u32_e32 v13, 0xc00, v9
	v_cndmask_b32_e64 v13, v13, v9, s[0:1]
	v_add_u32_e32 v9, v9, v8
	v_add_u32_e32 v14, 0xc00, v9
	v_cndmask_b32_e64 v14, v14, v9, s[0:1]
	v_add_u32_e32 v9, v9, v8
	v_add_u32_e32 v15, 0xc00, v9
	v_cndmask_b32_e64 v15, v15, v9, s[0:1]
	v_add_u32_e32 v9, v9, v8
	v_add_u32_e32 v16, 0xc00, v9
	v_add_u32_e32 v8, v9, v8
	v_cndmask_b32_e64 v16, v16, v9, s[0:1]
	v_add_u32_e32 v9, 0xc00, v8
	v_and_b32_e32 v10, 0xf80, v10
	v_and_b32_e32 v11, 0xff0, v11
	v_and_b32_e32 v12, 0xfe0, v12
	v_and_b32_e32 v13, 0xff0, v13
	v_and_b32_e32 v14, 0xfc0, v14
	v_and_b32_e32 v15, 0xff0, v15
	v_cndmask_b32_e64 v8, v9, v8, s[0:1]
	v_lshl_add_u32 v10, v10, 2, s3
	v_lshl_add_u32 v11, v11, 2, s3
	v_lshl_add_u32 v12, v12, 2, s3
	v_lshl_add_u32 v13, v13, 2, s3
	v_lshl_add_u32 v14, v14, 2, s3
	v_lshl_add_u32 v15, v15, 2, s3
	v_and_b32_e32 v16, 0xfe0, v16
	v_and_b32_e32 v8, 0xff0, v8
	v_lshl_add_u32 v16, v16, 2, s3
	v_lshl_add_u32 v17, v8, 2, s3
	ds_read_b32 v8, v10
	ds_read_b32 v9, v11
	ds_read_b32 v10, v12
	ds_read_b32 v11, v13
	ds_read_b32 v12, v14
	ds_read_b32 v13, v15
	ds_read_b32 v14, v16
	ds_read_b32 v15, v17
	v_lshl_add_u64 v[6:7], v[58:59], 0, v[6:7]
	global_store_dwordx4 v[6:7], v[2:5], off
	s_waitcnt lgkmcnt(2)
	v_pk_mul_f32 v[6:7], v[12:13], 4.0 op_sel_hi:[1,0]
	v_pk_mul_f32 v[2:3], v[8:9], 4.0 op_sel_hi:[1,0]
	v_pk_mul_f32 v[4:5], v[10:11], 4.0 op_sel_hi:[1,0]
	s_waitcnt lgkmcnt(0)
	v_pk_mul_f32 v[8:9], v[14:15], 4.0 op_sel_hi:[1,0]
	v_cvt_pk_bf16_f32 v2, v2, v3
	v_cvt_pk_bf16_f32 v3, v4, v5
	v_cvt_pk_bf16_f32 v4, v6, v7
	v_lshlrev_b64 v[6:7], 10, v[56:57]
	v_add_u32_e32 v56, s6, v89
	v_cvt_pk_bf16_f32 v5, v8, v9
	v_lshlrev_b32_e32 v8, 4, v56
	v_mul_lo_u32 v9, v8, v54
	v_add_u32_e32 v10, 0xc00, v9
	v_cndmask_b32_e64 v10, v10, v9, s[0:1]
	v_add_u32_e32 v9, v9, v8
	v_add_u32_e32 v11, 0xc00, v9
	v_cndmask_b32_e64 v11, v11, v9, s[0:1]
	v_add_u32_e32 v9, v9, v8
	v_add_u32_e32 v12, 0xc00, v9
	v_cndmask_b32_e64 v12, v12, v9, s[0:1]
	v_add_u32_e32 v9, v9, v8
	v_add_u32_e32 v13, 0xc00, v9
	v_cndmask_b32_e64 v13, v13, v9, s[0:1]
	v_add_u32_e32 v9, v9, v8
	v_add_u32_e32 v14, 0xc00, v9
	v_cndmask_b32_e64 v14, v14, v9, s[0:1]
	v_add_u32_e32 v9, v9, v8
	v_add_u32_e32 v15, 0xc00, v9
	v_cndmask_b32_e64 v15, v15, v9, s[0:1]
	v_add_u32_e32 v9, v9, v8
	v_add_u32_e32 v16, 0xc00, v9
	v_add_u32_e32 v8, v9, v8
	v_cndmask_b32_e64 v16, v16, v9, s[0:1]
	v_add_u32_e32 v9, 0xc00, v8
	v_and_b32_e32 v10, 0xf80, v10
	v_and_b32_e32 v11, 0xff0, v11
	v_and_b32_e32 v12, 0xfe0, v12
	v_and_b32_e32 v13, 0xff0, v13
	v_and_b32_e32 v14, 0xfc0, v14
	v_and_b32_e32 v15, 0xff0, v15
	v_cndmask_b32_e64 v8, v9, v8, s[0:1]
	v_lshl_add_u32 v10, v10, 2, s3
	v_lshl_add_u32 v11, v11, 2, s3
	v_lshl_add_u32 v12, v12, 2, s3
	v_lshl_add_u32 v13, v13, 2, s3
	v_lshl_add_u32 v14, v14, 2, s3
	v_lshl_add_u32 v15, v15, 2, s3
	v_and_b32_e32 v16, 0xfe0, v16
	v_and_b32_e32 v8, 0xff0, v8
	v_lshl_add_u32 v16, v16, 2, s3
	v_lshl_add_u32 v17, v8, 2, s3
	ds_read_b32 v8, v10
	ds_read_b32 v9, v11
	ds_read_b32 v10, v12
	ds_read_b32 v11, v13
	ds_read_b32 v12, v14
	ds_read_b32 v13, v15
	ds_read_b32 v14, v16
	ds_read_b32 v15, v17
	v_lshl_add_u64 v[6:7], v[58:59], 0, v[6:7]
	global_store_dwordx4 v[6:7], v[2:5], off
	s_waitcnt lgkmcnt(2)
	v_pk_mul_f32 v[6:7], v[12:13], 4.0 op_sel_hi:[1,0]
	s_mov_b64 s[6:7], 0
	v_pk_mul_f32 v[2:3], v[8:9], 4.0 op_sel_hi:[1,0]
	v_pk_mul_f32 v[4:5], v[10:11], 4.0 op_sel_hi:[1,0]
	s_waitcnt lgkmcnt(0)
	v_pk_mul_f32 v[8:9], v[14:15], 4.0 op_sel_hi:[1,0]
	v_cvt_pk_bf16_f32 v2, v2, v3
	v_cvt_pk_bf16_f32 v3, v4, v5
	v_cvt_pk_bf16_f32 v4, v6, v7
	v_lshlrev_b64 v[6:7], 10, v[56:57]
	v_cvt_pk_bf16_f32 v5, v8, v9
	v_lshl_add_u64 v[6:7], v[58:59], 0, v[6:7]
	global_store_dwordx4 v[6:7], v[2:5], off

.LBB0_81:
	s_barrier
	s_and_saveexec_b64 s[6:7], s[4:5]
	s_cbranch_execz .LBB0_25
	s_mov_b64 s[80:81], exec
	v_mbcnt_lo_u32_b32 v2, s80, 0
	v_mbcnt_hi_u32_b32 v2, s81, v2
	v_cmp_eq_u32_e32 vcc, 0, v2
	s_and_saveexec_b64 s[78:79], vcc
	s_cbranch_execz .LBB0_24
	s_waitcnt vmcnt(0)
	v_mov_b32_e32 v3, v120
	s_branch .LBB0_24

.LBB0_159:
	s_or_b64 exec, exec, s[6:7]
	s_movk_i32 s0, 0x1600
	v_cmp_gt_i32_e32 vcc, s0, v130
	s_and_saveexec_b64 s[30:31], vcc
	s_cbranch_execz .LBB0_168
	v_and_b32_e32 v1, 63, v1
	v_mov_b32_e32 v133, 0
	v_lshlrev_b32_e32 v132, 5, v1
	v_lshl_add_u64 v[106:107], s[56:57], 0, v[132:133]
	v_add_co_u32_e32 v20, vcc, 0x286d000, v106
	s_mov_b64 s[0:1], 0x286d000
	s_nop 0
	v_addc_co_u32_e32 v21, vcc, 0, v107, vcc
	v_add_co_u32_e32 v36, vcc, 0x2867000, v106
	v_lshl_add_u64 v[18:19], v[106:107], 0, s[0:1]
	s_nop 0
	v_addc_co_u32_e32 v37, vcc, 0, v107, vcc
	v_add_co_u32_e32 v52, vcc, 0x2861000, v106
	s_mov_b64 s[0:1], 0x2867000
	s_nop 0
	v_addc_co_u32_e32 v53, vcc, 0, v107, vcc
	v_add_co_u32_e32 v68, vcc, 0x285b000, v106
	v_lshl_add_u64 v[34:35], v[106:107], 0, s[0:1]
	s_nop 0
	v_addc_co_u32_e32 v69, vcc, 0, v107, vcc
	v_add_co_u32_e32 v84, vcc, 0x2855000, v106
	s_mov_b64 s[0:1], 0x2861000
	s_nop 0
	v_addc_co_u32_e32 v85, vcc, 0, v107, vcc
	v_lshl_add_u64 v[50:51], v[106:107], 0, s[0:1]
	s_mov_b64 s[0:1], 0x285b000
	v_add_co_u32_e32 v100, vcc, 0x284f000, v106
	v_lshl_add_u64 v[66:67], v[106:107], 0, s[0:1]
	s_mov_b64 s[0:1], 0x2855000
	v_addc_co_u32_e32 v101, vcc, 0, v107, vcc
	v_lshl_add_u64 v[82:83], v[106:107], 0, s[0:1]
	s_mov_b64 s[0:1], 0x284f000
	v_add_co_u32_e32 v108, vcc, 0x2849000, v106
	v_lshl_add_u64 v[98:99], v[106:107], 0, s[0:1]
	s_mov_b64 s[0:1], 0x2849000
	v_addc_co_u32_e32 v109, vcc, 0, v107, vcc
	v_lshl_add_u64 v[118:119], v[106:107], 0, s[0:1]
	s_mov_b64 s[0:1], 0x2843000
	v_add_co_u32_e32 v120, vcc, 0x2843000, v106
	v_lshl_add_u64 v[126:127], v[106:107], 0, s[0:1]
	s_nop 0
	v_addc_co_u32_e32 v121, vcc, 0, v107, vcc
	global_load_dwordx4 v[2:5], v[18:19], off offset:2064
	global_load_dwordx4 v[6:9], v[20:21], off
	global_load_dwordx4 v[10:13], v[18:19], off offset:2048
	global_load_dwordx4 v[14:17], v[18:19], off offset:16
	s_nop 0
	global_load_dwordx4 v[18:21], v[34:35], off offset:2064
	global_load_dwordx4 v[22:25], v[36:37], off
	global_load_dwordx4 v[26:29], v[34:35], off offset:2048
	global_load_dwordx4 v[30:33], v[34:35], off offset:16
	s_nop 0
	global_load_dwordx4 v[34:37], v[50:51], off offset:2064
	global_load_dwordx4 v[38:41], v[52:53], off
	global_load_dwordx4 v[42:45], v[50:51], off offset:2048
	global_load_dwordx4 v[46:49], v[50:51], off offset:16
	s_nop 0
	global_load_dwordx4 v[50:53], v[66:67], off offset:2064
	global_load_dwordx4 v[54:57], v[68:69], off
	global_load_dwordx4 v[58:61], v[66:67], off offset:2048
	global_load_dwordx4 v[62:65], v[66:67], off offset:16
	s_nop 0
	global_load_dwordx4 v[66:69], v[82:83], off offset:2064
	global_load_dwordx4 v[70:73], v[84:85], off
	global_load_dwordx4 v[74:77], v[82:83], off offset:2048
	global_load_dwordx4 v[78:81], v[82:83], off offset:16
	s_nop 0
	global_load_dwordx4 v[82:85], v[98:99], off offset:2064
	global_load_dwordx4 v[86:89], v[100:101], off
	global_load_dwordx4 v[90:93], v[98:99], off offset:2048
	global_load_dwordx4 v[94:97], v[98:99], off offset:16
	s_nop 0
	global_load_dwordx4 v[98:101], v[118:119], off offset:2064
	global_load_dwordx4 v[102:105], v[108:109], off
	s_nop 0
	global_load_dwordx4 v[106:109], v[118:119], off offset:2048
	global_load_dwordx4 v[110:113], v[118:119], off offset:16
	global_load_dwordx4 v[114:117], v[120:121], off
	s_nop 0
	global_load_dwordx4 v[118:121], v[126:127], off offset:2064
	global_load_dwordx4 v[122:125], v[126:127], off offset:2048
	s_nop 0
	global_load_dwordx4 v[126:129], v[126:127], off offset:16
	v_mbcnt_lo_u32_b32 v131, -1, 0
	v_mbcnt_hi_u32_b32 v131, -1, v131
	v_and_b32_e32 v134, 64, v131
	v_xor_b32_e32 v132, 1, v131
	v_add_u32_e32 v134, 64, v134
	v_cmp_lt_i32_e32 vcc, v132, v134
	s_mov_b64 s[44:45], 0x1eeb4000
	s_ashr_i32 s29, s28, 31
	v_cndmask_b32_e32 v137, v131, v132, vcc
	v_xor_b32_e32 v132, 2, v131
	v_cmp_lt_i32_e32 vcc, v132, v134
	s_mov_b64 s[46:47], 0x700000
	v_lshlrev_b32_e32 v136, 3, v1
	v_cndmask_b32_e32 v138, v131, v132, vcc
	v_xor_b32_e32 v132, 4, v131
	v_cmp_lt_i32_e32 vcc, v132, v134
	v_cmp_gt_u32_e64 s[0:1], 8, v1
	v_cmp_eq_u32_e64 s[4:5], 1, v1
	v_cndmask_b32_e32 v139, v131, v132, vcc
	v_xor_b32_e32 v132, 8, v131
	v_cmp_lt_i32_e32 vcc, v132, v134
	v_cmp_eq_u32_e64 s[6:7], 2, v1
	v_cmp_eq_u32_e64 s[8:9], 3, v1
	v_cndmask_b32_e32 v140, v131, v132, vcc
	v_xor_b32_e32 v132, 16, v131
	v_cmp_lt_i32_e32 vcc, v132, v134
	v_cmp_eq_u32_e64 s[10:11], 4, v1
	v_cmp_eq_u32_e64 s[12:13], 5, v1
	v_cndmask_b32_e32 v141, v131, v132, vcc
	v_xor_b32_e32 v132, 32, v131
	v_cmp_lt_i32_e32 vcc, v132, v134
	v_cmp_eq_u32_e64 s[14:15], 6, v1
	v_cmp_eq_u32_e64 s[16:17], 7, v1
	v_cndmask_b32_e32 v145, v131, v132, vcc
	v_ashrrev_i32_e32 v131, 31, v130
	v_mul_u32_u24_e32 v132, 0x5800, v1
	v_lshlrev_b64 v[134:135], 11, v[130:131]
	v_lshl_or_b32 v134, v1, 4, v134
	v_lshl_add_u64 v[132:133], v[130:131], 2, v[132:133]
	v_lshl_add_u64 v[132:133], s[56:57], 0, v[132:133]
	v_lshl_add_u64 v[134:135], s[56:57], 0, v[134:135]
	v_lshlrev_b32_e32 v1, 2, v137
	v_lshlrev_b32_e32 v137, 2, v138
	v_lshlrev_b32_e32 v142, 2, v139
	v_lshlrev_b32_e32 v143, 2, v140
	v_lshlrev_b32_e32 v144, 2, v141
	v_lshlrev_b32_e32 v145, 2, v145
	s_lshl_b64 s[38:39], s[28:29], 2
	s_lshl_b64 s[40:41], s[28:29], 11
	s_mov_b64 s[42:43], 0
	s_movk_i32 s3, 0x15ff
	v_mov_b32_e32 v131, v130
	v_lshl_add_u64 v[138:139], v[132:133], 0, s[44:45]
	v_lshl_add_u64 v[140:141], v[134:135], 0, s[46:47]
	global_load_dwordx4 v[188:191], v[140:141], off
	global_load_dwordx4 v[192:195], v[140:141], off offset:1024
	s_waitcnt vmcnt(0)
	s_branch .LBB0_162

.LBB0_162:
	s_waitcnt lgkmcnt(0)
	v_mov_b32_e32 v146, v188
	v_mov_b32_e32 v147, v189
	v_mov_b32_e32 v148, v190
	v_mov_b32_e32 v149, v191
	v_mov_b32_e32 v150, v192
	v_mov_b32_e32 v151, v193
	v_mov_b32_e32 v152, v194
	v_mov_b32_e32 v153, v195
	v_lshl_add_u64 v[196:197], v[140:141], 0, s[40:41]
	global_load_dwordx4 v[188:191], v[196:197], off
	global_load_dwordx4 v[192:195], v[196:197], off offset:1024
	v_and_b32_e32 v157, 0xffff0000, v146
	v_and_b32_e32 v159, 0xffff0000, v150
	s_waitcnt lgkmcnt(0)
	v_and_b32_e32 v161, 0xffff0000, v147
	v_and_b32_e32 v163, 0xffff0000, v151
	v_and_b32_e32 v165, 0xffff0000, v148
	v_and_b32_e32 v169, 0xffff0000, v149
	v_lshlrev_b32_e32 v156, 16, v146
	v_lshlrev_b32_e32 v158, 16, v150
	v_lshlrev_b32_e32 v160, 16, v147
	v_lshlrev_b32_e32 v162, 16, v151
	v_lshlrev_b32_e32 v164, 16, v148
	v_lshlrev_b32_e32 v168, 16, v149
	v_mul_f32_e32 v146, v115, v157
	v_mul_f32_e32 v147, v117, v161
	v_mul_f32_e32 v148, v127, v165
	v_mul_f32_e32 v149, v129, v169
	v_mul_f32_e32 v150, v123, v159
	v_mul_f32_e32 v151, v125, v163
	v_mul_f32_e32 v154, v103, v157
	v_mul_f32_e32 v155, v105, v161
	v_mul_f32_e32 v172, v111, v165
	v_mul_f32_e32 v173, v113, v169
	v_fmac_f32_e32 v146, v114, v156
	v_fmac_f32_e32 v147, v116, v160
	v_fmac_f32_e32 v148, v126, v164
	v_fmac_f32_e32 v149, v128, v168
	v_fmac_f32_e32 v150, v122, v158
	v_fmac_f32_e32 v151, v124, v162
	v_fmac_f32_e32 v154, v102, v156
	v_fmac_f32_e32 v155, v104, v160
	v_and_b32_e32 v167, 0xffff0000, v152
	v_and_b32_e32 v171, 0xffff0000, v153
	v_mul_f32_e32 v178, v87, v157
	v_mul_f32_e32 v179, v89, v161
	v_fmac_f32_e32 v172, v110, v164
	v_fmac_f32_e32 v173, v112, v168
	v_add_f32_e32 v146, v146, v147
	v_add_f32_e32 v147, v148, v149
	v_add_f32_e32 v148, v150, v151
	v_add_f32_e32 v150, v154, v155
	v_lshlrev_b32_e32 v166, 16, v152
	v_lshlrev_b32_e32 v170, 16, v153
	v_mul_f32_e32 v152, v119, v167
	v_mul_f32_e32 v153, v121, v171
	v_mul_f32_e32 v174, v107, v159
	v_mul_f32_e32 v175, v109, v163
	v_mul_f32_e32 v180, v95, v165
	v_mul_f32_e32 v181, v97, v169
	v_fmac_f32_e32 v178, v86, v156
	v_fmac_f32_e32 v179, v88, v160
	v_add_f32_e32 v151, v172, v173
	v_add_f32_e32 v146, 0, v146
	v_add_f32_e32 v150, 0, v150
	v_mul_f32_e32 v176, v99, v167
	v_mul_f32_e32 v177, v101, v171
	v_mul_f32_e32 v182, v91, v159
	v_mul_f32_e32 v183, v93, v163
	v_fmac_f32_e32 v152, v118, v166
	v_fmac_f32_e32 v153, v120, v170
	v_fmac_f32_e32 v174, v106, v158
	v_fmac_f32_e32 v175, v108, v162
	v_fmac_f32_e32 v180, v94, v164
	v_fmac_f32_e32 v181, v96, v168
	v_add_f32_e32 v146, v147, v146
	v_add_f32_e32 v147, v151, v150
	v_add_f32_e32 v150, v178, v179
	v_mul_f32_e32 v184, v83, v167
	v_mul_f32_e32 v185, v85, v171
	v_fmac_f32_e32 v176, v98, v166
	v_fmac_f32_e32 v177, v100, v170
	v_fmac_f32_e32 v182, v90, v158
	v_fmac_f32_e32 v183, v92, v162
	v_add_f32_e32 v149, v152, v153
	v_add_f32_e32 v152, v174, v175
	v_add_f32_e32 v151, v180, v181
	v_add_f32_e32 v150, 0, v150
	v_add_f32_e32 v153, v176, v177
	v_add_f32_e32 v147, v152, v147
	v_fmac_f32_e32 v184, v82, v166
	v_fmac_f32_e32 v185, v84, v170
	v_add_f32_e32 v152, v182, v183
	v_add_f32_e32 v150, v151, v150
	v_mul_f32_e32 v186, v71, v157
	v_mul_f32_e32 v187, v73, v161
	v_add_f32_e32 v147, v153, v147
	v_add_f32_e32 v153, v184, v185
	v_add_f32_e32 v150, v152, v150
	v_fmac_f32_e32 v186, v70, v156
	v_fmac_f32_e32 v187, v72, v160
	v_add_f32_e32 v150, v153, v150
	v_mul_f32_e32 v152, v79, v165
	v_mul_f32_e32 v153, v81, v169
	v_add_f32_e32 v154, v186, v187
	v_fmac_f32_e32 v152, v78, v164
	v_fmac_f32_e32 v153, v80, v168
	v_add_f32_e32 v154, 0, v154
	v_add_f32_e32 v152, v152, v153
	v_add_f32_e32 v152, v152, v154
	v_mul_f32_e32 v153, v75, v159
	v_mul_f32_e32 v154, v77, v163
	v_fmac_f32_e32 v153, v74, v158
	v_fmac_f32_e32 v154, v76, v162
	v_add_f32_e32 v153, v153, v154
	v_add_f32_e32 v152, v153, v152
	v_mul_f32_e32 v153, v67, v167
	v_mul_f32_e32 v154, v69, v171
	v_fmac_f32_e32 v153, v66, v166
	v_fmac_f32_e32 v154, v68, v170
	v_add_f32_e32 v153, v153, v154
	v_mul_f32_e32 v154, v55, v157
	v_mul_f32_e32 v155, v57, v161
	v_fmac_f32_e32 v154, v54, v156
	v_fmac_f32_e32 v155, v56, v160
	v_add_f32_e32 v154, v154, v155
	v_mul_f32_e32 v155, v63, v165
	v_mul_f32_e32 v172, v65, v169
	v_fmac_f32_e32 v155, v62, v164
	v_fmac_f32_e32 v172, v64, v168
	v_add_f32_e32 v154, 0, v154
	v_add_f32_e32 v155, v155, v172
	v_add_f32_e32 v154, v155, v154
	v_mul_f32_e32 v155, v59, v159
	v_mul_f32_e32 v172, v61, v163
	v_fmac_f32_e32 v155, v58, v158
	v_fmac_f32_e32 v172, v60, v162
	v_add_f32_e32 v155, v155, v172
	v_add_f32_e32 v154, v155, v154
	v_mul_f32_e32 v155, v51, v167
	v_mul_f32_e32 v172, v53, v171
	v_fmac_f32_e32 v155, v50, v166
	v_fmac_f32_e32 v172, v52, v170
	v_add_f32_e32 v155, v155, v172
	v_mul_f32_e32 v172, v39, v157
	v_mul_f32_e32 v173, v41, v161
	v_fmac_f32_e32 v172, v38, v156
	v_fmac_f32_e32 v173, v40, v160
	v_add_f32_e32 v172, v172, v173
	v_mul_f32_e32 v173, v47, v165
	v_mul_f32_e32 v174, v49, v169
	v_fmac_f32_e32 v173, v46, v164
	v_fmac_f32_e32 v174, v48, v168
	v_add_f32_e32 v172, 0, v172
	v_add_f32_e32 v173, v173, v174
	v_add_f32_e32 v172, v173, v172
	v_mul_f32_e32 v173, v43, v159
	v_mul_f32_e32 v174, v45, v163
	v_fmac_f32_e32 v173, v42, v158
	v_fmac_f32_e32 v174, v44, v162
	v_add_f32_e32 v173, v173, v174
	v_add_f32_e32 v172, v173, v172
	v_mul_f32_e32 v173, v35, v167
	v_mul_f32_e32 v174, v37, v171
	v_fmac_f32_e32 v173, v34, v166
	v_fmac_f32_e32 v174, v36, v170
	v_add_f32_e32 v173, v173, v174
	v_mul_f32_e32 v174, v23, v157
	v_mul_f32_e32 v157, v7, v157
	v_fmac_f32_e32 v174, v22, v156
	v_mul_f32_e32 v175, v25, v161
	v_fmac_f32_e32 v157, v6, v156
	v_mul_f32_e32 v156, v9, v161
	v_fmac_f32_e32 v175, v24, v160
	v_fmac_f32_e32 v156, v8, v160
	v_add_f32_e32 v174, v174, v175
	v_mul_f32_e32 v175, v31, v165
	v_mul_f32_e32 v176, v33, v169
	v_add_f32_e32 v156, v157, v156
	v_mul_f32_e32 v157, v15, v165
	v_mul_f32_e32 v160, v17, v169
	v_fmac_f32_e32 v175, v30, v164
	v_fmac_f32_e32 v176, v32, v168
	v_fmac_f32_e32 v157, v14, v164
	v_fmac_f32_e32 v160, v16, v168
	v_add_f32_e32 v174, 0, v174
	v_add_f32_e32 v175, v175, v176
	v_add_f32_e32 v156, 0, v156
	v_add_f32_e32 v157, v157, v160
	v_add_f32_e32 v174, v175, v174
	v_mul_f32_e32 v175, v27, v159
	v_add_f32_e32 v156, v157, v156
	v_mul_f32_e32 v157, v11, v159
	v_fmac_f32_e32 v175, v26, v158
	v_mul_f32_e32 v176, v29, v163
	v_fmac_f32_e32 v157, v10, v158
	v_mul_f32_e32 v158, v13, v163
	v_fmac_f32_e32 v176, v28, v162
	v_fmac_f32_e32 v158, v12, v162
	v_add_f32_e32 v175, v175, v176
	v_add_f32_e32 v157, v157, v158
	v_add_f32_e32 v174, v175, v174
	v_mul_f32_e32 v175, v19, v167
	v_mul_f32_e32 v176, v21, v171
	v_add_f32_e32 v156, v157, v156
	v_mul_f32_e32 v157, v3, v167
	v_mul_f32_e32 v158, v5, v171
	v_fmac_f32_e32 v175, v18, v166
	v_fmac_f32_e32 v176, v20, v170
	v_fmac_f32_e32 v157, v2, v166
	v_fmac_f32_e32 v158, v4, v170
	v_add_f32_e32 v146, v148, v146
	v_add_f32_e32 v175, v175, v176
	v_add_f32_e32 v157, v157, v158
	v_add_f32_e32 v146, v149, v146
	v_add_f32_e32 v152, v153, v152
	v_add_f32_e32 v154, v155, v154
	v_add_f32_e32 v172, v173, v172
	v_add_f32_e32 v174, v175, v174
	v_add_f32_e32 v156, v157, v156
	ds_bpermute_b32 v148, v1, v146
	ds_bpermute_b32 v149, v1, v147
	ds_bpermute_b32 v151, v1, v150
	ds_bpermute_b32 v153, v1, v152
	ds_bpermute_b32 v155, v1, v154
	ds_bpermute_b32 v173, v1, v172
	ds_bpermute_b32 v175, v1, v174
	ds_bpermute_b32 v157, v1, v156
	s_waitcnt lgkmcnt(7)
	v_add_f32_e32 v146, v146, v148
	s_waitcnt lgkmcnt(6)
	v_add_f32_e32 v147, v147, v149
	s_waitcnt lgkmcnt(5)
	v_add_f32_e32 v150, v150, v151
	s_waitcnt lgkmcnt(4)
	v_add_f32_e32 v152, v152, v153
	s_waitcnt lgkmcnt(3)
	v_add_f32_e32 v154, v154, v155
	s_waitcnt lgkmcnt(2)
	v_add_f32_e32 v158, v172, v173
	s_waitcnt lgkmcnt(1)
	v_add_f32_e32 v160, v174, v175
	s_waitcnt lgkmcnt(0)
	v_add_f32_e32 v156, v156, v157
	ds_bpermute_b32 v148, v137, v146
	ds_bpermute_b32 v149, v137, v147
	ds_bpermute_b32 v151, v137, v150
	ds_bpermute_b32 v153, v137, v152
	ds_bpermute_b32 v155, v137, v154
	ds_bpermute_b32 v159, v137, v158
	ds_bpermute_b32 v161, v137, v160
	ds_bpermute_b32 v157, v137, v156
	s_waitcnt lgkmcnt(7)
	v_add_f32_e32 v146, v146, v148
	s_waitcnt lgkmcnt(6)
	v_add_f32_e32 v147, v147, v149
	s_waitcnt lgkmcnt(5)
	v_add_f32_e32 v150, v150, v151
	s_waitcnt lgkmcnt(4)
	v_add_f32_e32 v152, v152, v153
	s_waitcnt lgkmcnt(3)
	v_add_f32_e32 v154, v154, v155
	s_waitcnt lgkmcnt(2)
	v_add_f32_e32 v158, v158, v159
	s_waitcnt lgkmcnt(1)
	v_add_f32_e32 v160, v160, v161
	s_waitcnt lgkmcnt(0)
	v_add_f32_e32 v156, v156, v157
	ds_bpermute_b32 v148, v142, v146
	ds_bpermute_b32 v149, v142, v147
	ds_bpermute_b32 v151, v142, v150
	ds_bpermute_b32 v153, v142, v152
	ds_bpermute_b32 v155, v142, v154
	ds_bpermute_b32 v159, v142, v158
	ds_bpermute_b32 v161, v142, v160
	ds_bpermute_b32 v157, v142, v156
	s_waitcnt lgkmcnt(7)
	v_add_f32_e32 v146, v146, v148
	s_waitcnt lgkmcnt(6)
	v_add_f32_e32 v147, v147, v149
	s_waitcnt lgkmcnt(5)
	v_add_f32_e32 v150, v150, v151
	s_waitcnt lgkmcnt(4)
	v_add_f32_e32 v152, v152, v153
	s_waitcnt lgkmcnt(3)
	v_add_f32_e32 v154, v154, v155
	s_waitcnt lgkmcnt(2)
	v_add_f32_e32 v158, v158, v159
	s_waitcnt lgkmcnt(1)
	v_add_f32_e32 v160, v160, v161
	s_waitcnt lgkmcnt(0)
	v_add_f32_e32 v156, v156, v157
	ds_bpermute_b32 v148, v143, v146
	ds_bpermute_b32 v149, v143, v147
	ds_bpermute_b32 v151, v143, v150
	ds_bpermute_b32 v153, v143, v152
	ds_bpermute_b32 v155, v143, v154
	ds_bpermute_b32 v159, v143, v158
	ds_bpermute_b32 v161, v143, v160
	ds_bpermute_b32 v157, v143, v156
	s_waitcnt lgkmcnt(7)
	v_add_f32_e32 v146, v146, v148
	s_waitcnt lgkmcnt(6)
	v_add_f32_e32 v147, v147, v149
	s_waitcnt lgkmcnt(5)
	v_add_f32_e32 v150, v150, v151
	s_waitcnt lgkmcnt(4)
	v_add_f32_e32 v152, v152, v153
	s_waitcnt lgkmcnt(3)
	v_add_f32_e32 v154, v154, v155
	s_waitcnt lgkmcnt(2)
	v_add_f32_e32 v158, v158, v159
	s_waitcnt lgkmcnt(1)
	v_add_f32_e32 v160, v160, v161
	s_waitcnt lgkmcnt(0)
	v_add_f32_e32 v162, v156, v157
	ds_bpermute_b32 v148, v144, v146
	ds_bpermute_b32 v149, v144, v147
	ds_bpermute_b32 v151, v144, v150
	ds_bpermute_b32 v153, v144, v152
	ds_bpermute_b32 v155, v144, v154
	ds_bpermute_b32 v159, v144, v158
	ds_bpermute_b32 v161, v144, v160
	ds_bpermute_b32 v163, v144, v162
	s_waitcnt lgkmcnt(7)
	v_add_f32_e32 v146, v146, v148
	s_waitcnt lgkmcnt(6)
	v_add_f32_e32 v148, v147, v149
	s_waitcnt lgkmcnt(5)
	v_add_f32_e32 v150, v150, v151
	s_waitcnt lgkmcnt(4)
	v_add_f32_e32 v152, v152, v153
	s_waitcnt lgkmcnt(3)
	v_add_f32_e32 v154, v154, v155
	s_waitcnt lgkmcnt(2)
	v_add_f32_e32 v156, v158, v159
	s_waitcnt lgkmcnt(1)
	v_add_f32_e32 v158, v160, v161
	s_waitcnt lgkmcnt(0)
	v_add_f32_e32 v160, v162, v163
	ds_bpermute_b32 v147, v145, v146
	ds_bpermute_b32 v149, v145, v148
	ds_bpermute_b32 v151, v145, v150
	ds_bpermute_b32 v153, v145, v152
	ds_bpermute_b32 v155, v145, v154
	ds_bpermute_b32 v157, v145, v156
	ds_bpermute_b32 v159, v145, v158
	ds_bpermute_b32 v161, v145, v160
	s_and_saveexec_b64 s[44:45], s[0:1]
	s_cbranch_execz .Lshw0_skip
	s_waitcnt lgkmcnt(6)
	v_add_f32_e32 v148, v148, v149
	v_add_f32_e32 v146, v146, v147
	s_waitcnt lgkmcnt(5)
	v_add_f32_e32 v150, v150, v151
	v_cndmask_b32_e64 v146, v146, v148, s[4:5]
	s_waitcnt lgkmcnt(4)
	v_add_f32_e32 v152, v152, v153
	v_cndmask_b32_e64 v146, v146, v150, s[6:7]
	s_waitcnt lgkmcnt(3)
	v_add_f32_e32 v154, v154, v155
	v_cndmask_b32_e64 v146, v146, v152, s[8:9]
	s_waitcnt lgkmcnt(2)
	v_add_f32_e32 v156, v156, v157
	v_cndmask_b32_e64 v146, v146, v154, s[10:11]
	s_waitcnt lgkmcnt(1)
	v_add_f32_e32 v158, v158, v159
	v_cndmask_b32_e64 v146, v146, v156, s[12:13]
	s_waitcnt lgkmcnt(0)
	v_add_f32_e32 v160, v160, v161
	v_cndmask_b32_e64 v146, v146, v158, s[14:15]
	v_cndmask_b32_e64 v146, v146, v160, s[16:17]
	global_store_dword v[138:139], v146, off
	s_waitcnt vmcnt(1)
	s_branch .LBB0_161
.Lshw0_skip:
	s_waitcnt vmcnt(0)
	s_branch .LBB0_161
.LBB0_164:
	s_or_b64 exec, exec, s[42:43]
	v_lshlrev_b32_e32 v2, 2, v136
	v_mov_b32_e32 v3, 0
	v_lshl_add_u64 v[114:115], s[56:57], 0, v[2:3]
	v_add_co_u32_e32 v6, vcc, 0x28a3000, v114
	s_mov_b64 s[42:43], 0x28a3000
	s_nop 0
	v_addc_co_u32_e32 v7, vcc, 0, v115, vcc
	v_add_co_u32_e32 v22, vcc, 0x289d000, v114
	v_lshl_add_u64 v[14:15], v[114:115], 0, s[42:43]
	s_nop 0
	v_addc_co_u32_e32 v23, vcc, 0, v115, vcc
	v_add_co_u32_e32 v38, vcc, 0x2897000, v114
	s_mov_b64 s[42:43], 0x289d000
	s_nop 0
	v_addc_co_u32_e32 v39, vcc, 0, v115, vcc
	v_add_co_u32_e32 v54, vcc, 0x2891000, v114
	v_lshl_add_u64 v[30:31], v[114:115], 0, s[42:43]
	s_nop 0
	v_addc_co_u32_e32 v55, vcc, 0, v115, vcc
	v_add_co_u32_e32 v70, vcc, 0x288b000, v114
	s_mov_b64 s[42:43], 0x2897000
	s_nop 0
	v_addc_co_u32_e32 v71, vcc, 0, v115, vcc
	v_lshl_add_u64 v[46:47], v[114:115], 0, s[42:43]
	s_mov_b64 s[42:43], 0x2891000
	v_add_co_u32_e32 v86, vcc, 0x2885000, v114
	v_lshl_add_u64 v[62:63], v[114:115], 0, s[42:43]
	s_mov_b64 s[42:43], 0x288b000
	v_addc_co_u32_e32 v87, vcc, 0, v115, vcc
	v_lshl_add_u64 v[78:79], v[114:115], 0, s[42:43]
	s_mov_b64 s[42:43], 0x2885000
	v_add_co_u32_e32 v102, vcc, 0x287f000, v114
	v_lshl_add_u64 v[94:95], v[114:115], 0, s[42:43]
	s_mov_b64 s[42:43], 0x287f000
	v_addc_co_u32_e32 v103, vcc, 0, v115, vcc
	v_lshl_add_u64 v[110:111], v[114:115], 0, s[42:43]
	s_mov_b64 s[42:43], 0x2879000
	v_add_co_u32_e32 v118, vcc, 0x2879000, v114
	v_lshl_add_u64 v[126:127], v[114:115], 0, s[42:43]
	s_nop 0
	v_addc_co_u32_e32 v119, vcc, 0, v115, vcc
	global_load_dwordx4 v[2:5], v[14:15], off offset:2064
	s_nop 0
	global_load_dwordx4 v[6:9], v[6:7], off
	s_nop 0
	global_load_dwordx4 v[10:13], v[14:15], off offset:2048
	s_nop 0
	global_load_dwordx4 v[14:17], v[14:15], off offset:16
	s_nop 0
	global_load_dwordx4 v[18:21], v[30:31], off offset:2064
	s_nop 0
	global_load_dwordx4 v[22:25], v[22:23], off
	s_nop 0
	global_load_dwordx4 v[26:29], v[30:31], off offset:2048
	s_nop 0
	global_load_dwordx4 v[30:33], v[30:31], off offset:16
	s_nop 0
	global_load_dwordx4 v[34:37], v[46:47], off offset:2064
	s_nop 0
	global_load_dwordx4 v[38:41], v[38:39], off
	s_nop 0
	global_load_dwordx4 v[42:45], v[46:47], off offset:2048
	s_nop 0
	global_load_dwordx4 v[46:49], v[46:47], off offset:16
	s_nop 0
	global_load_dwordx4 v[50:53], v[62:63], off offset:2064
	s_nop 0
	global_load_dwordx4 v[54:57], v[54:55], off
	s_nop 0
	global_load_dwordx4 v[58:61], v[62:63], off offset:2048
	s_nop 0
	global_load_dwordx4 v[62:65], v[62:63], off offset:16
	s_nop 0
	global_load_dwordx4 v[66:69], v[78:79], off offset:2064
	s_nop 0
	global_load_dwordx4 v[70:73], v[70:71], off
	s_nop 0
	global_load_dwordx4 v[74:77], v[78:79], off offset:2048
	s_nop 0
	global_load_dwordx4 v[78:81], v[78:79], off offset:16
	s_nop 0
	global_load_dwordx4 v[82:85], v[94:95], off offset:2064
	s_nop 0
	global_load_dwordx4 v[86:89], v[86:87], off
	s_nop 0
	global_load_dwordx4 v[90:93], v[94:95], off offset:2048
	s_nop 0
	global_load_dwordx4 v[94:97], v[94:95], off offset:16
	s_nop 0
	global_load_dwordx4 v[98:101], v[110:111], off offset:2064
	s_nop 0
	global_load_dwordx4 v[102:105], v[102:103], off
	s_nop 0
	global_load_dwordx4 v[106:109], v[110:111], off offset:2048
	s_nop 0
	global_load_dwordx4 v[110:113], v[110:111], off offset:16
	s_nop 0
	global_load_dwordx4 v[114:117], v[126:127], off offset:2064
	s_nop 0
	global_load_dwordx4 v[118:121], v[118:119], off
	s_nop 0
	global_load_dwordx4 v[122:125], v[126:127], off offset:2048
	s_nop 0
	global_load_dwordx4 v[126:129], v[126:127], off offset:16
	s_mov_b64 s[42:43], 0x1eee0000
	v_lshl_add_u64 v[132:133], v[132:133], 0, s[42:43]
	s_mov_b64 s[42:43], 0x1200000
	v_lshl_add_u64 v[134:135], v[134:135], 0, s[42:43]
	global_load_dwordx4 v[188:191], v[134:135], off
	global_load_dwordx4 v[192:195], v[134:135], off offset:1024
	s_waitcnt vmcnt(0)
	s_mov_b64 s[42:43], 0
	s_movk_i32 s3, 0x15ff
	s_branch .LBB0_166

.LBB0_166:
	s_waitcnt lgkmcnt(0)
	v_mov_b32_e32 v138, v188
	v_mov_b32_e32 v139, v189
	v_mov_b32_e32 v140, v190
	v_mov_b32_e32 v141, v191
	v_mov_b32_e32 v146, v192
	v_mov_b32_e32 v147, v193
	v_mov_b32_e32 v148, v194
	v_mov_b32_e32 v149, v195
	v_lshl_add_u64 v[196:197], v[134:135], 0, s[40:41]
	global_load_dwordx4 v[188:191], v[196:197], off
	global_load_dwordx4 v[192:195], v[196:197], off offset:1024
	v_and_b32_e32 v151, 0xffff0000, v138
	v_and_b32_e32 v153, 0xffff0000, v146
	s_waitcnt lgkmcnt(0)
	v_and_b32_e32 v155, 0xffff0000, v139
	s_waitcnt lgkmcnt(2)
	v_and_b32_e32 v157, 0xffff0000, v147
	s_waitcnt lgkmcnt(1)
	v_and_b32_e32 v159, 0xffff0000, v140
	v_and_b32_e32 v163, 0xffff0000, v141
	v_lshlrev_b32_e32 v150, 16, v138
	v_lshlrev_b32_e32 v152, 16, v146
	v_lshlrev_b32_e32 v154, 16, v139
	v_lshlrev_b32_e32 v156, 16, v147
	v_lshlrev_b32_e32 v158, 16, v140
	v_lshlrev_b32_e32 v160, 16, v148
	s_waitcnt lgkmcnt(0)
	v_and_b32_e32 v161, 0xffff0000, v148
	v_lshlrev_b32_e32 v162, 16, v141
	v_lshlrev_b32_e32 v164, 16, v149
	v_and_b32_e32 v165, 0xffff0000, v149
	v_mul_f32_e32 v131, v119, v151
	v_mul_f32_e32 v136, v121, v155
	v_mul_f32_e32 v138, v127, v159
	v_mul_f32_e32 v139, v129, v163
	v_mul_f32_e32 v140, v123, v153
	v_mul_f32_e32 v141, v125, v157
	v_mul_f32_e32 v148, v103, v151
	v_mul_f32_e32 v149, v105, v155
	v_mul_f32_e32 v166, v111, v159
	v_mul_f32_e32 v167, v113, v163
	v_fmac_f32_e32 v131, v118, v150
	v_fmac_f32_e32 v136, v120, v154
	v_fmac_f32_e32 v138, v126, v158
	v_fmac_f32_e32 v139, v128, v162
	v_fmac_f32_e32 v140, v122, v152
	v_fmac_f32_e32 v141, v124, v156
	v_fmac_f32_e32 v148, v102, v150
	v_fmac_f32_e32 v149, v104, v154
	v_mul_f32_e32 v146, v115, v161
	v_mul_f32_e32 v147, v117, v165
	v_mul_f32_e32 v168, v107, v153
	v_mul_f32_e32 v169, v109, v157
	v_fmac_f32_e32 v166, v110, v158
	v_fmac_f32_e32 v167, v112, v162
	v_add_f32_e32 v131, v131, v136
	v_add_f32_e32 v136, v138, v139
	v_add_f32_e32 v138, v140, v141
	v_add_f32_e32 v140, v148, v149
	v_mul_f32_e32 v170, v99, v161
	v_mul_f32_e32 v171, v101, v165
	v_fmac_f32_e32 v146, v114, v160
	v_fmac_f32_e32 v147, v116, v164
	v_fmac_f32_e32 v168, v106, v152
	v_fmac_f32_e32 v169, v108, v156
	v_add_f32_e32 v141, v166, v167
	v_add_f32_e32 v131, 0, v131
	v_add_f32_e32 v140, 0, v140
	v_fmac_f32_e32 v170, v98, v160
	v_fmac_f32_e32 v171, v100, v164
	v_add_f32_e32 v139, v146, v147
	v_add_f32_e32 v146, v168, v169
	v_add_f32_e32 v131, v136, v131
	v_add_f32_e32 v136, v141, v140
	v_add_f32_e32 v147, v170, v171
	v_add_f32_e32 v131, v138, v131
	v_add_f32_e32 v136, v146, v136
	v_add_f32_e32 v131, v139, v131
	v_add_f32_e32 v136, v147, v136
	ds_bpermute_b32 v138, v1, v131
	ds_bpermute_b32 v139, v1, v136
	v_mul_f32_e32 v172, v87, v151
	v_mul_f32_e32 v173, v89, v155
	v_mul_f32_e32 v174, v95, v159
	s_waitcnt lgkmcnt(1)
	v_add_f32_e32 v131, v131, v138
	s_waitcnt lgkmcnt(0)
	v_add_f32_e32 v136, v136, v139
	ds_bpermute_b32 v138, v137, v131
	ds_bpermute_b32 v139, v137, v136
	v_mul_f32_e32 v175, v97, v163
	v_fmac_f32_e32 v172, v86, v150
	v_fmac_f32_e32 v173, v88, v154
	s_waitcnt lgkmcnt(1)
	v_add_f32_e32 v131, v131, v138
	s_waitcnt lgkmcnt(0)
	v_add_f32_e32 v136, v136, v139
	ds_bpermute_b32 v138, v142, v131
	ds_bpermute_b32 v139, v142, v136
	v_mul_f32_e32 v176, v91, v153
	v_mul_f32_e32 v177, v93, v157
	v_fmac_f32_e32 v174, v94, v158
	s_waitcnt lgkmcnt(1)
	v_add_f32_e32 v131, v131, v138
	s_waitcnt lgkmcnt(0)
	v_add_f32_e32 v136, v136, v139
	ds_bpermute_b32 v138, v143, v131
	ds_bpermute_b32 v139, v143, v136
	v_fmac_f32_e32 v175, v96, v162
	v_add_f32_e32 v140, v172, v173
	v_mul_f32_e32 v178, v83, v161
	s_waitcnt lgkmcnt(1)
	v_add_f32_e32 v131, v131, v138
	s_waitcnt lgkmcnt(0)
	v_add_f32_e32 v136, v136, v139
	ds_bpermute_b32 v138, v144, v131
	ds_bpermute_b32 v139, v144, v136
	v_mul_f32_e32 v179, v85, v165
	v_fmac_f32_e32 v176, v90, v152
	v_fmac_f32_e32 v177, v92, v156
	v_add_f32_e32 v141, v174, v175
	v_add_f32_e32 v140, 0, v140
	v_mul_f32_e32 v180, v71, v151
	v_mul_f32_e32 v181, v73, v155
	v_fmac_f32_e32 v178, v82, v160
	v_fmac_f32_e32 v179, v84, v164
	v_add_f32_e32 v146, v176, v177
	v_add_f32_e32 v140, v141, v140
	v_mul_f32_e32 v182, v79, v159
	v_fmac_f32_e32 v180, v70, v150
	v_fmac_f32_e32 v181, v72, v154
	v_add_f32_e32 v147, v178, v179
	v_add_f32_e32 v140, v146, v140
	s_waitcnt lgkmcnt(1)
	v_add_f32_e32 v131, v131, v138
	s_waitcnt lgkmcnt(0)
	v_add_f32_e32 v138, v136, v139
	v_mul_f32_e32 v139, v81, v163
	v_add_f32_e32 v148, v180, v181
	v_add_f32_e32 v140, v147, v140
	v_fmac_f32_e32 v182, v78, v158
	v_fmac_f32_e32 v139, v80, v162
	v_mul_f32_e32 v146, v75, v153
	v_mul_f32_e32 v147, v77, v157
	v_add_f32_e32 v148, 0, v148
	v_add_f32_e32 v139, v182, v139
	v_fmac_f32_e32 v146, v74, v152
	v_fmac_f32_e32 v147, v76, v156
	v_add_f32_e32 v139, v139, v148
	v_add_f32_e32 v146, v146, v147
	v_add_f32_e32 v139, v146, v139
	v_mul_f32_e32 v146, v67, v161
	v_mul_f32_e32 v147, v69, v165
	v_fmac_f32_e32 v146, v66, v160
	v_fmac_f32_e32 v147, v68, v164
	v_add_f32_e32 v146, v146, v147
	v_mul_f32_e32 v147, v55, v151
	v_mul_f32_e32 v148, v57, v155
	v_fmac_f32_e32 v147, v54, v150
	v_fmac_f32_e32 v148, v56, v154
	v_add_f32_e32 v147, v147, v148
	v_mul_f32_e32 v148, v63, v159
	v_mul_f32_e32 v149, v65, v163
	v_fmac_f32_e32 v148, v62, v158
	v_fmac_f32_e32 v149, v64, v162
	v_add_f32_e32 v147, 0, v147
	v_add_f32_e32 v148, v148, v149
	v_add_f32_e32 v147, v148, v147
	v_mul_f32_e32 v148, v59, v153
	v_mul_f32_e32 v149, v61, v157
	v_fmac_f32_e32 v148, v58, v152
	v_fmac_f32_e32 v149, v60, v156
	v_add_f32_e32 v148, v148, v149
	v_add_f32_e32 v147, v148, v147
	v_mul_f32_e32 v148, v51, v161
	v_mul_f32_e32 v149, v53, v165
	v_fmac_f32_e32 v148, v50, v160
	v_fmac_f32_e32 v149, v52, v164
	v_add_f32_e32 v148, v148, v149
	v_add_f32_e32 v139, v146, v139
	v_add_f32_e32 v147, v148, v147
	ds_bpermute_b32 v146, v1, v139
	ds_bpermute_b32 v148, v1, v147
	v_mul_f32_e32 v166, v49, v163
	v_fmac_f32_e32 v166, v48, v162
	v_mul_f32_e32 v167, v33, v163
	s_waitcnt lgkmcnt(1)
	v_add_f32_e32 v139, v139, v146
	s_waitcnt lgkmcnt(0)
	v_add_f32_e32 v147, v147, v148
	ds_bpermute_b32 v146, v137, v139
	ds_bpermute_b32 v148, v137, v147
	v_fmac_f32_e32 v167, v32, v162
	ds_bpermute_b32 v141, v1, v140
	ds_bpermute_b32 v136, v145, v131
	s_waitcnt lgkmcnt(3)
	v_add_f32_e32 v139, v139, v146
	s_waitcnt lgkmcnt(2)
	v_add_f32_e32 v147, v147, v148
	ds_bpermute_b32 v146, v142, v139
	ds_bpermute_b32 v148, v142, v147
	s_waitcnt lgkmcnt(3)
	v_add_f32_e32 v140, v140, v141
	ds_bpermute_b32 v141, v137, v140
	s_waitcnt lgkmcnt(2)
	v_add_f32_e32 v139, v139, v146
	s_waitcnt lgkmcnt(1)
	v_add_f32_e32 v147, v147, v148
	ds_bpermute_b32 v146, v143, v139
	ds_bpermute_b32 v148, v143, v147
	s_waitcnt lgkmcnt(2)
	v_add_f32_e32 v140, v140, v141
	ds_bpermute_b32 v141, v142, v140
	s_waitcnt lgkmcnt(2)
	v_add_f32_e32 v146, v139, v146
	s_waitcnt lgkmcnt(1)
	v_add_f32_e32 v147, v147, v148
	ds_bpermute_b32 v149, v144, v146
	ds_bpermute_b32 v148, v144, v147
	s_waitcnt lgkmcnt(2)
	v_add_f32_e32 v140, v140, v141
	ds_bpermute_b32 v141, v143, v140
	ds_bpermute_b32 v139, v145, v138
	s_waitcnt lgkmcnt(3)
	v_add_f32_e32 v146, v146, v149
	s_waitcnt lgkmcnt(2)
	v_add_f32_e32 v147, v147, v148
	v_mul_f32_e32 v148, v39, v151
	v_mul_f32_e32 v149, v41, v155
	v_fmac_f32_e32 v148, v38, v150
	v_fmac_f32_e32 v149, v40, v154
	v_add_f32_e32 v148, v148, v149
	v_mul_f32_e32 v149, v47, v159
	v_fmac_f32_e32 v149, v46, v158
	v_add_f32_e32 v148, 0, v148
	v_add_f32_e32 v149, v149, v166
	v_add_f32_e32 v148, v149, v148
	v_mul_f32_e32 v149, v43, v153
	v_mul_f32_e32 v166, v45, v157
	v_fmac_f32_e32 v149, v42, v152
	v_fmac_f32_e32 v166, v44, v156
	v_add_f32_e32 v149, v149, v166
	v_add_f32_e32 v148, v149, v148
	v_mul_f32_e32 v149, v35, v161
	v_mul_f32_e32 v166, v37, v165
	v_fmac_f32_e32 v149, v34, v160
	v_fmac_f32_e32 v166, v36, v164
	v_add_f32_e32 v149, v149, v166
	v_add_f32_e32 v166, v149, v148
	v_mul_f32_e32 v148, v23, v151
	v_mul_f32_e32 v149, v25, v155
	v_fmac_f32_e32 v148, v22, v150
	v_fmac_f32_e32 v149, v24, v154
	v_add_f32_e32 v148, v148, v149
	v_mul_f32_e32 v149, v31, v159
	v_mul_f32_e32 v151, v7, v151
	v_mul_f32_e32 v155, v9, v155
	v_fmac_f32_e32 v149, v30, v158
	v_fmac_f32_e32 v151, v6, v150
	v_fmac_f32_e32 v155, v8, v154
	v_add_f32_e32 v148, 0, v148
	v_add_f32_e32 v149, v149, v167
	v_add_f32_e32 v151, v151, v155
	v_mul_f32_e32 v155, v15, v159
	v_add_f32_e32 v148, v149, v148
	v_mul_f32_e32 v149, v27, v153
	v_fmac_f32_e32 v155, v14, v158
	v_mul_f32_e32 v158, v17, v163
	v_mul_f32_e32 v153, v11, v153
	v_fmac_f32_e32 v149, v26, v152
	v_mul_f32_e32 v167, v29, v157
	v_fmac_f32_e32 v158, v16, v162
	v_fmac_f32_e32 v153, v10, v152
	v_mul_f32_e32 v152, v13, v157
	v_fmac_f32_e32 v167, v28, v156
	v_add_f32_e32 v151, 0, v151
	v_add_f32_e32 v155, v155, v158
	v_fmac_f32_e32 v152, v12, v156
	v_add_f32_e32 v149, v149, v167
	v_add_f32_e32 v151, v155, v151
	v_add_f32_e32 v152, v153, v152
	v_add_f32_e32 v149, v149, v148
	v_mul_f32_e32 v148, v19, v161
	v_mul_f32_e32 v167, v21, v165
	v_add_f32_e32 v151, v152, v151
	v_mul_f32_e32 v152, v3, v161
	v_mul_f32_e32 v153, v5, v165
	v_fmac_f32_e32 v148, v18, v160
	v_fmac_f32_e32 v167, v20, v164
	v_fmac_f32_e32 v152, v2, v160
	v_fmac_f32_e32 v153, v4, v164
	v_add_f32_e32 v167, v148, v167
	v_add_f32_e32 v152, v152, v153
	v_add_f32_e32 v167, v167, v149
	v_add_f32_e32 v151, v152, v151
	ds_bpermute_b32 v150, v1, v166
	ds_bpermute_b32 v154, v1, v167
	ds_bpermute_b32 v152, v1, v151
	s_waitcnt lgkmcnt(4)
	v_add_f32_e32 v140, v140, v141
	ds_bpermute_b32 v141, v144, v140
	s_waitcnt lgkmcnt(3)
	v_add_f32_e32 v150, v166, v150
	s_waitcnt lgkmcnt(2)
	v_add_f32_e32 v154, v167, v154
	s_waitcnt lgkmcnt(1)
	v_add_f32_e32 v151, v151, v152
	ds_bpermute_b32 v153, v137, v150
	ds_bpermute_b32 v155, v137, v154
	ds_bpermute_b32 v152, v137, v151
	s_waitcnt lgkmcnt(3)
	v_add_f32_e32 v140, v140, v141
	ds_bpermute_b32 v141, v145, v140
	s_waitcnt lgkmcnt(3)
	v_add_f32_e32 v150, v150, v153
	s_waitcnt lgkmcnt(2)
	v_add_f32_e32 v154, v154, v155
	s_waitcnt lgkmcnt(1)
	v_add_f32_e32 v151, v151, v152
	ds_bpermute_b32 v153, v142, v150
	ds_bpermute_b32 v155, v142, v154
	ds_bpermute_b32 v152, v142, v151
	ds_bpermute_b32 v148, v145, v146
	ds_bpermute_b32 v149, v145, v147
	s_waitcnt lgkmcnt(4)
	v_add_f32_e32 v150, v150, v153
	s_waitcnt lgkmcnt(3)
	v_add_f32_e32 v154, v154, v155
	s_waitcnt lgkmcnt(2)
	v_add_f32_e32 v151, v151, v152
	ds_bpermute_b32 v153, v143, v150
	ds_bpermute_b32 v155, v143, v154
	ds_bpermute_b32 v152, v143, v151
	s_waitcnt lgkmcnt(2)
	v_add_f32_e32 v150, v150, v153
	s_waitcnt lgkmcnt(1)
	v_add_f32_e32 v154, v154, v155
	s_waitcnt lgkmcnt(0)
	v_add_f32_e32 v156, v151, v152
	ds_bpermute_b32 v153, v144, v150
	ds_bpermute_b32 v155, v144, v154
	ds_bpermute_b32 v157, v144, v156
	s_waitcnt lgkmcnt(2)
	v_add_f32_e32 v150, v150, v153
	s_waitcnt lgkmcnt(1)
	v_add_f32_e32 v152, v154, v155
	s_waitcnt lgkmcnt(0)
	v_add_f32_e32 v154, v156, v157
	ds_bpermute_b32 v151, v145, v150
	ds_bpermute_b32 v153, v145, v152
	ds_bpermute_b32 v155, v145, v154
	s_and_saveexec_b64 s[44:45], s[0:1]
	s_cbranch_execz .Lshw1_skip
	v_add_f32_e32 v138, v138, v139
	v_add_f32_e32 v131, v131, v136
	v_add_f32_e32 v140, v140, v141
	v_cndmask_b32_e64 v131, v131, v138, s[4:5]
	v_add_f32_e32 v146, v146, v148
	v_cndmask_b32_e64 v131, v131, v140, s[6:7]
	v_add_f32_e32 v147, v147, v149
	v_cndmask_b32_e64 v131, v131, v146, s[8:9]
	s_waitcnt lgkmcnt(2)
	v_add_f32_e32 v150, v150, v151
	v_cndmask_b32_e64 v131, v131, v147, s[10:11]
	s_waitcnt lgkmcnt(1)
	v_add_f32_e32 v152, v152, v153
	v_cndmask_b32_e64 v131, v131, v150, s[12:13]
	s_waitcnt lgkmcnt(0)
	v_add_f32_e32 v154, v154, v155
	v_cndmask_b32_e64 v131, v131, v152, s[14:15]
	v_cndmask_b32_e64 v131, v131, v154, s[16:17]
	global_store_dword v[132:133], v131, off
	s_waitcnt vmcnt(1)
	s_branch .LBB0_165

.LBB0_418:
.LBB0_419:
	s_lshr_b32 s0, s3, 7
	s_lshl_b32 s0, s0, 23
	s_and_b32 s1, s3, 15
	s_lshl_b32 s1, s1, 19
	s_or_b32 s0, s0, s1
	s_bfe_u32 s1, s3, 0x30004
	s_lshl_b32 s1, s1, 8
	s_or_b32 s0, s0, s1
	s_add_u32 s60, s25, s0
	s_addc_u32 s61, s28, 0
	s_add_u32 s46, s21, s0
	s_addc_u32 s47, s24, 0
	s_lshr_b32 s1, s3, 6
	s_mul_i32 s1, s1, 0x110000
	s_add_u32 s62, s9, s1
	s_addc_u32 s63, s20, 0
	s_add_u32 s64, s29, s1
	s_addc_u32 s65, s30, 0
	v_readfirstlane_b32 s44, v1
	s_lshr_b32 s6, s44, 6
	s_lshl_b32 s45, s6, 10
	s_lshl_b32 s44, s6, 9
	s_add_i32 s44, s44, 0x20000
	v_and_b32_e32 v136, 15, v1
	v_bfe_u32 v137, v1, 4, 2
	v_lshrrev_b32_e32 v130, 4, v1
	v_xor_b32_e32 v131, v1, v130
	v_and_b32_e32 v131, 15, v131
	v_lshlrev_b32_e32 v131, 4, v131
	v_lshl_or_b32 v150, v130, 8, v131
	v_add_u32_e32 v151, 0x2000, v150
	v_and_b32_e32 v131, 7, v130
	v_lshlrev_b32_e32 v131, 1, v131
	v_xor_b32_e32 v131, v1, v131
	v_and_b32_e32 v131, 15, v131
	v_lshlrev_b32_e32 v131, 4, v131
	v_lshl_or_b32 v152, v130, 8, v131
	v_add_u32_e32 v153, 0x2000, v152
	v_lshlrev_b32_e32 v130, 8, v136
	v_add_u32_e32 v131, 0, v137
	v_xor_b32_e32 v131, v131, v136
	v_lshl_or_b32 v183, v131, 4, v130
	v_add_u32_e32 v187, 0x10000, v183
	v_add_u32_e32 v131, 4, v137
	v_xor_b32_e32 v131, v131, v136
	v_lshl_or_b32 v184, v131, 4, v130
	v_add_u32_e32 v188, 0x10000, v184
	v_add_u32_e32 v131, 8, v137
	v_xor_b32_e32 v131, v131, v136
	v_lshl_or_b32 v185, v131, 4, v130
	v_add_u32_e32 v189, 0x10000, v185
	v_add_u32_e32 v131, 12, v137
	v_xor_b32_e32 v131, v131, v136
	v_lshl_or_b32 v186, v131, 4, v130
	v_add_u32_e32 v190, 0x10000, v186
	v_bfe_u32 v130, v1, 2, 2
	v_lshl_or_b32 v131, v137, 2, v130
	v_and_b32_e32 v132, 7, v131
	v_and_b32_e32 v133, 3, v1
	v_lshlrev_b32_e32 v133, 3, v133
	v_lshl_or_b32 v133, v131, 8, v133
	v_xor_b32_e32 v134, 0, v132
	v_lshl_or_b32 v240, v134, 5, v133
	v_add_u32_e32 v142, 0x10000, v240
	v_xor_b32_e32 v134, 1, v132
	v_lshl_or_b32 v241, v134, 5, v133
	v_add_u32_e32 v143, 0x10000, v241
	v_xor_b32_e32 v134, 2, v132
	v_lshl_or_b32 v242, v134, 5, v133
	v_add_u32_e32 v144, 0x10000, v242
	v_xor_b32_e32 v134, 3, v132
	v_lshl_or_b32 v243, v134, 5, v133
	v_add_u32_e32 v145, 0x10000, v243
	v_xor_b32_e32 v134, 4, v132
	v_lshl_or_b32 v244, v134, 5, v133
	v_add_u32_e32 v146, 0x10000, v244
	v_xor_b32_e32 v134, 5, v132
	v_lshl_or_b32 v245, v134, 5, v133
	v_add_u32_e32 v147, 0x10000, v245
	v_xor_b32_e32 v134, 6, v132
	v_lshl_or_b32 v246, v134, 5, v133
	v_add_u32_e32 v148, 0x10000, v246
	v_xor_b32_e32 v134, 7, v132
	v_lshl_or_b32 v247, v134, 5, v133
	v_add_u32_e32 v149, 0x10000, v247
	s_lshl_b32 s18, s6, 16
	v_lshlrev_b32_e32 v130, 11, v136
	v_lshl_or_b32 v130, v137, 4, v130
	v_add_u32_e32 v154, s18, v130
	v_add_u32_e32 v155, 0x8000, v154
	v_lshlrev_b32_e32 v130, 13, v137
	v_lshl_or_b32 v130, v136, 1, v130
	v_add_u32_e32 v156, s18, v130
	v_add_u32_e32 v157, 0x1000, v156
	v_add_u32_e32 v158, 0x8000, v156
	v_add_u32_e32 v159, 0x9000, v156
	v_and_b32_e32 v130, 63, v1
	v_lshl_add_u32 v160, v130, 2, s44
	v_lshl_add_u32 v161, v137, 4, s44
	s_add_i32 m0, s45, 0x0
	s_nop 0
	global_load_lds_dwordx4 v152, s[64:65]
	s_add_i32 m0, s45, 0x4000
	s_nop 0
	global_load_lds_dwordx4 v150, s[62:63]
	s_add_i32 m0, s45, 0x2000
	s_nop 0
	global_load_lds_dwordx4 v153, s[64:65]
	s_add_i32 m0, s45, 0x6000
	s_nop 0
	global_load_lds_dwordx4 v151, s[62:63]
	s_add_u32 s62, s62, 0x4000
	s_addc_u32 s63, s63, 0
	s_add_u32 s64, s64, 0x4000
	s_addc_u32 s65, s65, 0
	s_add_i32 m0, s45, 0x8000
	s_nop 0
	global_load_lds_dwordx4 v152, s[64:65]
	s_add_i32 m0, s45, 0xc000
	s_nop 0
	global_load_lds_dwordx4 v150, s[62:63]
	s_add_i32 m0, s45, 0xa000
	s_nop 0
	global_load_lds_dwordx4 v153, s[64:65]
	s_add_i32 m0, s45, 0xe000
	s_nop 0
	global_load_lds_dwordx4 v151, s[62:63]
	s_add_u32 s62, s62, 0x4000
	s_addc_u32 s63, s63, 0
	s_add_u32 s64, s64, 0x4000
	s_addc_u32 s65, s65, 0
	global_load_dwordx4 v[98:101], v154, s[60:61]
	global_load_dwordx4 v[102:105], v154, s[60:61] offset:64
	global_load_dwordx4 v[106:109], v154, s[60:61] offset:128
	global_load_dwordx4 v[110:113], v154, s[60:61] offset:192
	global_load_dwordx4 v[114:117], v155, s[60:61]
	global_load_dwordx4 v[118:121], v155, s[60:61] offset:64
	global_load_dwordx4 v[122:125], v155, s[60:61] offset:128
	global_load_dwordx4 v[126:129], v155, s[60:61] offset:192
	v_mov_b32_e32 v2, 0
	v_mov_b32_e32 v3, 0
	v_mov_b32_e32 v4, 0
	v_mov_b32_e32 v5, 0
	v_mov_b32_e32 v6, 0
	v_mov_b32_e32 v7, 0
	v_mov_b32_e32 v8, 0
	v_mov_b32_e32 v9, 0
	v_mov_b32_e32 v10, 0
	v_mov_b32_e32 v11, 0
	v_mov_b32_e32 v12, 0
	v_mov_b32_e32 v13, 0
	v_mov_b32_e32 v14, 0
	v_mov_b32_e32 v15, 0
	v_mov_b32_e32 v16, 0
	v_mov_b32_e32 v17, 0
	v_mov_b32_e32 v18, 0
	v_mov_b32_e32 v19, 0
	v_mov_b32_e32 v20, 0
	v_mov_b32_e32 v21, 0
	v_mov_b32_e32 v22, 0
	v_mov_b32_e32 v23, 0
	v_mov_b32_e32 v24, 0
	v_mov_b32_e32 v25, 0
	v_mov_b32_e32 v26, 0
	v_mov_b32_e32 v27, 0
	v_mov_b32_e32 v28, 0
	v_mov_b32_e32 v29, 0
	v_mov_b32_e32 v30, 0
	v_mov_b32_e32 v31, 0
	v_mov_b32_e32 v32, 0
	v_mov_b32_e32 v33, 0
	v_mov_b32_e32 v34, 0
	v_mov_b32_e32 v35, 0
	v_mov_b32_e32 v36, 0
	v_mov_b32_e32 v37, 0
	v_mov_b32_e32 v38, 0
	v_mov_b32_e32 v39, 0
	v_mov_b32_e32 v40, 0
	v_mov_b32_e32 v41, 0
	v_mov_b32_e32 v42, 0
	v_mov_b32_e32 v43, 0
	v_mov_b32_e32 v44, 0
	v_mov_b32_e32 v45, 0
	v_mov_b32_e32 v46, 0
	v_mov_b32_e32 v47, 0
	v_mov_b32_e32 v48, 0
	v_mov_b32_e32 v49, 0
	v_mov_b32_e32 v50, 0
	v_mov_b32_e32 v51, 0
	v_mov_b32_e32 v52, 0
	v_mov_b32_e32 v53, 0
	v_mov_b32_e32 v54, 0
	v_mov_b32_e32 v55, 0
	v_mov_b32_e32 v56, 0
	v_mov_b32_e32 v57, 0
	v_mov_b32_e32 v58, 0
	v_mov_b32_e32 v59, 0
	v_mov_b32_e32 v60, 0
	v_mov_b32_e32 v61, 0
	v_mov_b32_e32 v62, 0
	v_mov_b32_e32 v63, 0
	v_mov_b32_e32 v64, 0
	v_mov_b32_e32 v65, 0
	v_mov_b32_e32 v165, 0
	v_mov_b32_e32 v163, 0
	s_waitcnt vmcnt(0)
.Lattn_unit:
	s_barrier
	ds_read_b128 v[166:169], v183 offset:16384
	ds_read_b128 v[170:173], v183 offset:20480
	ds_read_b128 v[174:177], v183 offset:24576
	ds_read_b128 v[178:181], v183 offset:28672
	ds_read_b128 v[224:227], v184 offset:16384
	ds_read_b128 v[228:231], v184 offset:20480
	ds_read_b128 v[232:235], v184 offset:24576
	ds_read_b128 v[236:239], v184 offset:28672
	s_waitcnt lgkmcnt(6)
	v_mfma_f32_16x16x32_bf16 v[66:69], v[166:169], v[98:101], 0
	v_mfma_f32_16x16x32_bf16 v[82:85], v[166:169], v[114:117], 0
	ds_read_b128 v[166:169], v185 offset:16384
	s_add_i32 m0, s45, 0x10000
	s_nop 0
	global_load_lds_dwordx4 v152, s[64:65]
	v_mfma_f32_16x16x32_bf16 v[70:73], v[170:173], v[98:101], 0
	v_mfma_f32_16x16x32_bf16 v[86:89], v[170:173], v[114:117], 0
	ds_read_b128 v[170:173], v185 offset:20480
	s_add_i32 m0, s45, 0x14000
	s_nop 0
	global_load_lds_dwordx4 v150, s[62:63]
	s_waitcnt lgkmcnt(6)
	v_mfma_f32_16x16x32_bf16 v[74:77], v[174:177], v[98:101], 0
	v_mfma_f32_16x16x32_bf16 v[90:93], v[174:177], v[114:117], 0
	ds_read_b128 v[174:177], v185 offset:24576
	s_add_i32 m0, s45, 0x12000
	s_nop 0
	global_load_lds_dwordx4 v153, s[64:65]
	v_mfma_f32_16x16x32_bf16 v[78:81], v[178:181], v[98:101], 0
	v_mfma_f32_16x16x32_bf16 v[94:97], v[178:181], v[114:117], 0
	ds_read_b128 v[178:181], v185 offset:28672
	s_add_i32 m0, s45, 0x16000
	s_nop 0
	global_load_lds_dwordx4 v151, s[62:63]
	s_add_u32 s62, s62, 0x4000
	s_addc_u32 s63, s63, 0
	s_add_u32 s64, s64, 0x4000
	s_addc_u32 s65, s65, 0
	s_waitcnt lgkmcnt(6)
	v_mfma_f32_16x16x32_bf16 v[66:69], v[224:227], v[102:105], v[66:69]
	v_mfma_f32_16x16x32_bf16 v[82:85], v[224:227], v[118:121], v[82:85]
	ds_read_b128 v[224:227], v186 offset:16384
	v_mfma_f32_16x16x32_bf16 v[70:73], v[228:231], v[102:105], v[70:73]
	v_mfma_f32_16x16x32_bf16 v[86:89], v[228:231], v[118:121], v[86:89]
	ds_read_b128 v[228:231], v186 offset:20480
	s_waitcnt lgkmcnt(6)
	v_mfma_f32_16x16x32_bf16 v[74:77], v[232:235], v[102:105], v[74:77]
	v_mfma_f32_16x16x32_bf16 v[90:93], v[232:235], v[118:121], v[90:93]
	ds_read_b128 v[232:235], v186 offset:24576
	v_mfma_f32_16x16x32_bf16 v[78:81], v[236:239], v[102:105], v[78:81]
	v_mfma_f32_16x16x32_bf16 v[94:97], v[236:239], v[118:121], v[94:97]
	ds_read_b128 v[236:239], v186 offset:28672
	s_waitcnt lgkmcnt(6)
	v_mfma_f32_16x16x32_bf16 v[66:69], v[166:169], v[106:109], v[66:69]
	v_mfma_f32_16x16x32_bf16 v[82:85], v[166:169], v[122:125], v[82:85]
	v_mfma_f32_16x16x32_bf16 v[70:73], v[170:173], v[106:109], v[70:73]
	v_mfma_f32_16x16x32_bf16 v[86:89], v[170:173], v[122:125], v[86:89]
	s_waitcnt lgkmcnt(4)
	v_mfma_f32_16x16x32_bf16 v[74:77], v[174:177], v[106:109], v[74:77]
	v_mfma_f32_16x16x32_bf16 v[90:93], v[174:177], v[122:125], v[90:93]
	v_mfma_f32_16x16x32_bf16 v[78:81], v[178:181], v[106:109], v[78:81]
	v_mfma_f32_16x16x32_bf16 v[94:97], v[178:181], v[122:125], v[94:97]
	s_waitcnt lgkmcnt(2)
	v_mfma_f32_16x16x32_bf16 v[66:69], v[224:227], v[110:113], v[66:69]
	v_mfma_f32_16x16x32_bf16 v[82:85], v[224:227], v[126:129], v[82:85]
	v_mfma_f32_16x16x32_bf16 v[70:73], v[228:231], v[110:113], v[70:73]
	v_mfma_f32_16x16x32_bf16 v[86:89], v[228:231], v[126:129], v[86:89]
	s_waitcnt lgkmcnt(0)
	v_mfma_f32_16x16x32_bf16 v[74:77], v[232:235], v[110:113], v[74:77]
	v_mfma_f32_16x16x32_bf16 v[90:93], v[232:235], v[126:129], v[90:93]
	v_mfma_f32_16x16x32_bf16 v[78:81], v[236:239], v[110:113], v[78:81]
	v_mfma_f32_16x16x32_bf16 v[94:97], v[236:239], v[126:129], v[94:97]
	s_nop 7
	s_nop 3
	v_exp_f32_e32 v66, v66
	v_exp_f32_e32 v67, v67
	v_exp_f32_e32 v68, v68
	v_exp_f32_e32 v69, v69
	v_exp_f32_e32 v82, v82
	v_exp_f32_e32 v83, v83
	v_exp_f32_e32 v84, v84
	v_exp_f32_e32 v85, v85
	v_exp_f32_e32 v70, v70
	v_exp_f32_e32 v71, v71
	v_exp_f32_e32 v72, v72
	v_exp_f32_e32 v73, v73
	v_exp_f32_e32 v86, v86
	v_exp_f32_e32 v87, v87
	v_exp_f32_e32 v88, v88
	v_exp_f32_e32 v89, v89
	v_exp_f32_e32 v74, v74
	v_exp_f32_e32 v75, v75
	v_exp_f32_e32 v76, v76
	v_exp_f32_e32 v77, v77
	v_exp_f32_e32 v90, v90
	v_exp_f32_e32 v91, v91
	v_exp_f32_e32 v92, v92
	v_exp_f32_e32 v93, v93
	v_exp_f32_e32 v78, v78
	v_exp_f32_e32 v79, v79
	v_exp_f32_e32 v80, v80
	v_exp_f32_e32 v81, v81
	v_exp_f32_e32 v94, v94
	v_exp_f32_e32 v95, v95
	v_exp_f32_e32 v96, v96
	v_exp_f32_e32 v97, v97
	ds_read_b128 v[166:169], v183 offset:49152
	ds_read_b128 v[170:173], v183 offset:53248
	ds_read_b128 v[174:177], v183 offset:57344
	ds_read_b128 v[178:181], v183 offset:61440
	ds_read_b128 v[224:227], v184 offset:49152
	ds_read_b128 v[228:231], v184 offset:53248
	ds_read_b128 v[232:235], v184 offset:57344
	ds_read_b128 v[236:239], v184 offset:61440
	s_waitcnt vmcnt(0)
	s_barrier
	s_mov_b32 s66, 16
.Lattn_loop:
	s_waitcnt lgkmcnt(6)
	v_mfma_f32_16x16x32_bf16 v[192:195], v[166:169], v[98:101], 0
	v_mfma_f32_16x16x32_bf16 v[208:211], v[166:169], v[114:117], 0
	ds_read_b128 v[166:169], v185 offset:49152
	s_add_i32 m0, s45, 0x18000
	v_add_f32_e32 v130, v66, v67
	v_add_f32_e32 v131, v68, v69
	v_add_f32_e32 v130, v70, v130
	global_load_lds_dwordx4 v152, s[64:65]
	v_mfma_f32_16x16x32_bf16 v[196:199], v[170:173], v[98:101], 0
	v_mfma_f32_16x16x32_bf16 v[212:215], v[170:173], v[114:117], 0
	ds_read_b128 v[170:173], v185 offset:53248
	s_add_i32 m0, s45, 0x1c000
	v_add_f32_e32 v131, v71, v131
	v_add_f32_e32 v130, v72, v130
	v_add_f32_e32 v131, v73, v131
	global_load_lds_dwordx4 v150, s[62:63]
	s_waitcnt lgkmcnt(6)
	v_mfma_f32_16x16x32_bf16 v[200:203], v[174:177], v[98:101], 0
	v_mfma_f32_16x16x32_bf16 v[216:219], v[174:177], v[114:117], 0
	ds_read_b128 v[174:177], v185 offset:57344
	s_add_i32 m0, s45, 0x1a000
	v_add_f32_e32 v130, v74, v130
	v_add_f32_e32 v131, v75, v131
	v_add_f32_e32 v130, v76, v130
	global_load_lds_dwordx4 v153, s[64:65]
	v_mfma_f32_16x16x32_bf16 v[204:207], v[178:181], v[98:101], 0
	v_mfma_f32_16x16x32_bf16 v[220:223], v[178:181], v[114:117], 0
	ds_read_b128 v[178:181], v185 offset:61440
	s_add_i32 m0, s45, 0x1e000
	v_add_f32_e32 v131, v77, v131
	v_add_f32_e32 v130, v78, v130
	v_add_f32_e32 v131, v79, v131
	global_load_lds_dwordx4 v151, s[62:63]
	s_add_u32 s62, s62, 0x4000
	s_addc_u32 s63, s63, 0
	s_add_u32 s64, s64, 0x4000
	s_addc_u32 s65, s65, 0
	s_waitcnt lgkmcnt(6)
	v_mfma_f32_16x16x32_bf16 v[192:195], v[224:227], v[102:105], v[192:195]
	v_mfma_f32_16x16x32_bf16 v[208:211], v[224:227], v[118:121], v[208:211]
	ds_read_b128 v[224:227], v186 offset:49152
	v_add_f32_e32 v130, v80, v130
	v_add_f32_e32 v131, v81, v131
	v_add_f32_e32 v130, v130, v131
	v_mfma_f32_16x16x32_bf16 v[196:199], v[228:231], v[102:105], v[196:199]
	v_mfma_f32_16x16x32_bf16 v[212:215], v[228:231], v[118:121], v[212:215]
	ds_read_b128 v[228:231], v186 offset:53248
	v_add_f32_e32 v165, v165, v130
	v_add_f32_e32 v132, v82, v83
	v_add_f32_e32 v133, v84, v85
	s_waitcnt lgkmcnt(6)
	v_mfma_f32_16x16x32_bf16 v[200:203], v[232:235], v[102:105], v[200:203]
	v_mfma_f32_16x16x32_bf16 v[216:219], v[232:235], v[118:121], v[216:219]
	ds_read_b128 v[232:235], v186 offset:57344
	v_add_f32_e32 v132, v86, v132
	v_add_f32_e32 v133, v87, v133
	v_add_f32_e32 v132, v88, v132
	v_mfma_f32_16x16x32_bf16 v[204:207], v[236:239], v[102:105], v[204:207]
	v_mfma_f32_16x16x32_bf16 v[220:223], v[236:239], v[118:121], v[220:223]
	ds_read_b128 v[236:239], v186 offset:61440
	v_add_f32_e32 v133, v89, v133
	v_add_f32_e32 v132, v90, v132
	v_add_f32_e32 v133, v91, v133
	s_waitcnt lgkmcnt(6)
	v_mfma_f32_16x16x32_bf16 v[192:195], v[166:169], v[106:109], v[192:195]
	v_mfma_f32_16x16x32_bf16 v[208:211], v[166:169], v[122:125], v[208:211]
	ds_read_b64_tr_b16 v[166:167], v240 offset:0
	ds_read_b64_tr_b16 v[168:169], v240 offset:4096
	v_add_f32_e32 v132, v92, v132
	v_add_f32_e32 v133, v93, v133
	v_add_f32_e32 v132, v94, v132
	v_mfma_f32_16x16x32_bf16 v[196:199], v[170:173], v[106:109], v[196:199]
	v_mfma_f32_16x16x32_bf16 v[212:215], v[170:173], v[122:125], v[212:215]
	ds_read_b64_tr_b16 v[170:171], v241 offset:0
	ds_read_b64_tr_b16 v[172:173], v241 offset:4096
	v_add_f32_e32 v133, v95, v133
	v_add_f32_e32 v132, v96, v132
	v_add_f32_e32 v133, v97, v133
	s_waitcnt lgkmcnt(8)
	v_mfma_f32_16x16x32_bf16 v[200:203], v[174:177], v[106:109], v[200:203]
	v_mfma_f32_16x16x32_bf16 v[216:219], v[174:177], v[122:125], v[216:219]
	ds_read_b64_tr_b16 v[174:175], v242 offset:0
	ds_read_b64_tr_b16 v[176:177], v242 offset:4096
	v_add_f32_e32 v132, v132, v133
	v_add_f32_e32 v163, v163, v132
	v_cvt_pk_bf16_f32 v66, v66, v67
	v_mfma_f32_16x16x32_bf16 v[204:207], v[178:181], v[106:109], v[204:207]
	v_mfma_f32_16x16x32_bf16 v[220:223], v[178:181], v[122:125], v[220:223]
	ds_read_b64_tr_b16 v[178:179], v243 offset:0
	ds_read_b64_tr_b16 v[180:181], v243 offset:4096
	v_cvt_pk_bf16_f32 v67, v68, v69
	v_cvt_pk_bf16_f32 v68, v70, v71
	v_cvt_pk_bf16_f32 v69, v72, v73
	s_waitcnt lgkmcnt(10)
	v_mfma_f32_16x16x32_bf16 v[192:195], v[224:227], v[110:113], v[192:195]
	v_mfma_f32_16x16x32_bf16 v[208:211], v[224:227], v[126:129], v[208:211]
	ds_read_b64_tr_b16 v[224:225], v244 offset:0
	ds_read_b64_tr_b16 v[226:227], v244 offset:4096
	v_cvt_pk_bf16_f32 v74, v74, v75
	v_cvt_pk_bf16_f32 v75, v76, v77
	v_cvt_pk_bf16_f32 v76, v78, v79
	v_mfma_f32_16x16x32_bf16 v[196:199], v[228:231], v[110:113], v[196:199]
	v_mfma_f32_16x16x32_bf16 v[212:215], v[228:231], v[126:129], v[212:215]
	ds_read_b64_tr_b16 v[228:229], v245 offset:0
	ds_read_b64_tr_b16 v[230:231], v245 offset:4096
	v_cvt_pk_bf16_f32 v77, v80, v81
	v_cvt_pk_bf16_f32 v82, v82, v83
	v_cvt_pk_bf16_f32 v83, v84, v85
	s_waitcnt lgkmcnt(12)
	v_mfma_f32_16x16x32_bf16 v[200:203], v[232:235], v[110:113], v[200:203]
	v_mfma_f32_16x16x32_bf16 v[216:219], v[232:235], v[126:129], v[216:219]
	v_cvt_pk_bf16_f32 v84, v86, v87
	v_cvt_pk_bf16_f32 v85, v88, v89
	v_cvt_pk_bf16_f32 v90, v90, v91
	v_mfma_f32_16x16x32_bf16 v[204:207], v[236:239], v[110:113], v[204:207]
	v_mfma_f32_16x16x32_bf16 v[220:223], v[236:239], v[126:129], v[220:223]
	v_cvt_pk_bf16_f32 v91, v92, v93
	v_cvt_pk_bf16_f32 v92, v94, v95
	v_cvt_pk_bf16_f32 v93, v96, v97
	s_waitcnt lgkmcnt(8)
	v_mfma_f32_16x16x32_bf16 v[2:5], v[66:69], v[166:169], v[2:5]
	v_mfma_f32_16x16x32_bf16 v[34:37], v[82:85], v[166:169], v[34:37]
	ds_read_b64_tr_b16 v[232:233], v246 offset:0
	ds_read_b64_tr_b16 v[234:235], v246 offset:4096
	v_mfma_f32_16x16x32_bf16 v[6:9], v[66:69], v[170:173], v[6:9]
	v_mfma_f32_16x16x32_bf16 v[38:41], v[82:85], v[170:173], v[38:41]
	ds_read_b64_tr_b16 v[236:237], v247 offset:0
	ds_read_b64_tr_b16 v[238:239], v247 offset:4096
	s_waitcnt lgkmcnt(8)
	v_mfma_f32_16x16x32_bf16 v[10:13], v[66:69], v[174:177], v[10:13]
	v_mfma_f32_16x16x32_bf16 v[42:45], v[82:85], v[174:177], v[42:45]
	ds_read_b64_tr_b16 v[166:167], v240 offset:8192
	ds_read_b64_tr_b16 v[168:169], v240 offset:12288
	v_exp_f32_e32 v192, v192
	v_exp_f32_e32 v193, v193
	v_exp_f32_e32 v194, v194
	v_mfma_f32_16x16x32_bf16 v[14:17], v[66:69], v[178:181], v[14:17]
	v_mfma_f32_16x16x32_bf16 v[46:49], v[82:85], v[178:181], v[46:49]
	ds_read_b64_tr_b16 v[170:171], v241 offset:8192
	ds_read_b64_tr_b16 v[172:173], v241 offset:12288
	v_exp_f32_e32 v195, v195
	v_exp_f32_e32 v208, v208
	s_waitcnt lgkmcnt(8)
	v_mfma_f32_16x16x32_bf16 v[18:21], v[66:69], v[224:227], v[18:21]
	v_mfma_f32_16x16x32_bf16 v[50:53], v[82:85], v[224:227], v[50:53]
	ds_read_b64_tr_b16 v[174:175], v242 offset:8192
	ds_read_b64_tr_b16 v[176:177], v242 offset:12288
	v_exp_f32_e32 v209, v209
	v_exp_f32_e32 v210, v210
	v_mfma_f32_16x16x32_bf16 v[22:25], v[66:69], v[228:231], v[22:25]
	v_mfma_f32_16x16x32_bf16 v[54:57], v[82:85], v[228:231], v[54:57]
	ds_read_b64_tr_b16 v[178:179], v243 offset:8192
	ds_read_b64_tr_b16 v[180:181], v243 offset:12288
	v_exp_f32_e32 v211, v211
	v_exp_f32_e32 v196, v196
	v_exp_f32_e32 v197, v197
	s_waitcnt lgkmcnt(8)
	v_mfma_f32_16x16x32_bf16 v[26:29], v[66:69], v[232:235], v[26:29]
	v_mfma_f32_16x16x32_bf16 v[58:61], v[82:85], v[232:235], v[58:61]
	ds_read_b64_tr_b16 v[224:225], v244 offset:8192
	ds_read_b64_tr_b16 v[226:227], v244 offset:12288
	v_exp_f32_e32 v198, v198
	v_exp_f32_e32 v199, v199
	v_mfma_f32_16x16x32_bf16 v[30:33], v[66:69], v[236:239], v[30:33]
	v_mfma_f32_16x16x32_bf16 v[62:65], v[82:85], v[236:239], v[62:65]
	ds_read_b64_tr_b16 v[228:229], v245 offset:8192
	ds_read_b64_tr_b16 v[230:231], v245 offset:12288
	v_exp_f32_e32 v212, v212
	v_exp_f32_e32 v213, v213
	s_waitcnt lgkmcnt(8)
	v_mfma_f32_16x16x32_bf16 v[2:5], v[74:77], v[166:169], v[2:5]
	v_mfma_f32_16x16x32_bf16 v[34:37], v[90:93], v[166:169], v[34:37]
	ds_read_b64_tr_b16 v[232:233], v246 offset:8192
	ds_read_b64_tr_b16 v[234:235], v246 offset:12288
	ds_read_b128 v[166:169], v187 offset:16384
	v_exp_f32_e32 v214, v214
	v_exp_f32_e32 v215, v215
	v_mfma_f32_16x16x32_bf16 v[6:9], v[74:77], v[170:173], v[6:9]
	v_mfma_f32_16x16x32_bf16 v[38:41], v[90:93], v[170:173], v[38:41]
	ds_read_b64_tr_b16 v[236:237], v247 offset:8192
	ds_read_b64_tr_b16 v[238:239], v247 offset:12288
	ds_read_b128 v[170:173], v187 offset:20480
	v_exp_f32_e32 v200, v200
	v_exp_f32_e32 v201, v201
	v_exp_f32_e32 v202, v202
	s_waitcnt lgkmcnt(10)
	v_mfma_f32_16x16x32_bf16 v[10:13], v[74:77], v[174:177], v[10:13]
	v_mfma_f32_16x16x32_bf16 v[42:45], v[90:93], v[174:177], v[42:45]
	ds_read_b128 v[174:177], v187 offset:24576
	v_exp_f32_e32 v203, v203
	v_exp_f32_e32 v216, v216
	v_mfma_f32_16x16x32_bf16 v[14:17], v[74:77], v[178:181], v[14:17]
	v_mfma_f32_16x16x32_bf16 v[46:49], v[90:93], v[178:181], v[46:49]
	ds_read_b128 v[178:181], v187 offset:28672
	v_exp_f32_e32 v217, v217
	v_exp_f32_e32 v218, v218
	s_waitcnt lgkmcnt(8)
	v_mfma_f32_16x16x32_bf16 v[18:21], v[74:77], v[224:227], v[18:21]
	v_mfma_f32_16x16x32_bf16 v[50:53], v[90:93], v[224:227], v[50:53]
	ds_read_b128 v[224:227], v188 offset:16384
	v_exp_f32_e32 v219, v219
	v_exp_f32_e32 v204, v204
	v_exp_f32_e32 v205, v205
	v_mfma_f32_16x16x32_bf16 v[22:25], v[74:77], v[228:231], v[22:25]
	v_mfma_f32_16x16x32_bf16 v[54:57], v[90:93], v[228:231], v[54:57]
	ds_read_b128 v[228:231], v188 offset:20480
	v_exp_f32_e32 v206, v206
	v_exp_f32_e32 v207, v207
	s_waitcnt lgkmcnt(5)
	v_mfma_f32_16x16x32_bf16 v[26:29], v[74:77], v[232:235], v[26:29]
	v_mfma_f32_16x16x32_bf16 v[58:61], v[90:93], v[232:235], v[58:61]
	ds_read_b128 v[232:235], v188 offset:24576
	v_exp_f32_e32 v220, v220
	v_exp_f32_e32 v221, v221
	v_mfma_f32_16x16x32_bf16 v[30:33], v[74:77], v[236:239], v[30:33]
	v_mfma_f32_16x16x32_bf16 v[62:65], v[90:93], v[236:239], v[62:65]
	ds_read_b128 v[236:239], v188 offset:28672
	v_exp_f32_e32 v222, v222
	v_exp_f32_e32 v223, v223
	s_waitcnt vmcnt(0)
	s_barrier
	s_waitcnt lgkmcnt(6)
	v_mfma_f32_16x16x32_bf16 v[66:69], v[166:169], v[98:101], 0
	v_mfma_f32_16x16x32_bf16 v[82:85], v[166:169], v[114:117], 0
	ds_read_b128 v[166:169], v189 offset:16384
	s_add_i32 m0, s45, 0x0
	v_add_f32_e32 v130, v192, v193
	v_add_f32_e32 v131, v194, v195
	v_add_f32_e32 v130, v196, v130
	global_load_lds_dwordx4 v152, s[64:65]
	v_mfma_f32_16x16x32_bf16 v[70:73], v[170:173], v[98:101], 0
	v_mfma_f32_16x16x32_bf16 v[86:89], v[170:173], v[114:117], 0
	ds_read_b128 v[170:173], v189 offset:20480
	s_add_i32 m0, s45, 0x4000
	v_add_f32_e32 v131, v197, v131
	v_add_f32_e32 v130, v198, v130
	v_add_f32_e32 v131, v199, v131
	global_load_lds_dwordx4 v150, s[62:63]
	s_waitcnt lgkmcnt(6)
	v_mfma_f32_16x16x32_bf16 v[74:77], v[174:177], v[98:101], 0
	v_mfma_f32_16x16x32_bf16 v[90:93], v[174:177], v[114:117], 0
	ds_read_b128 v[174:177], v189 offset:24576
	s_add_i32 m0, s45, 0x2000
	v_add_f32_e32 v130, v200, v130
	v_add_f32_e32 v131, v201, v131
	v_add_f32_e32 v130, v202, v130
	global_load_lds_dwordx4 v153, s[64:65]
	v_mfma_f32_16x16x32_bf16 v[78:81], v[178:181], v[98:101], 0
	v_mfma_f32_16x16x32_bf16 v[94:97], v[178:181], v[114:117], 0
	ds_read_b128 v[178:181], v189 offset:28672
	s_add_i32 m0, s45, 0x6000
	v_add_f32_e32 v131, v203, v131
	v_add_f32_e32 v130, v204, v130
	v_add_f32_e32 v131, v205, v131
	global_load_lds_dwordx4 v151, s[62:63]
	s_add_u32 s62, s62, 0x4000
	s_addc_u32 s63, s63, 0
	s_add_u32 s64, s64, 0x4000
	s_addc_u32 s65, s65, 0
	s_waitcnt lgkmcnt(6)
	v_mfma_f32_16x16x32_bf16 v[66:69], v[224:227], v[102:105], v[66:69]
	v_mfma_f32_16x16x32_bf16 v[82:85], v[224:227], v[118:121], v[82:85]
	ds_read_b128 v[224:227], v190 offset:16384
	v_add_f32_e32 v130, v206, v130
	v_add_f32_e32 v131, v207, v131
	v_add_f32_e32 v130, v130, v131
	v_mfma_f32_16x16x32_bf16 v[70:73], v[228:231], v[102:105], v[70:73]
	v_mfma_f32_16x16x32_bf16 v[86:89], v[228:231], v[118:121], v[86:89]
	ds_read_b128 v[228:231], v190 offset:20480
	v_add_f32_e32 v165, v165, v130
	v_add_f32_e32 v132, v208, v209
	v_add_f32_e32 v133, v210, v211
	s_waitcnt lgkmcnt(6)
	v_mfma_f32_16x16x32_bf16 v[74:77], v[232:235], v[102:105], v[74:77]
	v_mfma_f32_16x16x32_bf16 v[90:93], v[232:235], v[118:121], v[90:93]
	ds_read_b128 v[232:235], v190 offset:24576
	v_add_f32_e32 v132, v212, v132
	v_add_f32_e32 v133, v213, v133
	v_add_f32_e32 v132, v214, v132
	v_mfma_f32_16x16x32_bf16 v[78:81], v[236:239], v[102:105], v[78:81]
	v_mfma_f32_16x16x32_bf16 v[94:97], v[236:239], v[118:121], v[94:97]
	ds_read_b128 v[236:239], v190 offset:28672
	v_add_f32_e32 v133, v215, v133
	v_add_f32_e32 v132, v216, v132
	v_add_f32_e32 v133, v217, v133
	s_waitcnt lgkmcnt(6)
	v_mfma_f32_16x16x32_bf16 v[66:69], v[166:169], v[106:109], v[66:69]
	v_mfma_f32_16x16x32_bf16 v[82:85], v[166:169], v[122:125], v[82:85]
	ds_read_b64_tr_b16 v[166:167], v240 offset:32768
	ds_read_b64_tr_b16 v[168:169], v240 offset:36864
	v_add_f32_e32 v132, v218, v132
	v_add_f32_e32 v133, v219, v133
	v_add_f32_e32 v132, v220, v132
	v_mfma_f32_16x16x32_bf16 v[70:73], v[170:173], v[106:109], v[70:73]
	v_mfma_f32_16x16x32_bf16 v[86:89], v[170:173], v[122:125], v[86:89]
	ds_read_b64_tr_b16 v[170:171], v241 offset:32768
	ds_read_b64_tr_b16 v[172:173], v241 offset:36864
	v_add_f32_e32 v133, v221, v133
	v_add_f32_e32 v132, v222, v132
	v_add_f32_e32 v133, v223, v133
	s_waitcnt lgkmcnt(8)
	v_mfma_f32_16x16x32_bf16 v[74:77], v[174:177], v[106:109], v[74:77]
	v_mfma_f32_16x16x32_bf16 v[90:93], v[174:177], v[122:125], v[90:93]
	ds_read_b64_tr_b16 v[174:175], v242 offset:32768
	ds_read_b64_tr_b16 v[176:177], v242 offset:36864
	v_add_f32_e32 v132, v132, v133
	v_add_f32_e32 v163, v163, v132
	v_cvt_pk_bf16_f32 v192, v192, v193
	v_mfma_f32_16x16x32_bf16 v[78:81], v[178:181], v[106:109], v[78:81]
	v_mfma_f32_16x16x32_bf16 v[94:97], v[178:181], v[122:125], v[94:97]
	ds_read_b64_tr_b16 v[178:179], v243 offset:32768
	ds_read_b64_tr_b16 v[180:181], v243 offset:36864
	v_cvt_pk_bf16_f32 v193, v194, v195
	v_cvt_pk_bf16_f32 v194, v196, v197
	v_cvt_pk_bf16_f32 v195, v198, v199
	s_waitcnt lgkmcnt(10)
	v_mfma_f32_16x16x32_bf16 v[66:69], v[224:227], v[110:113], v[66:69]
	v_mfma_f32_16x16x32_bf16 v[82:85], v[224:227], v[126:129], v[82:85]
	ds_read_b64_tr_b16 v[224:225], v244 offset:32768
	ds_read_b64_tr_b16 v[226:227], v244 offset:36864
	v_cvt_pk_bf16_f32 v200, v200, v201
	v_cvt_pk_bf16_f32 v201, v202, v203
	v_cvt_pk_bf16_f32 v202, v204, v205
	v_mfma_f32_16x16x32_bf16 v[70:73], v[228:231], v[110:113], v[70:73]
	v_mfma_f32_16x16x32_bf16 v[86:89], v[228:231], v[126:129], v[86:89]
	ds_read_b64_tr_b16 v[228:229], v245 offset:32768
	ds_read_b64_tr_b16 v[230:231], v245 offset:36864
	v_cvt_pk_bf16_f32 v203, v206, v207
	v_cvt_pk_bf16_f32 v208, v208, v209
	v_cvt_pk_bf16_f32 v209, v210, v211
	s_waitcnt lgkmcnt(12)
	v_mfma_f32_16x16x32_bf16 v[74:77], v[232:235], v[110:113], v[74:77]
	v_mfma_f32_16x16x32_bf16 v[90:93], v[232:235], v[126:129], v[90:93]
	v_cvt_pk_bf16_f32 v210, v212, v213
	v_cvt_pk_bf16_f32 v211, v214, v215
	v_cvt_pk_bf16_f32 v216, v216, v217
	v_mfma_f32_16x16x32_bf16 v[78:81], v[236:239], v[110:113], v[78:81]
	v_mfma_f32_16x16x32_bf16 v[94:97], v[236:239], v[126:129], v[94:97]
	v_cvt_pk_bf16_f32 v217, v218, v219
	v_cvt_pk_bf16_f32 v218, v220, v221
	v_cvt_pk_bf16_f32 v219, v222, v223
	s_waitcnt lgkmcnt(8)
	v_mfma_f32_16x16x32_bf16 v[2:5], v[192:195], v[166:169], v[2:5]
	v_mfma_f32_16x16x32_bf16 v[34:37], v[208:211], v[166:169], v[34:37]
	ds_read_b64_tr_b16 v[232:233], v246 offset:32768
	ds_read_b64_tr_b16 v[234:235], v246 offset:36864
	v_mfma_f32_16x16x32_bf16 v[6:9], v[192:195], v[170:173], v[6:9]
	v_mfma_f32_16x16x32_bf16 v[38:41], v[208:211], v[170:173], v[38:41]
	ds_read_b64_tr_b16 v[236:237], v247 offset:32768
	ds_read_b64_tr_b16 v[238:239], v247 offset:36864
	s_waitcnt lgkmcnt(8)
	v_mfma_f32_16x16x32_bf16 v[10:13], v[192:195], v[174:177], v[10:13]
	v_mfma_f32_16x16x32_bf16 v[42:45], v[208:211], v[174:177], v[42:45]
	ds_read_b64_tr_b16 v[166:167], v240 offset:40960
	ds_read_b64_tr_b16 v[168:169], v240 offset:45056
	v_exp_f32_e32 v66, v66
	v_exp_f32_e32 v67, v67
	v_exp_f32_e32 v68, v68
	v_mfma_f32_16x16x32_bf16 v[14:17], v[192:195], v[178:181], v[14:17]
	v_mfma_f32_16x16x32_bf16 v[46:49], v[208:211], v[178:181], v[46:49]
	ds_read_b64_tr_b16 v[170:171], v241 offset:40960
	ds_read_b64_tr_b16 v[172:173], v241 offset:45056
	v_exp_f32_e32 v69, v69
	v_exp_f32_e32 v82, v82
	s_waitcnt lgkmcnt(8)
	v_mfma_f32_16x16x32_bf16 v[18:21], v[192:195], v[224:227], v[18:21]
	v_mfma_f32_16x16x32_bf16 v[50:53], v[208:211], v[224:227], v[50:53]
	ds_read_b64_tr_b16 v[174:175], v242 offset:40960
	ds_read_b64_tr_b16 v[176:177], v242 offset:45056
	v_exp_f32_e32 v83, v83
	v_exp_f32_e32 v84, v84
	v_mfma_f32_16x16x32_bf16 v[22:25], v[192:195], v[228:231], v[22:25]
	v_mfma_f32_16x16x32_bf16 v[54:57], v[208:211], v[228:231], v[54:57]
	ds_read_b64_tr_b16 v[178:179], v243 offset:40960
	ds_read_b64_tr_b16 v[180:181], v243 offset:45056
	v_exp_f32_e32 v85, v85
	v_exp_f32_e32 v70, v70
	v_exp_f32_e32 v71, v71
	s_waitcnt lgkmcnt(8)
	v_mfma_f32_16x16x32_bf16 v[26:29], v[192:195], v[232:235], v[26:29]
	v_mfma_f32_16x16x32_bf16 v[58:61], v[208:211], v[232:235], v[58:61]
	ds_read_b64_tr_b16 v[224:225], v244 offset:40960
	ds_read_b64_tr_b16 v[226:227], v244 offset:45056
	v_exp_f32_e32 v72, v72
	v_exp_f32_e32 v73, v73
	v_mfma_f32_16x16x32_bf16 v[30:33], v[192:195], v[236:239], v[30:33]
	v_mfma_f32_16x16x32_bf16 v[62:65], v[208:211], v[236:239], v[62:65]
	ds_read_b64_tr_b16 v[228:229], v245 offset:40960
	ds_read_b64_tr_b16 v[230:231], v245 offset:45056
	v_exp_f32_e32 v86, v86
	v_exp_f32_e32 v87, v87
	s_waitcnt lgkmcnt(8)
	v_mfma_f32_16x16x32_bf16 v[2:5], v[200:203], v[166:169], v[2:5]
	v_mfma_f32_16x16x32_bf16 v[34:37], v[216:219], v[166:169], v[34:37]
	ds_read_b64_tr_b16 v[232:233], v246 offset:40960
	ds_read_b64_tr_b16 v[234:235], v246 offset:45056
	ds_read_b128 v[166:169], v187 offset:49152
	v_exp_f32_e32 v88, v88
	v_exp_f32_e32 v89, v89
	v_mfma_f32_16x16x32_bf16 v[6:9], v[200:203], v[170:173], v[6:9]
	v_mfma_f32_16x16x32_bf16 v[38:41], v[216:219], v[170:173], v[38:41]
	ds_read_b64_tr_b16 v[236:237], v247 offset:40960
	ds_read_b64_tr_b16 v[238:239], v247 offset:45056
	ds_read_b128 v[170:173], v187 offset:53248
	v_exp_f32_e32 v74, v74
	v_exp_f32_e32 v75, v75
	v_exp_f32_e32 v76, v76
	s_waitcnt lgkmcnt(10)
	v_mfma_f32_16x16x32_bf16 v[10:13], v[200:203], v[174:177], v[10:13]
	v_mfma_f32_16x16x32_bf16 v[42:45], v[216:219], v[174:177], v[42:45]
	ds_read_b128 v[174:177], v187 offset:57344
	v_exp_f32_e32 v77, v77
	v_exp_f32_e32 v90, v90
	v_mfma_f32_16x16x32_bf16 v[14:17], v[200:203], v[178:181], v[14:17]
	v_mfma_f32_16x16x32_bf16 v[46:49], v[216:219], v[178:181], v[46:49]
	ds_read_b128 v[178:181], v187 offset:61440
	v_exp_f32_e32 v91, v91
	v_exp_f32_e32 v92, v92
	s_waitcnt lgkmcnt(8)
	v_mfma_f32_16x16x32_bf16 v[18:21], v[200:203], v[224:227], v[18:21]
	v_mfma_f32_16x16x32_bf16 v[50:53], v[216:219], v[224:227], v[50:53]
	ds_read_b128 v[224:227], v188 offset:49152
	v_exp_f32_e32 v93, v93
	v_exp_f32_e32 v78, v78
	v_exp_f32_e32 v79, v79
	v_mfma_f32_16x16x32_bf16 v[22:25], v[200:203], v[228:231], v[22:25]
	v_mfma_f32_16x16x32_bf16 v[54:57], v[216:219], v[228:231], v[54:57]
	ds_read_b128 v[228:231], v188 offset:53248
	v_exp_f32_e32 v80, v80
	v_exp_f32_e32 v81, v81
	s_waitcnt lgkmcnt(5)
	v_mfma_f32_16x16x32_bf16 v[26:29], v[200:203], v[232:235], v[26:29]
	v_mfma_f32_16x16x32_bf16 v[58:61], v[216:219], v[232:235], v[58:61]
	ds_read_b128 v[232:235], v188 offset:57344
	v_exp_f32_e32 v94, v94
	v_exp_f32_e32 v95, v95
	v_mfma_f32_16x16x32_bf16 v[30:33], v[200:203], v[236:239], v[30:33]
	v_mfma_f32_16x16x32_bf16 v[62:65], v[216:219], v[236:239], v[62:65]
	ds_read_b128 v[236:239], v188 offset:61440
	v_exp_f32_e32 v96, v96
	v_exp_f32_e32 v97, v97
	s_waitcnt vmcnt(0)
	s_barrier
	s_waitcnt lgkmcnt(6)
	v_mfma_f32_16x16x32_bf16 v[192:195], v[166:169], v[98:101], 0
	v_mfma_f32_16x16x32_bf16 v[208:211], v[166:169], v[114:117], 0
	ds_read_b128 v[166:169], v189 offset:49152
	s_add_i32 m0, s45, 0x8000
	v_add_f32_e32 v130, v66, v67
	v_add_f32_e32 v131, v68, v69
	v_add_f32_e32 v130, v70, v130
	global_load_lds_dwordx4 v152, s[64:65]
	v_mfma_f32_16x16x32_bf16 v[196:199], v[170:173], v[98:101], 0
	v_mfma_f32_16x16x32_bf16 v[212:215], v[170:173], v[114:117], 0
	ds_read_b128 v[170:173], v189 offset:53248
	s_add_i32 m0, s45, 0xc000
	v_add_f32_e32 v131, v71, v131
	v_add_f32_e32 v130, v72, v130
	v_add_f32_e32 v131, v73, v131
	global_load_lds_dwordx4 v150, s[62:63]
	s_waitcnt lgkmcnt(6)
	v_mfma_f32_16x16x32_bf16 v[200:203], v[174:177], v[98:101], 0
	v_mfma_f32_16x16x32_bf16 v[216:219], v[174:177], v[114:117], 0
	ds_read_b128 v[174:177], v189 offset:57344
	s_add_i32 m0, s45, 0xa000
	v_add_f32_e32 v130, v74, v130
	v_add_f32_e32 v131, v75, v131
	v_add_f32_e32 v130, v76, v130
	global_load_lds_dwordx4 v153, s[64:65]
	v_mfma_f32_16x16x32_bf16 v[204:207], v[178:181], v[98:101], 0
	v_mfma_f32_16x16x32_bf16 v[220:223], v[178:181], v[114:117], 0
	ds_read_b128 v[178:181], v189 offset:61440
	s_add_i32 m0, s45, 0xe000
	v_add_f32_e32 v131, v77, v131
	v_add_f32_e32 v130, v78, v130
	v_add_f32_e32 v131, v79, v131
	global_load_lds_dwordx4 v151, s[62:63]
	s_add_u32 s62, s62, 0x4000
	s_addc_u32 s63, s63, 0
	s_add_u32 s64, s64, 0x4000
	s_addc_u32 s65, s65, 0
	s_waitcnt lgkmcnt(6)
	v_mfma_f32_16x16x32_bf16 v[192:195], v[224:227], v[102:105], v[192:195]
	v_mfma_f32_16x16x32_bf16 v[208:211], v[224:227], v[118:121], v[208:211]
	ds_read_b128 v[224:227], v190 offset:49152
	v_add_f32_e32 v130, v80, v130
	v_add_f32_e32 v131, v81, v131
	v_add_f32_e32 v130, v130, v131
	v_mfma_f32_16x16x32_bf16 v[196:199], v[228:231], v[102:105], v[196:199]
	v_mfma_f32_16x16x32_bf16 v[212:215], v[228:231], v[118:121], v[212:215]
	ds_read_b128 v[228:231], v190 offset:53248
	v_add_f32_e32 v165, v165, v130
	v_add_f32_e32 v132, v82, v83
	v_add_f32_e32 v133, v84, v85
	s_waitcnt lgkmcnt(6)
	v_mfma_f32_16x16x32_bf16 v[200:203], v[232:235], v[102:105], v[200:203]
	v_mfma_f32_16x16x32_bf16 v[216:219], v[232:235], v[118:121], v[216:219]
	ds_read_b128 v[232:235], v190 offset:57344
	v_add_f32_e32 v132, v86, v132
	v_add_f32_e32 v133, v87, v133
	v_add_f32_e32 v132, v88, v132
	v_mfma_f32_16x16x32_bf16 v[204:207], v[236:239], v[102:105], v[204:207]
	v_mfma_f32_16x16x32_bf16 v[220:223], v[236:239], v[118:121], v[220:223]
	ds_read_b128 v[236:239], v190 offset:61440
	v_add_f32_e32 v133, v89, v133
	v_add_f32_e32 v132, v90, v132
	v_add_f32_e32 v133, v91, v133
	s_waitcnt lgkmcnt(6)
	v_mfma_f32_16x16x32_bf16 v[192:195], v[166:169], v[106:109], v[192:195]
	v_mfma_f32_16x16x32_bf16 v[208:211], v[166:169], v[122:125], v[208:211]
	ds_read_b64_tr_b16 v[166:167], v142 offset:0
	ds_read_b64_tr_b16 v[168:169], v142 offset:4096
	v_add_f32_e32 v132, v92, v132
	v_add_f32_e32 v133, v93, v133
	v_add_f32_e32 v132, v94, v132
	v_mfma_f32_16x16x32_bf16 v[196:199], v[170:173], v[106:109], v[196:199]
	v_mfma_f32_16x16x32_bf16 v[212:215], v[170:173], v[122:125], v[212:215]
	ds_read_b64_tr_b16 v[170:171], v143 offset:0
	ds_read_b64_tr_b16 v[172:173], v143 offset:4096
	v_add_f32_e32 v133, v95, v133
	v_add_f32_e32 v132, v96, v132
	v_add_f32_e32 v133, v97, v133
	s_waitcnt lgkmcnt(8)
	v_mfma_f32_16x16x32_bf16 v[200:203], v[174:177], v[106:109], v[200:203]
	v_mfma_f32_16x16x32_bf16 v[216:219], v[174:177], v[122:125], v[216:219]
	ds_read_b64_tr_b16 v[174:175], v144 offset:0
	ds_read_b64_tr_b16 v[176:177], v144 offset:4096
	v_add_f32_e32 v132, v132, v133
	v_add_f32_e32 v163, v163, v132
	v_cvt_pk_bf16_f32 v66, v66, v67
	v_mfma_f32_16x16x32_bf16 v[204:207], v[178:181], v[106:109], v[204:207]
	v_mfma_f32_16x16x32_bf16 v[220:223], v[178:181], v[122:125], v[220:223]
	ds_read_b64_tr_b16 v[178:179], v145 offset:0
	ds_read_b64_tr_b16 v[180:181], v145 offset:4096
	v_cvt_pk_bf16_f32 v67, v68, v69
	v_cvt_pk_bf16_f32 v68, v70, v71
	v_cvt_pk_bf16_f32 v69, v72, v73
	s_waitcnt lgkmcnt(10)
	v_mfma_f32_16x16x32_bf16 v[192:195], v[224:227], v[110:113], v[192:195]
	v_mfma_f32_16x16x32_bf16 v[208:211], v[224:227], v[126:129], v[208:211]
	ds_read_b64_tr_b16 v[224:225], v146 offset:0
	ds_read_b64_tr_b16 v[226:227], v146 offset:4096
	v_cvt_pk_bf16_f32 v74, v74, v75
	v_cvt_pk_bf16_f32 v75, v76, v77
	v_cvt_pk_bf16_f32 v76, v78, v79
	v_mfma_f32_16x16x32_bf16 v[196:199], v[228:231], v[110:113], v[196:199]
	v_mfma_f32_16x16x32_bf16 v[212:215], v[228:231], v[126:129], v[212:215]
	ds_read_b64_tr_b16 v[228:229], v147 offset:0
	ds_read_b64_tr_b16 v[230:231], v147 offset:4096
	v_cvt_pk_bf16_f32 v77, v80, v81
	v_cvt_pk_bf16_f32 v82, v82, v83
	v_cvt_pk_bf16_f32 v83, v84, v85
	s_waitcnt lgkmcnt(12)
	v_mfma_f32_16x16x32_bf16 v[200:203], v[232:235], v[110:113], v[200:203]
	v_mfma_f32_16x16x32_bf16 v[216:219], v[232:235], v[126:129], v[216:219]
	v_cvt_pk_bf16_f32 v84, v86, v87
	v_cvt_pk_bf16_f32 v85, v88, v89
	v_cvt_pk_bf16_f32 v90, v90, v91
	v_mfma_f32_16x16x32_bf16 v[204:207], v[236:239], v[110:113], v[204:207]
	v_mfma_f32_16x16x32_bf16 v[220:223], v[236:239], v[126:129], v[220:223]
	v_cvt_pk_bf16_f32 v91, v92, v93
	v_cvt_pk_bf16_f32 v92, v94, v95
	v_cvt_pk_bf16_f32 v93, v96, v97
	s_waitcnt lgkmcnt(8)
	v_mfma_f32_16x16x32_bf16 v[2:5], v[66:69], v[166:169], v[2:5]
	v_mfma_f32_16x16x32_bf16 v[34:37], v[82:85], v[166:169], v[34:37]
	ds_read_b64_tr_b16 v[232:233], v148 offset:0
	ds_read_b64_tr_b16 v[234:235], v148 offset:4096
	v_mfma_f32_16x16x32_bf16 v[6:9], v[66:69], v[170:173], v[6:9]
	v_mfma_f32_16x16x32_bf16 v[38:41], v[82:85], v[170:173], v[38:41]
	ds_read_b64_tr_b16 v[236:237], v149 offset:0
	ds_read_b64_tr_b16 v[238:239], v149 offset:4096
	s_waitcnt lgkmcnt(8)
	v_mfma_f32_16x16x32_bf16 v[10:13], v[66:69], v[174:177], v[10:13]
	v_mfma_f32_16x16x32_bf16 v[42:45], v[82:85], v[174:177], v[42:45]
	ds_read_b64_tr_b16 v[166:167], v142 offset:8192
	ds_read_b64_tr_b16 v[168:169], v142 offset:12288
	v_exp_f32_e32 v192, v192
	v_exp_f32_e32 v193, v193
	v_exp_f32_e32 v194, v194
	v_mfma_f32_16x16x32_bf16 v[14:17], v[66:69], v[178:181], v[14:17]
	v_mfma_f32_16x16x32_bf16 v[46:49], v[82:85], v[178:181], v[46:49]
	ds_read_b64_tr_b16 v[170:171], v143 offset:8192
	ds_read_b64_tr_b16 v[172:173], v143 offset:12288
	v_exp_f32_e32 v195, v195
	v_exp_f32_e32 v208, v208
	s_waitcnt lgkmcnt(8)
	v_mfma_f32_16x16x32_bf16 v[18:21], v[66:69], v[224:227], v[18:21]
	v_mfma_f32_16x16x32_bf16 v[50:53], v[82:85], v[224:227], v[50:53]
	ds_read_b64_tr_b16 v[174:175], v144 offset:8192
	ds_read_b64_tr_b16 v[176:177], v144 offset:12288
	v_exp_f32_e32 v209, v209
	v_exp_f32_e32 v210, v210
	v_mfma_f32_16x16x32_bf16 v[22:25], v[66:69], v[228:231], v[22:25]
	v_mfma_f32_16x16x32_bf16 v[54:57], v[82:85], v[228:231], v[54:57]
	ds_read_b64_tr_b16 v[178:179], v145 offset:8192
	ds_read_b64_tr_b16 v[180:181], v145 offset:12288
	v_exp_f32_e32 v211, v211
	v_exp_f32_e32 v196, v196
	v_exp_f32_e32 v197, v197
	s_waitcnt lgkmcnt(8)
	v_mfma_f32_16x16x32_bf16 v[26:29], v[66:69], v[232:235], v[26:29]
	v_mfma_f32_16x16x32_bf16 v[58:61], v[82:85], v[232:235], v[58:61]
	ds_read_b64_tr_b16 v[224:225], v146 offset:8192
	ds_read_b64_tr_b16 v[226:227], v146 offset:12288
	v_exp_f32_e32 v198, v198
	v_exp_f32_e32 v199, v199
	v_mfma_f32_16x16x32_bf16 v[30:33], v[66:69], v[236:239], v[30:33]
	v_mfma_f32_16x16x32_bf16 v[62:65], v[82:85], v[236:239], v[62:65]
	ds_read_b64_tr_b16 v[228:229], v147 offset:8192
	ds_read_b64_tr_b16 v[230:231], v147 offset:12288
	v_exp_f32_e32 v212, v212
	v_exp_f32_e32 v213, v213
	s_waitcnt lgkmcnt(8)
	v_mfma_f32_16x16x32_bf16 v[2:5], v[74:77], v[166:169], v[2:5]
	v_mfma_f32_16x16x32_bf16 v[34:37], v[90:93], v[166:169], v[34:37]
	ds_read_b64_tr_b16 v[232:233], v148 offset:8192
	ds_read_b64_tr_b16 v[234:235], v148 offset:12288
	ds_read_b128 v[166:169], v183 offset:16384
	v_exp_f32_e32 v214, v214
	v_exp_f32_e32 v215, v215
	v_mfma_f32_16x16x32_bf16 v[6:9], v[74:77], v[170:173], v[6:9]
	v_mfma_f32_16x16x32_bf16 v[38:41], v[90:93], v[170:173], v[38:41]
	ds_read_b64_tr_b16 v[236:237], v149 offset:8192
	ds_read_b64_tr_b16 v[238:239], v149 offset:12288
	ds_read_b128 v[170:173], v183 offset:20480
	v_exp_f32_e32 v200, v200
	v_exp_f32_e32 v201, v201
	v_exp_f32_e32 v202, v202
	s_waitcnt lgkmcnt(10)
	v_mfma_f32_16x16x32_bf16 v[10:13], v[74:77], v[174:177], v[10:13]
	v_mfma_f32_16x16x32_bf16 v[42:45], v[90:93], v[174:177], v[42:45]
	ds_read_b128 v[174:177], v183 offset:24576
	v_exp_f32_e32 v203, v203
	v_exp_f32_e32 v216, v216
	v_mfma_f32_16x16x32_bf16 v[14:17], v[74:77], v[178:181], v[14:17]
	v_mfma_f32_16x16x32_bf16 v[46:49], v[90:93], v[178:181], v[46:49]
	ds_read_b128 v[178:181], v183 offset:28672
	v_exp_f32_e32 v217, v217
	v_exp_f32_e32 v218, v218
	s_waitcnt lgkmcnt(8)
	v_mfma_f32_16x16x32_bf16 v[18:21], v[74:77], v[224:227], v[18:21]
	v_mfma_f32_16x16x32_bf16 v[50:53], v[90:93], v[224:227], v[50:53]
	ds_read_b128 v[224:227], v184 offset:16384
	v_exp_f32_e32 v219, v219
	v_exp_f32_e32 v204, v204
	v_exp_f32_e32 v205, v205
	v_mfma_f32_16x16x32_bf16 v[22:25], v[74:77], v[228:231], v[22:25]
	v_mfma_f32_16x16x32_bf16 v[54:57], v[90:93], v[228:231], v[54:57]
	ds_read_b128 v[228:231], v184 offset:20480
	v_exp_f32_e32 v206, v206
	v_exp_f32_e32 v207, v207
	s_waitcnt lgkmcnt(5)
	v_mfma_f32_16x16x32_bf16 v[26:29], v[74:77], v[232:235], v[26:29]
	v_mfma_f32_16x16x32_bf16 v[58:61], v[90:93], v[232:235], v[58:61]
	ds_read_b128 v[232:235], v184 offset:24576
	v_exp_f32_e32 v220, v220
	v_exp_f32_e32 v221, v221
	v_mfma_f32_16x16x32_bf16 v[30:33], v[74:77], v[236:239], v[30:33]
	v_mfma_f32_16x16x32_bf16 v[62:65], v[90:93], v[236:239], v[62:65]
	ds_read_b128 v[236:239], v184 offset:28672
	v_exp_f32_e32 v222, v222
	v_exp_f32_e32 v223, v223
	s_waitcnt vmcnt(0)
	s_barrier
	s_waitcnt lgkmcnt(6)
	v_mfma_f32_16x16x32_bf16 v[66:69], v[166:169], v[98:101], 0
	v_mfma_f32_16x16x32_bf16 v[82:85], v[166:169], v[114:117], 0
	ds_read_b128 v[166:169], v185 offset:16384
	s_add_i32 m0, s45, 0x10000
	v_add_f32_e32 v130, v192, v193
	v_add_f32_e32 v131, v194, v195
	v_add_f32_e32 v130, v196, v130
	global_load_lds_dwordx4 v152, s[64:65]
	v_mfma_f32_16x16x32_bf16 v[70:73], v[170:173], v[98:101], 0
	v_mfma_f32_16x16x32_bf16 v[86:89], v[170:173], v[114:117], 0
	ds_read_b128 v[170:173], v185 offset:20480
	s_add_i32 m0, s45, 0x14000
	v_add_f32_e32 v131, v197, v131
	v_add_f32_e32 v130, v198, v130
	v_add_f32_e32 v131, v199, v131
	global_load_lds_dwordx4 v150, s[62:63]
	s_waitcnt lgkmcnt(6)
	v_mfma_f32_16x16x32_bf16 v[74:77], v[174:177], v[98:101], 0
	v_mfma_f32_16x16x32_bf16 v[90:93], v[174:177], v[114:117], 0
	ds_read_b128 v[174:177], v185 offset:24576
	s_add_i32 m0, s45, 0x12000
	v_add_f32_e32 v130, v200, v130
	v_add_f32_e32 v131, v201, v131
	v_add_f32_e32 v130, v202, v130
	global_load_lds_dwordx4 v153, s[64:65]
	v_mfma_f32_16x16x32_bf16 v[78:81], v[178:181], v[98:101], 0
	v_mfma_f32_16x16x32_bf16 v[94:97], v[178:181], v[114:117], 0
	ds_read_b128 v[178:181], v185 offset:28672
	s_add_i32 m0, s45, 0x16000
	v_add_f32_e32 v131, v203, v131
	v_add_f32_e32 v130, v204, v130
	v_add_f32_e32 v131, v205, v131
	global_load_lds_dwordx4 v151, s[62:63]
	s_add_u32 s62, s62, 0x4000
	s_addc_u32 s63, s63, 0
	s_add_u32 s64, s64, 0x4000
	s_addc_u32 s65, s65, 0
	s_waitcnt lgkmcnt(6)
	v_mfma_f32_16x16x32_bf16 v[66:69], v[224:227], v[102:105], v[66:69]
	v_mfma_f32_16x16x32_bf16 v[82:85], v[224:227], v[118:121], v[82:85]
	ds_read_b128 v[224:227], v186 offset:16384
	v_add_f32_e32 v130, v206, v130
	v_add_f32_e32 v131, v207, v131
	v_add_f32_e32 v130, v130, v131
	v_mfma_f32_16x16x32_bf16 v[70:73], v[228:231], v[102:105], v[70:73]
	v_mfma_f32_16x16x32_bf16 v[86:89], v[228:231], v[118:121], v[86:89]
	ds_read_b128 v[228:231], v186 offset:20480
	v_add_f32_e32 v165, v165, v130
	v_add_f32_e32 v132, v208, v209
	v_add_f32_e32 v133, v210, v211
	s_waitcnt lgkmcnt(6)
	v_mfma_f32_16x16x32_bf16 v[74:77], v[232:235], v[102:105], v[74:77]
	v_mfma_f32_16x16x32_bf16 v[90:93], v[232:235], v[118:121], v[90:93]
	ds_read_b128 v[232:235], v186 offset:24576
	v_add_f32_e32 v132, v212, v132
	v_add_f32_e32 v133, v213, v133
	v_add_f32_e32 v132, v214, v132
	v_mfma_f32_16x16x32_bf16 v[78:81], v[236:239], v[102:105], v[78:81]
	v_mfma_f32_16x16x32_bf16 v[94:97], v[236:239], v[118:121], v[94:97]
	ds_read_b128 v[236:239], v186 offset:28672
	v_add_f32_e32 v133, v215, v133
	v_add_f32_e32 v132, v216, v132
	v_add_f32_e32 v133, v217, v133
	s_waitcnt lgkmcnt(6)
	v_mfma_f32_16x16x32_bf16 v[66:69], v[166:169], v[106:109], v[66:69]
	v_mfma_f32_16x16x32_bf16 v[82:85], v[166:169], v[122:125], v[82:85]
	ds_read_b64_tr_b16 v[166:167], v142 offset:32768
	ds_read_b64_tr_b16 v[168:169], v142 offset:36864
	v_add_f32_e32 v132, v218, v132
	v_add_f32_e32 v133, v219, v133
	v_add_f32_e32 v132, v220, v132
	v_mfma_f32_16x16x32_bf16 v[70:73], v[170:173], v[106:109], v[70:73]
	v_mfma_f32_16x16x32_bf16 v[86:89], v[170:173], v[122:125], v[86:89]
	ds_read_b64_tr_b16 v[170:171], v143 offset:32768
	ds_read_b64_tr_b16 v[172:173], v143 offset:36864
	v_add_f32_e32 v133, v221, v133
	v_add_f32_e32 v132, v222, v132
	v_add_f32_e32 v133, v223, v133
	s_waitcnt lgkmcnt(8)
	v_mfma_f32_16x16x32_bf16 v[74:77], v[174:177], v[106:109], v[74:77]
	v_mfma_f32_16x16x32_bf16 v[90:93], v[174:177], v[122:125], v[90:93]
	ds_read_b64_tr_b16 v[174:175], v144 offset:32768
	ds_read_b64_tr_b16 v[176:177], v144 offset:36864
	v_add_f32_e32 v132, v132, v133
	v_add_f32_e32 v163, v163, v132
	v_cvt_pk_bf16_f32 v192, v192, v193
	v_mfma_f32_16x16x32_bf16 v[78:81], v[178:181], v[106:109], v[78:81]
	v_mfma_f32_16x16x32_bf16 v[94:97], v[178:181], v[122:125], v[94:97]
	ds_read_b64_tr_b16 v[178:179], v145 offset:32768
	ds_read_b64_tr_b16 v[180:181], v145 offset:36864
	v_cvt_pk_bf16_f32 v193, v194, v195
	v_cvt_pk_bf16_f32 v194, v196, v197
	v_cvt_pk_bf16_f32 v195, v198, v199
	s_waitcnt lgkmcnt(10)
	v_mfma_f32_16x16x32_bf16 v[66:69], v[224:227], v[110:113], v[66:69]
	v_mfma_f32_16x16x32_bf16 v[82:85], v[224:227], v[126:129], v[82:85]
	ds_read_b64_tr_b16 v[224:225], v146 offset:32768
	ds_read_b64_tr_b16 v[226:227], v146 offset:36864
	v_cvt_pk_bf16_f32 v200, v200, v201
	v_cvt_pk_bf16_f32 v201, v202, v203
	v_cvt_pk_bf16_f32 v202, v204, v205
	v_mfma_f32_16x16x32_bf16 v[70:73], v[228:231], v[110:113], v[70:73]
	v_mfma_f32_16x16x32_bf16 v[86:89], v[228:231], v[126:129], v[86:89]
	ds_read_b64_tr_b16 v[228:229], v147 offset:32768
	ds_read_b64_tr_b16 v[230:231], v147 offset:36864
	v_cvt_pk_bf16_f32 v203, v206, v207
	v_cvt_pk_bf16_f32 v208, v208, v209
	v_cvt_pk_bf16_f32 v209, v210, v211
	s_waitcnt lgkmcnt(12)
	v_mfma_f32_16x16x32_bf16 v[74:77], v[232:235], v[110:113], v[74:77]
	v_mfma_f32_16x16x32_bf16 v[90:93], v[232:235], v[126:129], v[90:93]
	v_cvt_pk_bf16_f32 v210, v212, v213
	v_cvt_pk_bf16_f32 v211, v214, v215
	v_cvt_pk_bf16_f32 v216, v216, v217
	v_mfma_f32_16x16x32_bf16 v[78:81], v[236:239], v[110:113], v[78:81]
	v_mfma_f32_16x16x32_bf16 v[94:97], v[236:239], v[126:129], v[94:97]
	v_cvt_pk_bf16_f32 v217, v218, v219
	v_cvt_pk_bf16_f32 v218, v220, v221
	v_cvt_pk_bf16_f32 v219, v222, v223
	s_waitcnt lgkmcnt(8)
	v_mfma_f32_16x16x32_bf16 v[2:5], v[192:195], v[166:169], v[2:5]
	v_mfma_f32_16x16x32_bf16 v[34:37], v[208:211], v[166:169], v[34:37]
	ds_read_b64_tr_b16 v[232:233], v148 offset:32768
	ds_read_b64_tr_b16 v[234:235], v148 offset:36864
	v_mfma_f32_16x16x32_bf16 v[6:9], v[192:195], v[170:173], v[6:9]
	v_mfma_f32_16x16x32_bf16 v[38:41], v[208:211], v[170:173], v[38:41]
	ds_read_b64_tr_b16 v[236:237], v149 offset:32768
	ds_read_b64_tr_b16 v[238:239], v149 offset:36864
	s_waitcnt lgkmcnt(8)
	v_mfma_f32_16x16x32_bf16 v[10:13], v[192:195], v[174:177], v[10:13]
	v_mfma_f32_16x16x32_bf16 v[42:45], v[208:211], v[174:177], v[42:45]
	ds_read_b64_tr_b16 v[166:167], v142 offset:40960
	ds_read_b64_tr_b16 v[168:169], v142 offset:45056
	v_exp_f32_e32 v66, v66
	v_exp_f32_e32 v67, v67
	v_exp_f32_e32 v68, v68
	v_mfma_f32_16x16x32_bf16 v[14:17], v[192:195], v[178:181], v[14:17]
	v_mfma_f32_16x16x32_bf16 v[46:49], v[208:211], v[178:181], v[46:49]
	ds_read_b64_tr_b16 v[170:171], v143 offset:40960
	ds_read_b64_tr_b16 v[172:173], v143 offset:45056
	v_exp_f32_e32 v69, v69
	v_exp_f32_e32 v82, v82
	s_waitcnt lgkmcnt(8)
	v_mfma_f32_16x16x32_bf16 v[18:21], v[192:195], v[224:227], v[18:21]
	v_mfma_f32_16x16x32_bf16 v[50:53], v[208:211], v[224:227], v[50:53]
	ds_read_b64_tr_b16 v[174:175], v144 offset:40960
	ds_read_b64_tr_b16 v[176:177], v144 offset:45056
	v_exp_f32_e32 v83, v83
	v_exp_f32_e32 v84, v84
	v_mfma_f32_16x16x32_bf16 v[22:25], v[192:195], v[228:231], v[22:25]
	v_mfma_f32_16x16x32_bf16 v[54:57], v[208:211], v[228:231], v[54:57]
	ds_read_b64_tr_b16 v[178:179], v145 offset:40960
	ds_read_b64_tr_b16 v[180:181], v145 offset:45056
	v_exp_f32_e32 v85, v85
	v_exp_f32_e32 v70, v70
	v_exp_f32_e32 v71, v71
	s_waitcnt lgkmcnt(8)
	v_mfma_f32_16x16x32_bf16 v[26:29], v[192:195], v[232:235], v[26:29]
	v_mfma_f32_16x16x32_bf16 v[58:61], v[208:211], v[232:235], v[58:61]
	ds_read_b64_tr_b16 v[224:225], v146 offset:40960
	ds_read_b64_tr_b16 v[226:227], v146 offset:45056
	v_exp_f32_e32 v72, v72
	v_exp_f32_e32 v73, v73
	v_mfma_f32_16x16x32_bf16 v[30:33], v[192:195], v[236:239], v[30:33]
	v_mfma_f32_16x16x32_bf16 v[62:65], v[208:211], v[236:239], v[62:65]
	ds_read_b64_tr_b16 v[228:229], v147 offset:40960
	ds_read_b64_tr_b16 v[230:231], v147 offset:45056
	v_exp_f32_e32 v86, v86
	v_exp_f32_e32 v87, v87
	s_waitcnt lgkmcnt(8)
	v_mfma_f32_16x16x32_bf16 v[2:5], v[200:203], v[166:169], v[2:5]
	v_mfma_f32_16x16x32_bf16 v[34:37], v[216:219], v[166:169], v[34:37]
	ds_read_b64_tr_b16 v[232:233], v148 offset:40960
	ds_read_b64_tr_b16 v[234:235], v148 offset:45056
	ds_read_b128 v[166:169], v183 offset:49152
	v_exp_f32_e32 v88, v88
	v_exp_f32_e32 v89, v89
	v_mfma_f32_16x16x32_bf16 v[6:9], v[200:203], v[170:173], v[6:9]
	v_mfma_f32_16x16x32_bf16 v[38:41], v[216:219], v[170:173], v[38:41]
	ds_read_b64_tr_b16 v[236:237], v149 offset:40960
	ds_read_b64_tr_b16 v[238:239], v149 offset:45056
	ds_read_b128 v[170:173], v183 offset:53248
	v_exp_f32_e32 v74, v74
	v_exp_f32_e32 v75, v75
	v_exp_f32_e32 v76, v76
	s_waitcnt lgkmcnt(10)
	v_mfma_f32_16x16x32_bf16 v[10:13], v[200:203], v[174:177], v[10:13]
	v_mfma_f32_16x16x32_bf16 v[42:45], v[216:219], v[174:177], v[42:45]
	ds_read_b128 v[174:177], v183 offset:57344
	v_exp_f32_e32 v77, v77
	v_exp_f32_e32 v90, v90
	v_mfma_f32_16x16x32_bf16 v[14:17], v[200:203], v[178:181], v[14:17]
	v_mfma_f32_16x16x32_bf16 v[46:49], v[216:219], v[178:181], v[46:49]
	ds_read_b128 v[178:181], v183 offset:61440
	v_exp_f32_e32 v91, v91
	v_exp_f32_e32 v92, v92
	s_waitcnt lgkmcnt(8)
	v_mfma_f32_16x16x32_bf16 v[18:21], v[200:203], v[224:227], v[18:21]
	v_mfma_f32_16x16x32_bf16 v[50:53], v[216:219], v[224:227], v[50:53]
	ds_read_b128 v[224:227], v184 offset:49152
	v_exp_f32_e32 v93, v93
	v_exp_f32_e32 v78, v78
	v_exp_f32_e32 v79, v79
	v_mfma_f32_16x16x32_bf16 v[22:25], v[200:203], v[228:231], v[22:25]
	v_mfma_f32_16x16x32_bf16 v[54:57], v[216:219], v[228:231], v[54:57]
	ds_read_b128 v[228:231], v184 offset:53248
	v_exp_f32_e32 v80, v80
	v_exp_f32_e32 v81, v81
	s_waitcnt lgkmcnt(5)
	v_mfma_f32_16x16x32_bf16 v[26:29], v[200:203], v[232:235], v[26:29]
	v_mfma_f32_16x16x32_bf16 v[58:61], v[216:219], v[232:235], v[58:61]
	ds_read_b128 v[232:235], v184 offset:57344
	v_exp_f32_e32 v94, v94
	v_exp_f32_e32 v95, v95
	v_mfma_f32_16x16x32_bf16 v[30:33], v[200:203], v[236:239], v[30:33]
	v_mfma_f32_16x16x32_bf16 v[62:65], v[216:219], v[236:239], v[62:65]
	ds_read_b128 v[236:239], v184 offset:61440
	v_exp_f32_e32 v96, v96
	v_exp_f32_e32 v97, v97
	s_waitcnt vmcnt(0)
	s_barrier
	s_sub_u32 s66, s66, 1
	s_cmp_lg_u32 s66, 0
	s_cbranch_scc1 .Lattn_loop
	s_waitcnt lgkmcnt(6)
	v_mfma_f32_16x16x32_bf16 v[192:195], v[166:169], v[98:101], 0
	v_mfma_f32_16x16x32_bf16 v[208:211], v[166:169], v[114:117], 0
	ds_read_b128 v[166:169], v185 offset:49152
	s_add_i32 m0, s45, 0x18000
	v_add_f32_e32 v130, v66, v67
	v_add_f32_e32 v131, v68, v69
	v_add_f32_e32 v130, v70, v130
	global_load_lds_dwordx4 v152, s[64:65]
	v_mfma_f32_16x16x32_bf16 v[196:199], v[170:173], v[98:101], 0
	v_mfma_f32_16x16x32_bf16 v[212:215], v[170:173], v[114:117], 0
	ds_read_b128 v[170:173], v185 offset:53248
	s_add_i32 m0, s45, 0x1c000
	v_add_f32_e32 v131, v71, v131
	v_add_f32_e32 v130, v72, v130
	v_add_f32_e32 v131, v73, v131
	global_load_lds_dwordx4 v150, s[62:63]
	s_waitcnt lgkmcnt(6)
	v_mfma_f32_16x16x32_bf16 v[200:203], v[174:177], v[98:101], 0
	v_mfma_f32_16x16x32_bf16 v[216:219], v[174:177], v[114:117], 0
	ds_read_b128 v[174:177], v185 offset:57344
	s_add_i32 m0, s45, 0x1a000
	v_add_f32_e32 v130, v74, v130
	v_add_f32_e32 v131, v75, v131
	v_add_f32_e32 v130, v76, v130
	global_load_lds_dwordx4 v153, s[64:65]
	v_mfma_f32_16x16x32_bf16 v[204:207], v[178:181], v[98:101], 0
	v_mfma_f32_16x16x32_bf16 v[220:223], v[178:181], v[114:117], 0
	ds_read_b128 v[178:181], v185 offset:61440
	s_add_i32 m0, s45, 0x1e000
	v_add_f32_e32 v131, v77, v131
	v_add_f32_e32 v130, v78, v130
	v_add_f32_e32 v131, v79, v131
	global_load_lds_dwordx4 v151, s[62:63]
	s_add_u32 s62, s62, 0x4000
	s_addc_u32 s63, s63, 0
	s_add_u32 s64, s64, 0x4000
	s_addc_u32 s65, s65, 0
	s_waitcnt lgkmcnt(6)
	v_mfma_f32_16x16x32_bf16 v[192:195], v[224:227], v[102:105], v[192:195]
	v_mfma_f32_16x16x32_bf16 v[208:211], v[224:227], v[118:121], v[208:211]
	ds_read_b128 v[224:227], v186 offset:49152
	v_add_f32_e32 v130, v80, v130
	v_add_f32_e32 v131, v81, v131
	v_add_f32_e32 v130, v130, v131
	v_mfma_f32_16x16x32_bf16 v[196:199], v[228:231], v[102:105], v[196:199]
	v_mfma_f32_16x16x32_bf16 v[212:215], v[228:231], v[118:121], v[212:215]
	ds_read_b128 v[228:231], v186 offset:53248
	v_add_f32_e32 v165, v165, v130
	v_add_f32_e32 v132, v82, v83
	v_add_f32_e32 v133, v84, v85
	s_waitcnt lgkmcnt(6)
	v_mfma_f32_16x16x32_bf16 v[200:203], v[232:235], v[102:105], v[200:203]
	v_mfma_f32_16x16x32_bf16 v[216:219], v[232:235], v[118:121], v[216:219]
	ds_read_b128 v[232:235], v186 offset:57344
	v_add_f32_e32 v132, v86, v132
	v_add_f32_e32 v133, v87, v133
	v_add_f32_e32 v132, v88, v132
	v_mfma_f32_16x16x32_bf16 v[204:207], v[236:239], v[102:105], v[204:207]
	v_mfma_f32_16x16x32_bf16 v[220:223], v[236:239], v[118:121], v[220:223]
	ds_read_b128 v[236:239], v186 offset:61440
	v_add_f32_e32 v133, v89, v133
	v_add_f32_e32 v132, v90, v132
	v_add_f32_e32 v133, v91, v133
	s_waitcnt lgkmcnt(6)
	v_mfma_f32_16x16x32_bf16 v[192:195], v[166:169], v[106:109], v[192:195]
	v_mfma_f32_16x16x32_bf16 v[208:211], v[166:169], v[122:125], v[208:211]
	ds_read_b64_tr_b16 v[166:167], v240 offset:0
	ds_read_b64_tr_b16 v[168:169], v240 offset:4096
	v_add_f32_e32 v132, v92, v132
	v_add_f32_e32 v133, v93, v133
	v_add_f32_e32 v132, v94, v132
	v_mfma_f32_16x16x32_bf16 v[196:199], v[170:173], v[106:109], v[196:199]
	v_mfma_f32_16x16x32_bf16 v[212:215], v[170:173], v[122:125], v[212:215]
	ds_read_b64_tr_b16 v[170:171], v241 offset:0
	ds_read_b64_tr_b16 v[172:173], v241 offset:4096
	v_add_f32_e32 v133, v95, v133
	v_add_f32_e32 v132, v96, v132
	v_add_f32_e32 v133, v97, v133
	s_waitcnt lgkmcnt(8)
	v_mfma_f32_16x16x32_bf16 v[200:203], v[174:177], v[106:109], v[200:203]
	v_mfma_f32_16x16x32_bf16 v[216:219], v[174:177], v[122:125], v[216:219]
	ds_read_b64_tr_b16 v[174:175], v242 offset:0
	ds_read_b64_tr_b16 v[176:177], v242 offset:4096
	v_add_f32_e32 v132, v132, v133
	v_add_f32_e32 v163, v163, v132
	v_cvt_pk_bf16_f32 v66, v66, v67
	v_mfma_f32_16x16x32_bf16 v[204:207], v[178:181], v[106:109], v[204:207]
	v_mfma_f32_16x16x32_bf16 v[220:223], v[178:181], v[122:125], v[220:223]
	ds_read_b64_tr_b16 v[178:179], v243 offset:0
	ds_read_b64_tr_b16 v[180:181], v243 offset:4096
	v_cvt_pk_bf16_f32 v67, v68, v69
	v_cvt_pk_bf16_f32 v68, v70, v71
	v_cvt_pk_bf16_f32 v69, v72, v73
	s_waitcnt lgkmcnt(10)
	v_mfma_f32_16x16x32_bf16 v[192:195], v[224:227], v[110:113], v[192:195]
	v_mfma_f32_16x16x32_bf16 v[208:211], v[224:227], v[126:129], v[208:211]
	ds_read_b64_tr_b16 v[224:225], v244 offset:0
	ds_read_b64_tr_b16 v[226:227], v244 offset:4096
	v_cvt_pk_bf16_f32 v74, v74, v75
	v_cvt_pk_bf16_f32 v75, v76, v77
	v_cvt_pk_bf16_f32 v76, v78, v79
	v_mfma_f32_16x16x32_bf16 v[196:199], v[228:231], v[110:113], v[196:199]
	v_mfma_f32_16x16x32_bf16 v[212:215], v[228:231], v[126:129], v[212:215]
	ds_read_b64_tr_b16 v[228:229], v245 offset:0
	ds_read_b64_tr_b16 v[230:231], v245 offset:4096
	v_cvt_pk_bf16_f32 v77, v80, v81
	v_cvt_pk_bf16_f32 v82, v82, v83
	v_cvt_pk_bf16_f32 v83, v84, v85
	s_waitcnt lgkmcnt(12)
	v_mfma_f32_16x16x32_bf16 v[200:203], v[232:235], v[110:113], v[200:203]
	v_mfma_f32_16x16x32_bf16 v[216:219], v[232:235], v[126:129], v[216:219]
	v_cvt_pk_bf16_f32 v84, v86, v87
	v_cvt_pk_bf16_f32 v85, v88, v89
	v_cvt_pk_bf16_f32 v90, v90, v91
	v_mfma_f32_16x16x32_bf16 v[204:207], v[236:239], v[110:113], v[204:207]
	v_mfma_f32_16x16x32_bf16 v[220:223], v[236:239], v[126:129], v[220:223]
	v_cvt_pk_bf16_f32 v91, v92, v93
	v_cvt_pk_bf16_f32 v92, v94, v95
	v_cvt_pk_bf16_f32 v93, v96, v97
	s_waitcnt lgkmcnt(8)
	v_mfma_f32_16x16x32_bf16 v[2:5], v[66:69], v[166:169], v[2:5]
	v_mfma_f32_16x16x32_bf16 v[34:37], v[82:85], v[166:169], v[34:37]
	ds_read_b64_tr_b16 v[232:233], v246 offset:0
	ds_read_b64_tr_b16 v[234:235], v246 offset:4096
	v_mfma_f32_16x16x32_bf16 v[6:9], v[66:69], v[170:173], v[6:9]
	v_mfma_f32_16x16x32_bf16 v[38:41], v[82:85], v[170:173], v[38:41]
	ds_read_b64_tr_b16 v[236:237], v247 offset:0
	ds_read_b64_tr_b16 v[238:239], v247 offset:4096
	s_waitcnt lgkmcnt(8)
	v_mfma_f32_16x16x32_bf16 v[10:13], v[66:69], v[174:177], v[10:13]
	v_mfma_f32_16x16x32_bf16 v[42:45], v[82:85], v[174:177], v[42:45]
	ds_read_b64_tr_b16 v[166:167], v240 offset:8192
	ds_read_b64_tr_b16 v[168:169], v240 offset:12288
	v_exp_f32_e32 v192, v192
	v_exp_f32_e32 v193, v193
	v_exp_f32_e32 v194, v194
	v_mfma_f32_16x16x32_bf16 v[14:17], v[66:69], v[178:181], v[14:17]
	v_mfma_f32_16x16x32_bf16 v[46:49], v[82:85], v[178:181], v[46:49]
	ds_read_b64_tr_b16 v[170:171], v241 offset:8192
	ds_read_b64_tr_b16 v[172:173], v241 offset:12288
	v_exp_f32_e32 v195, v195
	v_exp_f32_e32 v208, v208
	s_waitcnt lgkmcnt(8)
	v_mfma_f32_16x16x32_bf16 v[18:21], v[66:69], v[224:227], v[18:21]
	v_mfma_f32_16x16x32_bf16 v[50:53], v[82:85], v[224:227], v[50:53]
	ds_read_b64_tr_b16 v[174:175], v242 offset:8192
	ds_read_b64_tr_b16 v[176:177], v242 offset:12288
	v_exp_f32_e32 v209, v209
	v_exp_f32_e32 v210, v210
	v_mfma_f32_16x16x32_bf16 v[22:25], v[66:69], v[228:231], v[22:25]
	v_mfma_f32_16x16x32_bf16 v[54:57], v[82:85], v[228:231], v[54:57]
	ds_read_b64_tr_b16 v[178:179], v243 offset:8192
	ds_read_b64_tr_b16 v[180:181], v243 offset:12288
	v_exp_f32_e32 v211, v211
	v_exp_f32_e32 v196, v196
	v_exp_f32_e32 v197, v197
	s_waitcnt lgkmcnt(8)
	v_mfma_f32_16x16x32_bf16 v[26:29], v[66:69], v[232:235], v[26:29]
	v_mfma_f32_16x16x32_bf16 v[58:61], v[82:85], v[232:235], v[58:61]
	ds_read_b64_tr_b16 v[224:225], v244 offset:8192
	ds_read_b64_tr_b16 v[226:227], v244 offset:12288
	v_exp_f32_e32 v198, v198
	v_exp_f32_e32 v199, v199
	v_mfma_f32_16x16x32_bf16 v[30:33], v[66:69], v[236:239], v[30:33]
	v_mfma_f32_16x16x32_bf16 v[62:65], v[82:85], v[236:239], v[62:65]
	ds_read_b64_tr_b16 v[228:229], v245 offset:8192
	ds_read_b64_tr_b16 v[230:231], v245 offset:12288
	v_exp_f32_e32 v212, v212
	v_exp_f32_e32 v213, v213
	s_waitcnt lgkmcnt(8)
	v_mfma_f32_16x16x32_bf16 v[2:5], v[74:77], v[166:169], v[2:5]
	v_mfma_f32_16x16x32_bf16 v[34:37], v[90:93], v[166:169], v[34:37]
	ds_read_b64_tr_b16 v[232:233], v246 offset:8192
	ds_read_b64_tr_b16 v[234:235], v246 offset:12288
	ds_read_b128 v[166:169], v187 offset:16384
	v_exp_f32_e32 v214, v214
	v_exp_f32_e32 v215, v215
	v_mfma_f32_16x16x32_bf16 v[6:9], v[74:77], v[170:173], v[6:9]
	v_mfma_f32_16x16x32_bf16 v[38:41], v[90:93], v[170:173], v[38:41]
	ds_read_b64_tr_b16 v[236:237], v247 offset:8192
	ds_read_b64_tr_b16 v[238:239], v247 offset:12288
	ds_read_b128 v[170:173], v187 offset:20480
	v_exp_f32_e32 v200, v200
	v_exp_f32_e32 v201, v201
	v_exp_f32_e32 v202, v202
	s_waitcnt lgkmcnt(10)
	v_mfma_f32_16x16x32_bf16 v[10:13], v[74:77], v[174:177], v[10:13]
	v_mfma_f32_16x16x32_bf16 v[42:45], v[90:93], v[174:177], v[42:45]
	ds_read_b128 v[174:177], v187 offset:24576
	v_exp_f32_e32 v203, v203
	v_exp_f32_e32 v216, v216
	v_mfma_f32_16x16x32_bf16 v[14:17], v[74:77], v[178:181], v[14:17]
	v_mfma_f32_16x16x32_bf16 v[46:49], v[90:93], v[178:181], v[46:49]
	ds_read_b128 v[178:181], v187 offset:28672
	v_exp_f32_e32 v217, v217
	v_exp_f32_e32 v218, v218
	s_waitcnt lgkmcnt(8)
	v_mfma_f32_16x16x32_bf16 v[18:21], v[74:77], v[224:227], v[18:21]
	v_mfma_f32_16x16x32_bf16 v[50:53], v[90:93], v[224:227], v[50:53]
	ds_read_b128 v[224:227], v188 offset:16384
	v_exp_f32_e32 v219, v219
	v_exp_f32_e32 v204, v204
	v_exp_f32_e32 v205, v205
	v_mfma_f32_16x16x32_bf16 v[22:25], v[74:77], v[228:231], v[22:25]
	v_mfma_f32_16x16x32_bf16 v[54:57], v[90:93], v[228:231], v[54:57]
	ds_read_b128 v[228:231], v188 offset:20480
	v_exp_f32_e32 v206, v206
	v_exp_f32_e32 v207, v207
	s_waitcnt lgkmcnt(5)
	v_mfma_f32_16x16x32_bf16 v[26:29], v[74:77], v[232:235], v[26:29]
	v_mfma_f32_16x16x32_bf16 v[58:61], v[90:93], v[232:235], v[58:61]
	ds_read_b128 v[232:235], v188 offset:24576
	v_exp_f32_e32 v220, v220
	v_exp_f32_e32 v221, v221
	v_mfma_f32_16x16x32_bf16 v[30:33], v[74:77], v[236:239], v[30:33]
	v_mfma_f32_16x16x32_bf16 v[62:65], v[90:93], v[236:239], v[62:65]
	ds_read_b128 v[236:239], v188 offset:28672
	v_exp_f32_e32 v222, v222
	v_exp_f32_e32 v223, v223
	s_waitcnt vmcnt(0)
	s_barrier
	s_add_i32 s66, s3, s33
	s_cmpk_lt_i32 s66, 0x400
	s_cselect_b32 s66, s66, s3
	s_lshr_b32 s0, s66, 7
	s_lshl_b32 s0, s0, 23
	s_and_b32 s1, s66, 15
	s_lshl_b32 s1, s1, 19
	s_or_b32 s0, s0, s1
	s_bfe_u32 s1, s66, 0x30004
	s_lshl_b32 s1, s1, 8
	s_or_b32 s0, s0, s1
	s_add_u32 s60, s25, s0
	s_addc_u32 s61, s28, 0
	s_add_u32 s18, s21, s0
	s_addc_u32 s19, s24, 0
	s_lshr_b32 s1, s66, 6
	s_mul_i32 s1, s1, 0x110000
	s_add_u32 s62, s9, s1
	s_addc_u32 s63, s20, 0
	s_add_u32 s64, s29, s1
	s_addc_u32 s65, s30, 0
	s_waitcnt lgkmcnt(6)
	v_mfma_f32_16x16x32_bf16 v[66:69], v[166:169], v[98:101], 0
	v_mfma_f32_16x16x32_bf16 v[82:85], v[166:169], v[114:117], 0
	ds_read_b128 v[166:169], v189 offset:16384
	v_add_f32_e32 v130, v192, v193
	v_add_f32_e32 v131, v194, v195
	v_add_f32_e32 v130, v196, v130
	v_mfma_f32_16x16x32_bf16 v[70:73], v[170:173], v[98:101], 0
	v_mfma_f32_16x16x32_bf16 v[86:89], v[170:173], v[114:117], 0
	ds_read_b128 v[170:173], v189 offset:20480
	v_add_f32_e32 v131, v197, v131
	v_add_f32_e32 v130, v198, v130
	v_add_f32_e32 v131, v199, v131
	s_waitcnt lgkmcnt(6)
	v_mfma_f32_16x16x32_bf16 v[74:77], v[174:177], v[98:101], 0
	v_mfma_f32_16x16x32_bf16 v[90:93], v[174:177], v[114:117], 0
	ds_read_b128 v[174:177], v189 offset:24576
	v_add_f32_e32 v130, v200, v130
	v_add_f32_e32 v131, v201, v131
	v_add_f32_e32 v130, v202, v130
	v_mfma_f32_16x16x32_bf16 v[78:81], v[178:181], v[98:101], 0
	v_mfma_f32_16x16x32_bf16 v[94:97], v[178:181], v[114:117], 0
	ds_read_b128 v[178:181], v189 offset:28672
	v_add_f32_e32 v131, v203, v131
	v_add_f32_e32 v130, v204, v130
	v_add_f32_e32 v131, v205, v131
	s_waitcnt lgkmcnt(6)
	v_mfma_f32_16x16x32_bf16 v[66:69], v[224:227], v[102:105], v[66:69]
	v_mfma_f32_16x16x32_bf16 v[82:85], v[224:227], v[118:121], v[82:85]
	ds_read_b128 v[224:227], v190 offset:16384
	v_add_f32_e32 v130, v206, v130
	v_add_f32_e32 v131, v207, v131
	v_add_f32_e32 v130, v130, v131
	v_mfma_f32_16x16x32_bf16 v[70:73], v[228:231], v[102:105], v[70:73]
	v_mfma_f32_16x16x32_bf16 v[86:89], v[228:231], v[118:121], v[86:89]
	ds_read_b128 v[228:231], v190 offset:20480
	v_add_f32_e32 v165, v165, v130
	v_add_f32_e32 v132, v208, v209
	v_add_f32_e32 v133, v210, v211
	s_waitcnt lgkmcnt(6)
	v_mfma_f32_16x16x32_bf16 v[74:77], v[232:235], v[102:105], v[74:77]
	v_mfma_f32_16x16x32_bf16 v[90:93], v[232:235], v[118:121], v[90:93]
	ds_read_b128 v[232:235], v190 offset:24576
	v_add_f32_e32 v132, v212, v132
	v_add_f32_e32 v133, v213, v133
	v_add_f32_e32 v132, v214, v132
	v_mfma_f32_16x16x32_bf16 v[78:81], v[236:239], v[102:105], v[78:81]
	v_mfma_f32_16x16x32_bf16 v[94:97], v[236:239], v[118:121], v[94:97]
	ds_read_b128 v[236:239], v190 offset:28672
	v_add_f32_e32 v133, v215, v133
	v_add_f32_e32 v132, v216, v132
	v_add_f32_e32 v133, v217, v133
	s_waitcnt lgkmcnt(6)
	v_mfma_f32_16x16x32_bf16 v[66:69], v[166:169], v[106:109], v[66:69]
	v_mfma_f32_16x16x32_bf16 v[82:85], v[166:169], v[122:125], v[82:85]
	ds_read_b64_tr_b16 v[166:167], v240 offset:32768
	ds_read_b64_tr_b16 v[168:169], v240 offset:36864
	v_add_f32_e32 v132, v218, v132
	v_add_f32_e32 v133, v219, v133
	v_add_f32_e32 v132, v220, v132
	v_mfma_f32_16x16x32_bf16 v[70:73], v[170:173], v[106:109], v[70:73]
	v_mfma_f32_16x16x32_bf16 v[86:89], v[170:173], v[122:125], v[86:89]
	ds_read_b64_tr_b16 v[170:171], v241 offset:32768
	ds_read_b64_tr_b16 v[172:173], v241 offset:36864
	v_add_f32_e32 v133, v221, v133
	v_add_f32_e32 v132, v222, v132
	v_add_f32_e32 v133, v223, v133
	s_waitcnt lgkmcnt(8)
	v_mfma_f32_16x16x32_bf16 v[74:77], v[174:177], v[106:109], v[74:77]
	v_mfma_f32_16x16x32_bf16 v[90:93], v[174:177], v[122:125], v[90:93]
	ds_read_b64_tr_b16 v[174:175], v242 offset:32768
	ds_read_b64_tr_b16 v[176:177], v242 offset:36864
	v_add_f32_e32 v132, v132, v133
	v_add_f32_e32 v163, v163, v132
	v_cvt_pk_bf16_f32 v192, v192, v193
	v_mfma_f32_16x16x32_bf16 v[78:81], v[178:181], v[106:109], v[78:81]
	v_mfma_f32_16x16x32_bf16 v[94:97], v[178:181], v[122:125], v[94:97]
	ds_read_b64_tr_b16 v[178:179], v243 offset:32768
	ds_read_b64_tr_b16 v[180:181], v243 offset:36864
	v_cvt_pk_bf16_f32 v193, v194, v195
	v_cvt_pk_bf16_f32 v194, v196, v197
	v_cvt_pk_bf16_f32 v195, v198, v199
	s_waitcnt lgkmcnt(10)
	v_mfma_f32_16x16x32_bf16 v[66:69], v[224:227], v[110:113], v[66:69]
	v_mfma_f32_16x16x32_bf16 v[82:85], v[224:227], v[126:129], v[82:85]
	ds_read_b64_tr_b16 v[224:225], v244 offset:32768
	ds_read_b64_tr_b16 v[226:227], v244 offset:36864
	v_cvt_pk_bf16_f32 v200, v200, v201
	v_cvt_pk_bf16_f32 v201, v202, v203
	v_cvt_pk_bf16_f32 v202, v204, v205
	v_mfma_f32_16x16x32_bf16 v[70:73], v[228:231], v[110:113], v[70:73]
	v_mfma_f32_16x16x32_bf16 v[86:89], v[228:231], v[126:129], v[86:89]
	ds_read_b64_tr_b16 v[228:229], v245 offset:32768
	ds_read_b64_tr_b16 v[230:231], v245 offset:36864
	v_cvt_pk_bf16_f32 v203, v206, v207
	v_cvt_pk_bf16_f32 v208, v208, v209
	v_cvt_pk_bf16_f32 v209, v210, v211
	s_waitcnt lgkmcnt(12)
	v_mfma_f32_16x16x32_bf16 v[74:77], v[232:235], v[110:113], v[74:77]
	v_mfma_f32_16x16x32_bf16 v[90:93], v[232:235], v[126:129], v[90:93]
	v_cvt_pk_bf16_f32 v210, v212, v213
	v_cvt_pk_bf16_f32 v211, v214, v215
	v_cvt_pk_bf16_f32 v216, v216, v217
	v_mfma_f32_16x16x32_bf16 v[78:81], v[236:239], v[110:113], v[78:81]
	v_mfma_f32_16x16x32_bf16 v[94:97], v[236:239], v[126:129], v[94:97]
	v_cvt_pk_bf16_f32 v217, v218, v219
	v_cvt_pk_bf16_f32 v218, v220, v221
	v_cvt_pk_bf16_f32 v219, v222, v223
	s_waitcnt lgkmcnt(8)
	v_mfma_f32_16x16x32_bf16 v[2:5], v[192:195], v[166:169], v[2:5]
	v_mfma_f32_16x16x32_bf16 v[34:37], v[208:211], v[166:169], v[34:37]
	ds_read_b64_tr_b16 v[232:233], v246 offset:32768
	ds_read_b64_tr_b16 v[234:235], v246 offset:36864
	v_mfma_f32_16x16x32_bf16 v[6:9], v[192:195], v[170:173], v[6:9]
	v_mfma_f32_16x16x32_bf16 v[38:41], v[208:211], v[170:173], v[38:41]
	ds_read_b64_tr_b16 v[236:237], v247 offset:32768
	ds_read_b64_tr_b16 v[238:239], v247 offset:36864
	s_waitcnt lgkmcnt(8)
	v_mfma_f32_16x16x32_bf16 v[10:13], v[192:195], v[174:177], v[10:13]
	v_mfma_f32_16x16x32_bf16 v[42:45], v[208:211], v[174:177], v[42:45]
	ds_read_b64_tr_b16 v[166:167], v240 offset:40960
	ds_read_b64_tr_b16 v[168:169], v240 offset:45056
	v_exp_f32_e32 v66, v66
	v_exp_f32_e32 v67, v67
	v_exp_f32_e32 v68, v68
	v_mfma_f32_16x16x32_bf16 v[14:17], v[192:195], v[178:181], v[14:17]
	v_mfma_f32_16x16x32_bf16 v[46:49], v[208:211], v[178:181], v[46:49]
	ds_read_b64_tr_b16 v[170:171], v241 offset:40960
	ds_read_b64_tr_b16 v[172:173], v241 offset:45056
	v_exp_f32_e32 v69, v69
	v_exp_f32_e32 v82, v82
	s_waitcnt lgkmcnt(8)
	v_mfma_f32_16x16x32_bf16 v[18:21], v[192:195], v[224:227], v[18:21]
	v_mfma_f32_16x16x32_bf16 v[50:53], v[208:211], v[224:227], v[50:53]
	ds_read_b64_tr_b16 v[174:175], v242 offset:40960
	ds_read_b64_tr_b16 v[176:177], v242 offset:45056
	v_exp_f32_e32 v83, v83
	v_exp_f32_e32 v84, v84
	v_mfma_f32_16x16x32_bf16 v[22:25], v[192:195], v[228:231], v[22:25]
	v_mfma_f32_16x16x32_bf16 v[54:57], v[208:211], v[228:231], v[54:57]
	ds_read_b64_tr_b16 v[178:179], v243 offset:40960
	ds_read_b64_tr_b16 v[180:181], v243 offset:45056
	v_exp_f32_e32 v85, v85
	v_exp_f32_e32 v70, v70
	v_exp_f32_e32 v71, v71
	s_waitcnt lgkmcnt(8)
	v_mfma_f32_16x16x32_bf16 v[26:29], v[192:195], v[232:235], v[26:29]
	v_mfma_f32_16x16x32_bf16 v[58:61], v[208:211], v[232:235], v[58:61]
	ds_read_b64_tr_b16 v[224:225], v244 offset:40960
	ds_read_b64_tr_b16 v[226:227], v244 offset:45056
	v_exp_f32_e32 v72, v72
	v_exp_f32_e32 v73, v73
	v_mfma_f32_16x16x32_bf16 v[30:33], v[192:195], v[236:239], v[30:33]
	v_mfma_f32_16x16x32_bf16 v[62:65], v[208:211], v[236:239], v[62:65]
	ds_read_b64_tr_b16 v[228:229], v245 offset:40960
	ds_read_b64_tr_b16 v[230:231], v245 offset:45056
	v_exp_f32_e32 v86, v86
	v_exp_f32_e32 v87, v87
	s_waitcnt lgkmcnt(8)
	v_mfma_f32_16x16x32_bf16 v[2:5], v[200:203], v[166:169], v[2:5]
	v_mfma_f32_16x16x32_bf16 v[34:37], v[216:219], v[166:169], v[34:37]
	ds_read_b64_tr_b16 v[232:233], v246 offset:40960
	ds_read_b64_tr_b16 v[234:235], v246 offset:45056
	ds_read_b128 v[166:169], v187 offset:49152
	v_exp_f32_e32 v88, v88
	v_exp_f32_e32 v89, v89
	v_mfma_f32_16x16x32_bf16 v[6:9], v[200:203], v[170:173], v[6:9]
	v_mfma_f32_16x16x32_bf16 v[38:41], v[216:219], v[170:173], v[38:41]
	ds_read_b64_tr_b16 v[236:237], v247 offset:40960
	ds_read_b64_tr_b16 v[238:239], v247 offset:45056
	ds_read_b128 v[170:173], v187 offset:53248
	v_exp_f32_e32 v74, v74
	v_exp_f32_e32 v75, v75
	v_exp_f32_e32 v76, v76
	s_waitcnt lgkmcnt(10)
	v_mfma_f32_16x16x32_bf16 v[10:13], v[200:203], v[174:177], v[10:13]
	v_mfma_f32_16x16x32_bf16 v[42:45], v[216:219], v[174:177], v[42:45]
	ds_read_b128 v[174:177], v187 offset:57344
	v_exp_f32_e32 v77, v77
	v_exp_f32_e32 v90, v90
	v_mfma_f32_16x16x32_bf16 v[14:17], v[200:203], v[178:181], v[14:17]
	v_mfma_f32_16x16x32_bf16 v[46:49], v[216:219], v[178:181], v[46:49]
	ds_read_b128 v[178:181], v187 offset:61440
	v_exp_f32_e32 v91, v91
	v_exp_f32_e32 v92, v92
	s_waitcnt lgkmcnt(8)
	v_mfma_f32_16x16x32_bf16 v[18:21], v[200:203], v[224:227], v[18:21]
	v_mfma_f32_16x16x32_bf16 v[50:53], v[216:219], v[224:227], v[50:53]
	ds_read_b128 v[224:227], v188 offset:49152
	v_exp_f32_e32 v93, v93
	v_exp_f32_e32 v78, v78
	v_exp_f32_e32 v79, v79
	v_mfma_f32_16x16x32_bf16 v[22:25], v[200:203], v[228:231], v[22:25]
	v_mfma_f32_16x16x32_bf16 v[54:57], v[216:219], v[228:231], v[54:57]
	ds_read_b128 v[228:231], v188 offset:53248
	v_exp_f32_e32 v80, v80
	v_exp_f32_e32 v81, v81
	s_waitcnt lgkmcnt(5)
	v_mfma_f32_16x16x32_bf16 v[26:29], v[200:203], v[232:235], v[26:29]
	v_mfma_f32_16x16x32_bf16 v[58:61], v[216:219], v[232:235], v[58:61]
	ds_read_b128 v[232:235], v188 offset:57344
	v_exp_f32_e32 v94, v94
	v_exp_f32_e32 v95, v95
	v_mfma_f32_16x16x32_bf16 v[30:33], v[200:203], v[236:239], v[30:33]
	v_mfma_f32_16x16x32_bf16 v[62:65], v[216:219], v[236:239], v[62:65]
	ds_read_b128 v[236:239], v188 offset:61440
	v_exp_f32_e32 v96, v96
	v_exp_f32_e32 v97, v97
	s_barrier
	s_waitcnt lgkmcnt(6)
	v_mfma_f32_16x16x32_bf16 v[192:195], v[166:169], v[98:101], 0
	v_mfma_f32_16x16x32_bf16 v[208:211], v[166:169], v[114:117], 0
	ds_read_b128 v[166:169], v189 offset:49152
	s_add_i32 m0, s45, 0x0
	v_add_f32_e32 v130, v66, v67
	v_add_f32_e32 v131, v68, v69
	v_add_f32_e32 v130, v70, v130
	global_load_lds_dwordx4 v152, s[64:65]
	v_mfma_f32_16x16x32_bf16 v[196:199], v[170:173], v[98:101], 0
	v_mfma_f32_16x16x32_bf16 v[212:215], v[170:173], v[114:117], 0
	ds_read_b128 v[170:173], v189 offset:53248
	s_add_i32 m0, s45, 0x4000
	v_add_f32_e32 v131, v71, v131
	v_add_f32_e32 v130, v72, v130
	v_add_f32_e32 v131, v73, v131
	global_load_lds_dwordx4 v150, s[62:63]
	s_waitcnt lgkmcnt(6)
	v_mfma_f32_16x16x32_bf16 v[200:203], v[174:177], v[98:101], 0
	v_mfma_f32_16x16x32_bf16 v[216:219], v[174:177], v[114:117], 0
	ds_read_b128 v[174:177], v189 offset:57344
	s_add_i32 m0, s45, 0x2000
	v_add_f32_e32 v130, v74, v130
	v_add_f32_e32 v131, v75, v131
	v_add_f32_e32 v130, v76, v130
	global_load_lds_dwordx4 v153, s[64:65]
	v_mfma_f32_16x16x32_bf16 v[204:207], v[178:181], v[98:101], 0
	v_mfma_f32_16x16x32_bf16 v[220:223], v[178:181], v[114:117], 0
	ds_read_b128 v[178:181], v189 offset:61440
	s_add_i32 m0, s45, 0x6000
	v_add_f32_e32 v131, v77, v131
	v_add_f32_e32 v130, v78, v130
	v_add_f32_e32 v131, v79, v131
	global_load_lds_dwordx4 v151, s[62:63]
	s_add_u32 s62, s62, 0x4000
	s_addc_u32 s63, s63, 0
	s_add_u32 s64, s64, 0x4000
	s_addc_u32 s65, s65, 0
	s_waitcnt lgkmcnt(6)
	v_mfma_f32_16x16x32_bf16 v[192:195], v[224:227], v[102:105], v[192:195]
	v_mfma_f32_16x16x32_bf16 v[208:211], v[224:227], v[118:121], v[208:211]
	ds_read_b128 v[224:227], v190 offset:49152
	v_add_f32_e32 v130, v80, v130
	v_add_f32_e32 v131, v81, v131
	v_add_f32_e32 v130, v130, v131
	v_mfma_f32_16x16x32_bf16 v[196:199], v[228:231], v[102:105], v[196:199]
	v_mfma_f32_16x16x32_bf16 v[212:215], v[228:231], v[118:121], v[212:215]
	ds_read_b128 v[228:231], v190 offset:53248
	v_add_f32_e32 v165, v165, v130
	v_add_f32_e32 v132, v82, v83
	v_add_f32_e32 v133, v84, v85
	s_waitcnt lgkmcnt(6)
	v_mfma_f32_16x16x32_bf16 v[200:203], v[232:235], v[102:105], v[200:203]
	v_mfma_f32_16x16x32_bf16 v[216:219], v[232:235], v[118:121], v[216:219]
	ds_read_b128 v[232:235], v190 offset:57344
	v_add_f32_e32 v132, v86, v132
	v_add_f32_e32 v133, v87, v133
	v_add_f32_e32 v132, v88, v132
	v_mfma_f32_16x16x32_bf16 v[204:207], v[236:239], v[102:105], v[204:207]
	v_mfma_f32_16x16x32_bf16 v[220:223], v[236:239], v[118:121], v[220:223]
	ds_read_b128 v[236:239], v190 offset:61440
	v_add_f32_e32 v133, v89, v133
	v_add_f32_e32 v132, v90, v132
	v_add_f32_e32 v133, v91, v133
	s_waitcnt lgkmcnt(6)
	v_mfma_f32_16x16x32_bf16 v[192:195], v[166:169], v[106:109], v[192:195]
	v_mfma_f32_16x16x32_bf16 v[208:211], v[166:169], v[122:125], v[208:211]
	ds_read_b64_tr_b16 v[166:167], v142 offset:0
	ds_read_b64_tr_b16 v[168:169], v142 offset:4096
	v_add_f32_e32 v132, v92, v132
	v_add_f32_e32 v133, v93, v133
	v_add_f32_e32 v132, v94, v132
	v_mfma_f32_16x16x32_bf16 v[196:199], v[170:173], v[106:109], v[196:199]
	v_mfma_f32_16x16x32_bf16 v[212:215], v[170:173], v[122:125], v[212:215]
	ds_read_b64_tr_b16 v[170:171], v143 offset:0
	ds_read_b64_tr_b16 v[172:173], v143 offset:4096
	v_add_f32_e32 v133, v95, v133
	v_add_f32_e32 v132, v96, v132
	v_add_f32_e32 v133, v97, v133
	s_waitcnt lgkmcnt(8)
	v_mfma_f32_16x16x32_bf16 v[200:203], v[174:177], v[106:109], v[200:203]
	v_mfma_f32_16x16x32_bf16 v[216:219], v[174:177], v[122:125], v[216:219]
	ds_read_b64_tr_b16 v[174:175], v144 offset:0
	ds_read_b64_tr_b16 v[176:177], v144 offset:4096
	v_add_f32_e32 v132, v132, v133
	v_add_f32_e32 v163, v163, v132
	v_cvt_pk_bf16_f32 v66, v66, v67
	v_mfma_f32_16x16x32_bf16 v[204:207], v[178:181], v[106:109], v[204:207]
	v_mfma_f32_16x16x32_bf16 v[220:223], v[178:181], v[122:125], v[220:223]
	ds_read_b64_tr_b16 v[178:179], v145 offset:0
	ds_read_b64_tr_b16 v[180:181], v145 offset:4096
	v_cvt_pk_bf16_f32 v67, v68, v69
	v_cvt_pk_bf16_f32 v68, v70, v71
	v_cvt_pk_bf16_f32 v69, v72, v73
	s_waitcnt lgkmcnt(10)
	v_mfma_f32_16x16x32_bf16 v[192:195], v[224:227], v[110:113], v[192:195]
	v_mfma_f32_16x16x32_bf16 v[208:211], v[224:227], v[126:129], v[208:211]
	ds_read_b64_tr_b16 v[224:225], v146 offset:0
	ds_read_b64_tr_b16 v[226:227], v146 offset:4096
	v_cvt_pk_bf16_f32 v74, v74, v75
	v_cvt_pk_bf16_f32 v75, v76, v77
	v_cvt_pk_bf16_f32 v76, v78, v79
	v_mfma_f32_16x16x32_bf16 v[196:199], v[228:231], v[110:113], v[196:199]
	v_mfma_f32_16x16x32_bf16 v[212:215], v[228:231], v[126:129], v[212:215]
	ds_read_b64_tr_b16 v[228:229], v147 offset:0
	ds_read_b64_tr_b16 v[230:231], v147 offset:4096
	v_cvt_pk_bf16_f32 v77, v80, v81
	v_cvt_pk_bf16_f32 v82, v82, v83
	v_cvt_pk_bf16_f32 v83, v84, v85
	s_waitcnt lgkmcnt(12)
	v_mfma_f32_16x16x32_bf16 v[200:203], v[232:235], v[110:113], v[200:203]
	v_mfma_f32_16x16x32_bf16 v[216:219], v[232:235], v[126:129], v[216:219]
	v_cvt_pk_bf16_f32 v84, v86, v87
	v_cvt_pk_bf16_f32 v85, v88, v89
	v_cvt_pk_bf16_f32 v90, v90, v91
	v_mfma_f32_16x16x32_bf16 v[204:207], v[236:239], v[110:113], v[204:207]
	v_mfma_f32_16x16x32_bf16 v[220:223], v[236:239], v[126:129], v[220:223]
	v_cvt_pk_bf16_f32 v91, v92, v93
	v_cvt_pk_bf16_f32 v92, v94, v95
	v_cvt_pk_bf16_f32 v93, v96, v97
	s_waitcnt lgkmcnt(8)
	v_mfma_f32_16x16x32_bf16 v[2:5], v[66:69], v[166:169], v[2:5]
	v_mfma_f32_16x16x32_bf16 v[34:37], v[82:85], v[166:169], v[34:37]
	ds_read_b64_tr_b16 v[232:233], v148 offset:0
	ds_read_b64_tr_b16 v[234:235], v148 offset:4096
	v_mfma_f32_16x16x32_bf16 v[6:9], v[66:69], v[170:173], v[6:9]
	v_mfma_f32_16x16x32_bf16 v[38:41], v[82:85], v[170:173], v[38:41]
	ds_read_b64_tr_b16 v[236:237], v149 offset:0
	ds_read_b64_tr_b16 v[238:239], v149 offset:4096
	s_waitcnt lgkmcnt(8)
	v_mfma_f32_16x16x32_bf16 v[10:13], v[66:69], v[174:177], v[10:13]
	v_mfma_f32_16x16x32_bf16 v[42:45], v[82:85], v[174:177], v[42:45]
	ds_read_b64_tr_b16 v[166:167], v142 offset:8192
	ds_read_b64_tr_b16 v[168:169], v142 offset:12288
	v_exp_f32_e32 v192, v192
	v_exp_f32_e32 v193, v193
	v_exp_f32_e32 v194, v194
	v_mfma_f32_16x16x32_bf16 v[14:17], v[66:69], v[178:181], v[14:17]
	v_mfma_f32_16x16x32_bf16 v[46:49], v[82:85], v[178:181], v[46:49]
	ds_read_b64_tr_b16 v[170:171], v143 offset:8192
	ds_read_b64_tr_b16 v[172:173], v143 offset:12288
	v_exp_f32_e32 v195, v195
	v_exp_f32_e32 v208, v208
	s_waitcnt lgkmcnt(8)
	v_mfma_f32_16x16x32_bf16 v[18:21], v[66:69], v[224:227], v[18:21]
	v_mfma_f32_16x16x32_bf16 v[50:53], v[82:85], v[224:227], v[50:53]
	ds_read_b64_tr_b16 v[174:175], v144 offset:8192
	ds_read_b64_tr_b16 v[176:177], v144 offset:12288
	v_exp_f32_e32 v209, v209
	v_exp_f32_e32 v210, v210
	v_mfma_f32_16x16x32_bf16 v[22:25], v[66:69], v[228:231], v[22:25]
	v_mfma_f32_16x16x32_bf16 v[54:57], v[82:85], v[228:231], v[54:57]
	ds_read_b64_tr_b16 v[178:179], v145 offset:8192
	ds_read_b64_tr_b16 v[180:181], v145 offset:12288
	v_exp_f32_e32 v211, v211
	v_exp_f32_e32 v196, v196
	v_exp_f32_e32 v197, v197
	s_waitcnt lgkmcnt(8)
	v_mfma_f32_16x16x32_bf16 v[26:29], v[66:69], v[232:235], v[26:29]
	v_mfma_f32_16x16x32_bf16 v[58:61], v[82:85], v[232:235], v[58:61]
	ds_read_b64_tr_b16 v[224:225], v146 offset:8192
	ds_read_b64_tr_b16 v[226:227], v146 offset:12288
	v_exp_f32_e32 v198, v198
	v_exp_f32_e32 v199, v199
	v_mfma_f32_16x16x32_bf16 v[30:33], v[66:69], v[236:239], v[30:33]
	v_mfma_f32_16x16x32_bf16 v[62:65], v[82:85], v[236:239], v[62:65]
	ds_read_b64_tr_b16 v[228:229], v147 offset:8192
	ds_read_b64_tr_b16 v[230:231], v147 offset:12288
	v_exp_f32_e32 v212, v212
	v_exp_f32_e32 v213, v213
	s_waitcnt lgkmcnt(8)
	v_mfma_f32_16x16x32_bf16 v[2:5], v[74:77], v[166:169], v[2:5]
	v_mfma_f32_16x16x32_bf16 v[34:37], v[90:93], v[166:169], v[34:37]
	ds_read_b64_tr_b16 v[232:233], v148 offset:8192
	ds_read_b64_tr_b16 v[234:235], v148 offset:12288
	v_exp_f32_e32 v214, v214
	v_exp_f32_e32 v215, v215
	v_mfma_f32_16x16x32_bf16 v[6:9], v[74:77], v[170:173], v[6:9]
	v_mfma_f32_16x16x32_bf16 v[38:41], v[90:93], v[170:173], v[38:41]
	ds_read_b64_tr_b16 v[236:237], v149 offset:8192
	ds_read_b64_tr_b16 v[238:239], v149 offset:12288
	v_exp_f32_e32 v200, v200
	v_exp_f32_e32 v201, v201
	v_exp_f32_e32 v202, v202
	s_waitcnt lgkmcnt(8)
	v_mfma_f32_16x16x32_bf16 v[10:13], v[74:77], v[174:177], v[10:13]
	v_mfma_f32_16x16x32_bf16 v[42:45], v[90:93], v[174:177], v[42:45]
	v_exp_f32_e32 v203, v203
	v_exp_f32_e32 v216, v216
	v_mfma_f32_16x16x32_bf16 v[14:17], v[74:77], v[178:181], v[14:17]
	v_mfma_f32_16x16x32_bf16 v[46:49], v[90:93], v[178:181], v[46:49]
	v_exp_f32_e32 v217, v217
	v_exp_f32_e32 v218, v218
	s_waitcnt lgkmcnt(4)
	v_mfma_f32_16x16x32_bf16 v[18:21], v[74:77], v[224:227], v[18:21]
	v_mfma_f32_16x16x32_bf16 v[50:53], v[90:93], v[224:227], v[50:53]
	v_exp_f32_e32 v219, v219
	v_exp_f32_e32 v204, v204
	v_exp_f32_e32 v205, v205
	v_mfma_f32_16x16x32_bf16 v[22:25], v[74:77], v[228:231], v[22:25]
	v_mfma_f32_16x16x32_bf16 v[54:57], v[90:93], v[228:231], v[54:57]
	v_exp_f32_e32 v206, v206
	v_exp_f32_e32 v207, v207
	s_waitcnt lgkmcnt(0)
	v_mfma_f32_16x16x32_bf16 v[26:29], v[74:77], v[232:235], v[26:29]
	v_mfma_f32_16x16x32_bf16 v[58:61], v[90:93], v[232:235], v[58:61]
	v_exp_f32_e32 v220, v220
	v_exp_f32_e32 v221, v221
	v_mfma_f32_16x16x32_bf16 v[30:33], v[74:77], v[236:239], v[30:33]
	v_mfma_f32_16x16x32_bf16 v[62:65], v[90:93], v[236:239], v[62:65]
	v_exp_f32_e32 v222, v222
	v_exp_f32_e32 v223, v223
	s_add_i32 m0, s45, 0x8000
	s_nop 0
	global_load_lds_dwordx4 v152, s[64:65]
	s_add_i32 m0, s45, 0xc000
	s_nop 0
	global_load_lds_dwordx4 v150, s[62:63]
	s_add_i32 m0, s45, 0xa000
	s_nop 0
	global_load_lds_dwordx4 v153, s[64:65]
	s_add_i32 m0, s45, 0xe000
	s_nop 0
	global_load_lds_dwordx4 v151, s[62:63]
	s_add_u32 s62, s62, 0x4000
	s_addc_u32 s63, s63, 0
	s_add_u32 s64, s64, 0x4000
	s_addc_u32 s65, s65, 0
	global_load_dwordx4 v[98:101], v154, s[60:61]
	global_load_dwordx4 v[102:105], v154, s[60:61] offset:64
	global_load_dwordx4 v[106:109], v154, s[60:61] offset:128
	global_load_dwordx4 v[110:113], v154, s[60:61] offset:192
	global_load_dwordx4 v[114:117], v155, s[60:61]
	global_load_dwordx4 v[118:121], v155, s[60:61] offset:64
	global_load_dwordx4 v[122:125], v155, s[60:61] offset:128
	global_load_dwordx4 v[126:129], v155, s[60:61] offset:192
	s_barrier
	ds_read_b64_tr_b16 v[166:167], v142 offset:32768
	ds_read_b64_tr_b16 v[168:169], v142 offset:36864
	ds_read_b64_tr_b16 v[170:171], v143 offset:32768
	ds_read_b64_tr_b16 v[172:173], v143 offset:36864
	ds_read_b64_tr_b16 v[174:175], v144 offset:32768
	ds_read_b64_tr_b16 v[176:177], v144 offset:36864
	ds_read_b64_tr_b16 v[178:179], v145 offset:32768
	ds_read_b64_tr_b16 v[180:181], v145 offset:36864
	ds_read_b64_tr_b16 v[224:225], v146 offset:32768
	ds_read_b64_tr_b16 v[226:227], v146 offset:36864
	ds_read_b64_tr_b16 v[228:229], v147 offset:32768
	ds_read_b64_tr_b16 v[230:231], v147 offset:36864
	v_add_f32_e32 v130, v192, v193
	v_add_f32_e32 v131, v194, v195
	v_add_f32_e32 v130, v196, v130
	v_add_f32_e32 v131, v197, v131
	v_add_f32_e32 v130, v198, v130
	v_add_f32_e32 v131, v199, v131
	v_add_f32_e32 v130, v200, v130
	v_add_f32_e32 v131, v201, v131
	v_add_f32_e32 v130, v202, v130
	v_add_f32_e32 v131, v203, v131
	v_add_f32_e32 v130, v204, v130
	v_add_f32_e32 v131, v205, v131
	v_add_f32_e32 v130, v206, v130
	v_add_f32_e32 v131, v207, v131
	v_add_f32_e32 v130, v130, v131
	v_add_f32_e32 v165, v165, v130
	v_add_f32_e32 v132, v208, v209
	v_add_f32_e32 v133, v210, v211
	v_add_f32_e32 v132, v212, v132
	v_add_f32_e32 v133, v213, v133
	v_add_f32_e32 v132, v214, v132
	v_add_f32_e32 v133, v215, v133
	v_add_f32_e32 v132, v216, v132
	v_add_f32_e32 v133, v217, v133
	v_add_f32_e32 v132, v218, v132
	v_add_f32_e32 v133, v219, v133
	v_add_f32_e32 v132, v220, v132
	v_add_f32_e32 v133, v221, v133
	v_add_f32_e32 v132, v222, v132
	v_add_f32_e32 v133, v223, v133
	v_add_f32_e32 v132, v132, v133
	v_add_f32_e32 v163, v163, v132
	v_cvt_pk_bf16_f32 v192, v192, v193
	v_cvt_pk_bf16_f32 v193, v194, v195
	v_cvt_pk_bf16_f32 v194, v196, v197
	v_cvt_pk_bf16_f32 v195, v198, v199
	v_cvt_pk_bf16_f32 v200, v200, v201
	v_cvt_pk_bf16_f32 v201, v202, v203
	v_cvt_pk_bf16_f32 v202, v204, v205
	v_cvt_pk_bf16_f32 v203, v206, v207
	v_cvt_pk_bf16_f32 v208, v208, v209
	v_cvt_pk_bf16_f32 v209, v210, v211
	v_cvt_pk_bf16_f32 v210, v212, v213
	v_cvt_pk_bf16_f32 v211, v214, v215
	v_cvt_pk_bf16_f32 v216, v216, v217
	v_cvt_pk_bf16_f32 v217, v218, v219
	v_cvt_pk_bf16_f32 v218, v220, v221
	v_cvt_pk_bf16_f32 v219, v222, v223
	s_waitcnt lgkmcnt(8)
	v_mfma_f32_16x16x32_bf16 v[2:5], v[192:195], v[166:169], v[2:5]
	v_mfma_f32_16x16x32_bf16 v[34:37], v[208:211], v[166:169], v[34:37]
	ds_read_b64_tr_b16 v[232:233], v148 offset:32768
	ds_read_b64_tr_b16 v[234:235], v148 offset:36864
	v_mfma_f32_16x16x32_bf16 v[6:9], v[192:195], v[170:173], v[6:9]
	v_mfma_f32_16x16x32_bf16 v[38:41], v[208:211], v[170:173], v[38:41]
	ds_read_b64_tr_b16 v[236:237], v149 offset:32768
	ds_read_b64_tr_b16 v[238:239], v149 offset:36864
	s_waitcnt lgkmcnt(8)
	v_mfma_f32_16x16x32_bf16 v[10:13], v[192:195], v[174:177], v[10:13]
	v_mfma_f32_16x16x32_bf16 v[42:45], v[208:211], v[174:177], v[42:45]
	ds_read_b64_tr_b16 v[166:167], v142 offset:40960
	ds_read_b64_tr_b16 v[168:169], v142 offset:45056
	v_mfma_f32_16x16x32_bf16 v[14:17], v[192:195], v[178:181], v[14:17]
	v_mfma_f32_16x16x32_bf16 v[46:49], v[208:211], v[178:181], v[46:49]
	ds_read_b64_tr_b16 v[170:171], v143 offset:40960
	ds_read_b64_tr_b16 v[172:173], v143 offset:45056
	s_waitcnt lgkmcnt(8)
	v_mfma_f32_16x16x32_bf16 v[18:21], v[192:195], v[224:227], v[18:21]
	v_mfma_f32_16x16x32_bf16 v[50:53], v[208:211], v[224:227], v[50:53]
	ds_read_b64_tr_b16 v[174:175], v144 offset:40960
	ds_read_b64_tr_b16 v[176:177], v144 offset:45056
	v_mfma_f32_16x16x32_bf16 v[22:25], v[192:195], v[228:231], v[22:25]
	v_mfma_f32_16x16x32_bf16 v[54:57], v[208:211], v[228:231], v[54:57]
	ds_read_b64_tr_b16 v[178:179], v145 offset:40960
	ds_read_b64_tr_b16 v[180:181], v145 offset:45056
	s_waitcnt lgkmcnt(8)
	v_mfma_f32_16x16x32_bf16 v[26:29], v[192:195], v[232:235], v[26:29]
	v_mfma_f32_16x16x32_bf16 v[58:61], v[208:211], v[232:235], v[58:61]
	ds_read_b64_tr_b16 v[224:225], v146 offset:40960
	ds_read_b64_tr_b16 v[226:227], v146 offset:45056
	v_mfma_f32_16x16x32_bf16 v[30:33], v[192:195], v[236:239], v[30:33]
	v_mfma_f32_16x16x32_bf16 v[62:65], v[208:211], v[236:239], v[62:65]
	ds_read_b64_tr_b16 v[228:229], v147 offset:40960
	ds_read_b64_tr_b16 v[230:231], v147 offset:45056
	s_waitcnt lgkmcnt(8)
	v_mfma_f32_16x16x32_bf16 v[2:5], v[200:203], v[166:169], v[2:5]
	v_mfma_f32_16x16x32_bf16 v[34:37], v[216:219], v[166:169], v[34:37]
	ds_read_b64_tr_b16 v[232:233], v148 offset:40960
	ds_read_b64_tr_b16 v[234:235], v148 offset:45056
	v_mfma_f32_16x16x32_bf16 v[6:9], v[200:203], v[170:173], v[6:9]
	v_mfma_f32_16x16x32_bf16 v[38:41], v[216:219], v[170:173], v[38:41]
	ds_read_b64_tr_b16 v[236:237], v149 offset:40960
	ds_read_b64_tr_b16 v[238:239], v149 offset:45056
	s_waitcnt lgkmcnt(8)
	v_mfma_f32_16x16x32_bf16 v[10:13], v[200:203], v[174:177], v[10:13]
	v_mfma_f32_16x16x32_bf16 v[42:45], v[216:219], v[174:177], v[42:45]
	v_mfma_f32_16x16x32_bf16 v[14:17], v[200:203], v[178:181], v[14:17]
	v_mfma_f32_16x16x32_bf16 v[46:49], v[216:219], v[178:181], v[46:49]
	s_waitcnt lgkmcnt(4)
	v_mfma_f32_16x16x32_bf16 v[18:21], v[200:203], v[224:227], v[18:21]
	v_mfma_f32_16x16x32_bf16 v[50:53], v[216:219], v[224:227], v[50:53]
	v_mfma_f32_16x16x32_bf16 v[22:25], v[200:203], v[228:231], v[22:25]
	v_mfma_f32_16x16x32_bf16 v[54:57], v[216:219], v[228:231], v[54:57]
	s_waitcnt lgkmcnt(0)
	v_mfma_f32_16x16x32_bf16 v[26:29], v[200:203], v[232:235], v[26:29]
	v_mfma_f32_16x16x32_bf16 v[58:61], v[216:219], v[232:235], v[58:61]
	v_mfma_f32_16x16x32_bf16 v[30:33], v[200:203], v[236:239], v[30:33]
	v_mfma_f32_16x16x32_bf16 v[62:65], v[216:219], v[236:239], v[62:65]
	ds_write_b32 v160, v165
	ds_write_b32 v160, v163 offset:256
	s_waitcnt lgkmcnt(0)
	ds_read_b128 v[66:69], v161 offset:0
	ds_read_b128 v[70:73], v161 offset:64
	ds_read_b128 v[74:77], v161 offset:128
	ds_read_b128 v[78:81], v161 offset:192
	ds_read_b128 v[82:85], v161 offset:256
	ds_read_b128 v[86:89], v161 offset:320
	ds_read_b128 v[90:93], v161 offset:384
	ds_read_b128 v[94:97], v161 offset:448
	s_waitcnt lgkmcnt(0)
	v_add_f32_e32 v66, v66, v70
	v_add_f32_e32 v74, v74, v78
	v_add_f32_e32 v66, v66, v74
	v_rcp_f32_e32 v192, v66
	v_add_f32_e32 v67, v67, v71
	v_add_f32_e32 v75, v75, v79
	v_add_f32_e32 v67, v67, v75
	v_rcp_f32_e32 v193, v67
	v_add_f32_e32 v68, v68, v72
	v_add_f32_e32 v76, v76, v80
	v_add_f32_e32 v68, v68, v76
	v_rcp_f32_e32 v194, v68
	v_add_f32_e32 v69, v69, v73
	v_add_f32_e32 v77, v77, v81
	v_add_f32_e32 v69, v69, v77
	v_rcp_f32_e32 v195, v69
	v_add_f32_e32 v82, v82, v86
	v_add_f32_e32 v90, v90, v94
	v_add_f32_e32 v82, v82, v90
	v_rcp_f32_e32 v196, v82
	v_add_f32_e32 v83, v83, v87
	v_add_f32_e32 v91, v91, v95
	v_add_f32_e32 v83, v83, v91
	v_rcp_f32_e32 v197, v83
	v_add_f32_e32 v84, v84, v88
	v_add_f32_e32 v92, v92, v96
	v_add_f32_e32 v84, v84, v92
	v_rcp_f32_e32 v198, v84
	v_add_f32_e32 v85, v85, v89
	v_add_f32_e32 v93, v93, v97
	v_add_f32_e32 v85, v85, v93
	v_rcp_f32_e32 v199, v85
	s_nop 0
	v_mul_f32_e32 v2, v2, v192
	v_mul_f32_e32 v6, v6, v192
	v_cvt_pk_bf16_f32 v200, v2, v6
	global_store_short v156, v200, s[46:47] offset:0
	global_store_short_d16_hi v156, v200, s[46:47] offset:32
	v_mul_f32_e32 v10, v10, v192
	v_mul_f32_e32 v14, v14, v192
	v_cvt_pk_bf16_f32 v201, v10, v14
	global_store_short v156, v201, s[46:47] offset:64
	global_store_short_d16_hi v156, v201, s[46:47] offset:96
	v_mul_f32_e32 v18, v18, v192
	v_mul_f32_e32 v22, v22, v192
	v_cvt_pk_bf16_f32 v202, v18, v22
	global_store_short v156, v202, s[46:47] offset:128
	global_store_short_d16_hi v156, v202, s[46:47] offset:160
	v_mul_f32_e32 v26, v26, v192
	v_mul_f32_e32 v30, v30, v192
	v_cvt_pk_bf16_f32 v203, v26, v30
	global_store_short v156, v203, s[46:47] offset:192
	global_store_short_d16_hi v156, v203, s[46:47] offset:224
	v_mul_f32_e32 v3, v3, v193
	v_mul_f32_e32 v7, v7, v193
	v_cvt_pk_bf16_f32 v204, v3, v7
	global_store_short v156, v204, s[46:47] offset:2048
	global_store_short_d16_hi v156, v204, s[46:47] offset:2080
	v_mul_f32_e32 v11, v11, v193
	v_mul_f32_e32 v15, v15, v193
	v_cvt_pk_bf16_f32 v205, v11, v15
	global_store_short v156, v205, s[46:47] offset:2112
	global_store_short_d16_hi v156, v205, s[46:47] offset:2144
	v_mul_f32_e32 v19, v19, v193
	v_mul_f32_e32 v23, v23, v193
	v_cvt_pk_bf16_f32 v206, v19, v23
	global_store_short v156, v206, s[46:47] offset:2176
	global_store_short_d16_hi v156, v206, s[46:47] offset:2208
	v_mul_f32_e32 v27, v27, v193
	v_mul_f32_e32 v31, v31, v193
	v_cvt_pk_bf16_f32 v207, v27, v31
	global_store_short v156, v207, s[46:47] offset:2240
	global_store_short_d16_hi v156, v207, s[46:47] offset:2272
	v_mul_f32_e32 v4, v4, v194
	v_mul_f32_e32 v8, v8, v194
	v_cvt_pk_bf16_f32 v200, v4, v8
	global_store_short v157, v200, s[46:47] offset:0
	global_store_short_d16_hi v157, v200, s[46:47] offset:32
	v_mul_f32_e32 v12, v12, v194
	v_mul_f32_e32 v16, v16, v194
	v_cvt_pk_bf16_f32 v201, v12, v16
	global_store_short v157, v201, s[46:47] offset:64
	global_store_short_d16_hi v157, v201, s[46:47] offset:96
	v_mul_f32_e32 v20, v20, v194
	v_mul_f32_e32 v24, v24, v194
	v_cvt_pk_bf16_f32 v202, v20, v24
	global_store_short v157, v202, s[46:47] offset:128
	global_store_short_d16_hi v157, v202, s[46:47] offset:160
	v_mul_f32_e32 v28, v28, v194
	v_mul_f32_e32 v32, v32, v194
	v_cvt_pk_bf16_f32 v203, v28, v32
	global_store_short v157, v203, s[46:47] offset:192
	global_store_short_d16_hi v157, v203, s[46:47] offset:224
	v_mul_f32_e32 v5, v5, v195
	v_mul_f32_e32 v9, v9, v195
	v_cvt_pk_bf16_f32 v204, v5, v9
	global_store_short v157, v204, s[46:47] offset:2048
	global_store_short_d16_hi v157, v204, s[46:47] offset:2080
	v_mul_f32_e32 v13, v13, v195
	v_mul_f32_e32 v17, v17, v195
	v_cvt_pk_bf16_f32 v205, v13, v17
	global_store_short v157, v205, s[46:47] offset:2112
	global_store_short_d16_hi v157, v205, s[46:47] offset:2144
	v_mul_f32_e32 v21, v21, v195
	v_mul_f32_e32 v25, v25, v195
	v_cvt_pk_bf16_f32 v206, v21, v25
	global_store_short v157, v206, s[46:47] offset:2176
	global_store_short_d16_hi v157, v206, s[46:47] offset:2208
	v_mul_f32_e32 v29, v29, v195
	v_mul_f32_e32 v33, v33, v195
	v_cvt_pk_bf16_f32 v207, v29, v33
	global_store_short v157, v207, s[46:47] offset:2240
	global_store_short_d16_hi v157, v207, s[46:47] offset:2272
	v_mul_f32_e32 v34, v34, v196
	v_mul_f32_e32 v38, v38, v196
	v_cvt_pk_bf16_f32 v200, v34, v38
	global_store_short v158, v200, s[46:47] offset:0
	global_store_short_d16_hi v158, v200, s[46:47] offset:32
	v_mul_f32_e32 v42, v42, v196
	v_mul_f32_e32 v46, v46, v196
	v_cvt_pk_bf16_f32 v201, v42, v46
	global_store_short v158, v201, s[46:47] offset:64
	global_store_short_d16_hi v158, v201, s[46:47] offset:96
	v_mul_f32_e32 v50, v50, v196
	v_mul_f32_e32 v54, v54, v196
	v_cvt_pk_bf16_f32 v202, v50, v54
	global_store_short v158, v202, s[46:47] offset:128
	global_store_short_d16_hi v158, v202, s[46:47] offset:160
	v_mul_f32_e32 v58, v58, v196
	v_mul_f32_e32 v62, v62, v196
	v_cvt_pk_bf16_f32 v203, v58, v62
	global_store_short v158, v203, s[46:47] offset:192
	global_store_short_d16_hi v158, v203, s[46:47] offset:224
	v_mul_f32_e32 v35, v35, v197
	v_mul_f32_e32 v39, v39, v197
	v_cvt_pk_bf16_f32 v204, v35, v39
	global_store_short v158, v204, s[46:47] offset:2048
	global_store_short_d16_hi v158, v204, s[46:47] offset:2080
	v_mul_f32_e32 v43, v43, v197
	v_mul_f32_e32 v47, v47, v197
	v_cvt_pk_bf16_f32 v205, v43, v47
	global_store_short v158, v205, s[46:47] offset:2112
	global_store_short_d16_hi v158, v205, s[46:47] offset:2144
	v_mul_f32_e32 v51, v51, v197
	v_mul_f32_e32 v55, v55, v197
	v_cvt_pk_bf16_f32 v206, v51, v55
	global_store_short v158, v206, s[46:47] offset:2176
	global_store_short_d16_hi v158, v206, s[46:47] offset:2208
	v_mul_f32_e32 v59, v59, v197
	v_mul_f32_e32 v63, v63, v197
	v_cvt_pk_bf16_f32 v207, v59, v63
	global_store_short v158, v207, s[46:47] offset:2240
	global_store_short_d16_hi v158, v207, s[46:47] offset:2272
	v_mul_f32_e32 v36, v36, v198
	v_mul_f32_e32 v40, v40, v198
	v_cvt_pk_bf16_f32 v200, v36, v40
	global_store_short v159, v200, s[46:47] offset:0
	global_store_short_d16_hi v159, v200, s[46:47] offset:32
	v_mul_f32_e32 v44, v44, v198
	v_mul_f32_e32 v48, v48, v198
	v_cvt_pk_bf16_f32 v201, v44, v48
	global_store_short v159, v201, s[46:47] offset:64
	global_store_short_d16_hi v159, v201, s[46:47] offset:96
	v_mul_f32_e32 v52, v52, v198
	v_mul_f32_e32 v56, v56, v198
	v_cvt_pk_bf16_f32 v202, v52, v56
	global_store_short v159, v202, s[46:47] offset:128
	global_store_short_d16_hi v159, v202, s[46:47] offset:160
	v_mul_f32_e32 v60, v60, v198
	v_mul_f32_e32 v64, v64, v198
	v_cvt_pk_bf16_f32 v203, v60, v64
	global_store_short v159, v203, s[46:47] offset:192
	global_store_short_d16_hi v159, v203, s[46:47] offset:224
	v_mul_f32_e32 v37, v37, v199
	v_mul_f32_e32 v41, v41, v199
	v_cvt_pk_bf16_f32 v204, v37, v41
	global_store_short v159, v204, s[46:47] offset:2048
	global_store_short_d16_hi v159, v204, s[46:47] offset:2080
	v_mul_f32_e32 v45, v45, v199
	v_mul_f32_e32 v49, v49, v199
	v_cvt_pk_bf16_f32 v205, v45, v49
	global_store_short v159, v205, s[46:47] offset:2112
	global_store_short_d16_hi v159, v205, s[46:47] offset:2144
	v_mul_f32_e32 v53, v53, v199
	v_mul_f32_e32 v57, v57, v199
	v_cvt_pk_bf16_f32 v206, v53, v57
	global_store_short v159, v206, s[46:47] offset:2176
	global_store_short_d16_hi v159, v206, s[46:47] offset:2208
	v_mul_f32_e32 v61, v61, v199
	v_mul_f32_e32 v65, v65, v199
	v_cvt_pk_bf16_f32 v207, v61, v65
	global_store_short v159, v207, s[46:47] offset:2240
	global_store_short_d16_hi v159, v207, s[46:47] offset:2272
	s_mov_b32 s46, s18
	s_mov_b32 s47, s19
	v_mov_b32_e32 v2, 0
	v_mov_b32_e32 v3, 0
	v_mov_b32_e32 v4, 0
	v_mov_b32_e32 v5, 0
	v_mov_b32_e32 v6, 0
	v_mov_b32_e32 v7, 0
	v_mov_b32_e32 v8, 0
	v_mov_b32_e32 v9, 0
	v_mov_b32_e32 v10, 0
	v_mov_b32_e32 v11, 0
	v_mov_b32_e32 v12, 0
	v_mov_b32_e32 v13, 0
	v_mov_b32_e32 v14, 0
	v_mov_b32_e32 v15, 0
	v_mov_b32_e32 v16, 0
	v_mov_b32_e32 v17, 0
	v_mov_b32_e32 v18, 0
	v_mov_b32_e32 v19, 0
	v_mov_b32_e32 v20, 0
	v_mov_b32_e32 v21, 0
	v_mov_b32_e32 v22, 0
	v_mov_b32_e32 v23, 0
	v_mov_b32_e32 v24, 0
	v_mov_b32_e32 v25, 0
	v_mov_b32_e32 v26, 0
	v_mov_b32_e32 v27, 0
	v_mov_b32_e32 v28, 0
	v_mov_b32_e32 v29, 0
	v_mov_b32_e32 v30, 0
	v_mov_b32_e32 v31, 0
	v_mov_b32_e32 v32, 0
	v_mov_b32_e32 v33, 0
	v_mov_b32_e32 v34, 0
	v_mov_b32_e32 v35, 0
	v_mov_b32_e32 v36, 0
	v_mov_b32_e32 v37, 0
	v_mov_b32_e32 v38, 0
	v_mov_b32_e32 v39, 0
	v_mov_b32_e32 v40, 0
	v_mov_b32_e32 v41, 0
	v_mov_b32_e32 v42, 0
	v_mov_b32_e32 v43, 0
	v_mov_b32_e32 v44, 0
	v_mov_b32_e32 v45, 0
	v_mov_b32_e32 v46, 0
	v_mov_b32_e32 v47, 0
	v_mov_b32_e32 v48, 0
	v_mov_b32_e32 v49, 0
	v_mov_b32_e32 v50, 0
	v_mov_b32_e32 v51, 0
	v_mov_b32_e32 v52, 0
	v_mov_b32_e32 v53, 0
	v_mov_b32_e32 v54, 0
	v_mov_b32_e32 v55, 0
	v_mov_b32_e32 v56, 0
	v_mov_b32_e32 v57, 0
	v_mov_b32_e32 v58, 0
	v_mov_b32_e32 v59, 0
	v_mov_b32_e32 v60, 0
	v_mov_b32_e32 v61, 0
	v_mov_b32_e32 v62, 0
	v_mov_b32_e32 v63, 0
	v_mov_b32_e32 v64, 0
	v_mov_b32_e32 v65, 0
	v_mov_b32_e32 v165, 0
	v_mov_b32_e32 v163, 0
	s_waitcnt vmcnt(63)
	s_add_i32 s3, s3, s33
	s_cmpk_lt_i32 s3, 0x400
	s_cbranch_scc1 .Lattn_unit

.LBB0_566:
	s_cmp_lt_i32 s58, 6
	s_cselect_b64 s[6:7], -1, 0
	s_and_b64 s[0:1], s[6:7], s[0:1]
	v_bfe_u32 v1, v0, 1, 9
	s_andn2_b64 vcc, exec, s[0:1]
	v_and_b32_e32 v211, 1, v0
	v_lshl_add_u32 v210, v1, 2, 0
	s_cbranch_vccnz .LBB0_591
	s_waitcnt vmcnt(0)
	v_lshlrev_b32_e32 v2, 5, v211
	s_waitcnt lgkmcnt(0)
	v_mov_b32_e32 v3, 0
	v_lshl_add_u64 v[2:3], s[56:57], 0, v[2:3]
	s_mov_b64 s[0:1], 0x1ecb4000
	v_lshl_add_u64 v[4:5], v[2:3], 0, s[0:1]
	v_and_b32_e32 v2, 0x3ff, v0
	v_mbcnt_lo_u32_b32 v11, -1, 0
	s_add_u32 s12, s56, 0x1eeb4000
	v_lshlrev_b32_e32 v3, 2, v2
	v_mbcnt_hi_u32_b32 v11, -1, v11
	s_addc_u32 s13, s57, 0
	s_ashr_i32 s3, s2, 31
	s_movk_i32 s4, 0x100
	v_add_u32_e32 v6, 0, v3
	v_and_b32_e32 v12, 64, v11
	s_ashr_i32 s40, s33, 31
	s_mov_b32 s14, 0
	v_cmp_eq_u32_e64 s[0:1], 0, v211
	v_cmp_gt_u32_e64 s[4:5], s4, v2
	v_add_u32_e32 v8, 0x20000, v210
	v_add_u32_e32 v9, 0x23000, v6
	v_mov_b64_e32 v[6:7], 0xaff
	s_movk_i32 s15, 0x161
	v_mov_b32_e32 v10, 0x358637bd
	v_xor_b32_e32 v13, 1, v11
	v_add_u32_e32 v14, 64, v12
	v_lshlrev_b32_e32 v12, 2, v2
	s_mov_b64 s[8:9], s[2:3]
	s_mov_b32 s99, 0
	v_cmp_gt_i64_e32 vcc, s[8:9], v[6:7]
	s_cbranch_vccnz .Lpre5_issued
	s_ashr_i32 s10, s8, 31
	s_lshr_b32 s10, s10, 29
	s_add_i32 s10, s8, s10
	s_ashr_i32 s11, s10, 3
	s_and_b32 s10, s10, -8
	s_sub_i32 s10, s8, s10
	s_cmp_lt_i32 s10, 0
	s_cselect_b32 s16, s15, 0x160
	s_mul_i32 s10, s10, s16
	s_add_i32 s10, s10, s11
	s_mul_hi_i32 s11, s10, 0x2e8ba2e9
	s_lshr_b32 s16, s11, 31
	s_ashr_i32 s11, s11, 5
	s_add_i32 s11, s11, s16
	s_lshl_b32 s17, s11, 3
	s_sub_i32 s16, 0x80, s17
	s_min_i32 s18, s16, 8
	s_abs_i32 s16, s18
	v_cvt_f32_u32_e32 v15, s16
	s_sub_i32 s24, 0, s16
	s_mulk_i32 s11, 0xb0
	s_sub_i32 s10, s10, s11
	v_rcp_iflag_f32_e32 v15, v15
	s_abs_i32 s11, s10
	s_xor_b32 s19, s10, s18
	s_ashr_i32 s19, s19, 31
	v_mul_f32_e32 v15, 0x4f7ffffe, v15
	v_cvt_u32_f32_e32 v15, v15
	v_cmp_lt_i32_e32 vcc, v13, v14
	v_readfirstlane_b32 s25, v15
	s_mul_i32 s24, s24, s25
	s_mul_hi_u32 s24, s25, s24
	s_add_i32 s25, s25, s24
	s_mul_hi_u32 s24, s11, s25
	s_mul_i32 s25, s24, s16
	s_sub_i32 s11, s11, s25
	s_add_i32 s28, s24, 1
	s_sub_i32 s25, s11, s16
	s_cmp_ge_u32 s11, s16
	s_cselect_b32 s24, s28, s24
	s_cselect_b32 s11, s25, s11
	s_add_i32 s25, s24, 1
	s_cmp_ge_u32 s11, s16
	s_cselect_b32 s11, s25, s24
	s_xor_b32 s11, s11, s19
	s_sub_i32 s16, s11, s19
	s_mul_i32 s11, s16, s18
	s_sub_i32 s10, s10, s11
	s_add_i32 s17, s17, s10
	v_lshl_add_u32 v16, s17, 8, v1
	v_ashrrev_i32_e32 v17, 31, v16
	v_lshlrev_b64 v[16:17], 6, v[16:17]
	v_lshl_add_u64 v[24:25], v[4:5], 0, v[16:17]
	global_load_dwordx4 v[32:35], v[24:25], off
	global_load_dwordx4 v[36:39], v[24:25], off offset:16
	s_and_saveexec_b64 s[10:11], s[4:5]
	s_ashr_i32 s18, s17, 4
	s_lshl_b32 s16, s16, 8
	s_ashr_i32 s17, s16, 31
	s_mul_hi_i32 s19, s18, 0x5800
	s_mulk_i32 s18, 0x5800
	s_add_u32 s18, s12, s18
	s_addc_u32 s19, s13, s19
	s_lshl_b64 s[16:17], s[16:17], 2
	s_add_u32 s16, s18, s16
	s_addc_u32 s17, s19, s17
	global_load_dword v40, v12, s[16:17]
	s_or_b64 exec, exec, s[10:11]
	s_add_u32 s8, s8, s33
	s_addc_u32 s9, s9, s40
	s_add_i32 s99, s99, 1
	v_cmp_gt_i64_e32 vcc, s[8:9], v[6:7]
	s_cbranch_vccnz .Lpre5_issued
	s_ashr_i32 s10, s8, 31
	s_lshr_b32 s10, s10, 29
	s_add_i32 s10, s8, s10
	s_ashr_i32 s11, s10, 3
	s_and_b32 s10, s10, -8
	s_sub_i32 s10, s8, s10
	s_cmp_lt_i32 s10, 0
	s_cselect_b32 s16, s15, 0x160
	s_mul_i32 s10, s10, s16
	s_add_i32 s10, s10, s11
	s_mul_hi_i32 s11, s10, 0x2e8ba2e9
	s_lshr_b32 s16, s11, 31
	s_ashr_i32 s11, s11, 5
	s_add_i32 s11, s11, s16
	s_lshl_b32 s17, s11, 3
	s_sub_i32 s16, 0x80, s17
	s_min_i32 s18, s16, 8
	s_abs_i32 s16, s18
	v_cvt_f32_u32_e32 v15, s16
	s_sub_i32 s24, 0, s16
	s_mulk_i32 s11, 0xb0
	s_sub_i32 s10, s10, s11
	v_rcp_iflag_f32_e32 v15, v15
	s_abs_i32 s11, s10
	s_xor_b32 s19, s10, s18
	s_ashr_i32 s19, s19, 31
	v_mul_f32_e32 v15, 0x4f7ffffe, v15
	v_cvt_u32_f32_e32 v15, v15
	v_cmp_lt_i32_e32 vcc, v13, v14
	v_readfirstlane_b32 s25, v15
	s_mul_i32 s24, s24, s25
	s_mul_hi_u32 s24, s25, s24
	s_add_i32 s25, s25, s24
	s_mul_hi_u32 s24, s11, s25
	s_mul_i32 s25, s24, s16
	s_sub_i32 s11, s11, s25
	s_add_i32 s28, s24, 1
	s_sub_i32 s25, s11, s16
	s_cmp_ge_u32 s11, s16
	s_cselect_b32 s24, s28, s24
	s_cselect_b32 s11, s25, s11
	s_add_i32 s25, s24, 1
	s_cmp_ge_u32 s11, s16
	s_cselect_b32 s11, s25, s24
	s_xor_b32 s11, s11, s19
	s_sub_i32 s16, s11, s19
	s_mul_i32 s11, s16, s18
	s_sub_i32 s10, s10, s11
	s_add_i32 s17, s17, s10
	v_lshl_add_u32 v16, s17, 8, v1
	v_ashrrev_i32_e32 v17, 31, v16
	v_lshlrev_b64 v[16:17], 6, v[16:17]
	v_lshl_add_u64 v[24:25], v[4:5], 0, v[16:17]
	global_load_dwordx4 v[44:47], v[24:25], off
	global_load_dwordx4 v[48:51], v[24:25], off offset:16
	s_and_saveexec_b64 s[10:11], s[4:5]
	s_ashr_i32 s18, s17, 4
	s_lshl_b32 s16, s16, 8
	s_ashr_i32 s17, s16, 31
	s_mul_hi_i32 s19, s18, 0x5800
	s_mulk_i32 s18, 0x5800
	s_add_u32 s18, s12, s18
	s_addc_u32 s19, s13, s19
	s_lshl_b64 s[16:17], s[16:17], 2
	s_add_u32 s16, s18, s16
	s_addc_u32 s17, s19, s17
	global_load_dword v52, v12, s[16:17]
	s_or_b64 exec, exec, s[10:11]
	s_add_u32 s8, s8, s33
	s_addc_u32 s9, s9, s40
	s_add_i32 s99, s99, 1
	v_cmp_gt_i64_e32 vcc, s[8:9], v[6:7]
	s_cbranch_vccnz .Lpre5_issued
	s_ashr_i32 s10, s8, 31
	s_lshr_b32 s10, s10, 29
	s_add_i32 s10, s8, s10
	s_ashr_i32 s11, s10, 3
	s_and_b32 s10, s10, -8
	s_sub_i32 s10, s8, s10
	s_cmp_lt_i32 s10, 0
	s_cselect_b32 s16, s15, 0x160
	s_mul_i32 s10, s10, s16
	s_add_i32 s10, s10, s11
	s_mul_hi_i32 s11, s10, 0x2e8ba2e9
	s_lshr_b32 s16, s11, 31
	s_ashr_i32 s11, s11, 5
	s_add_i32 s11, s11, s16
	s_lshl_b32 s17, s11, 3
	s_sub_i32 s16, 0x80, s17
	s_min_i32 s18, s16, 8
	s_abs_i32 s16, s18
	v_cvt_f32_u32_e32 v15, s16
	s_sub_i32 s24, 0, s16
	s_mulk_i32 s11, 0xb0
	s_sub_i32 s10, s10, s11
	v_rcp_iflag_f32_e32 v15, v15
	s_abs_i32 s11, s10
	s_xor_b32 s19, s10, s18
	s_ashr_i32 s19, s19, 31
	v_mul_f32_e32 v15, 0x4f7ffffe, v15
	v_cvt_u32_f32_e32 v15, v15
	v_cmp_lt_i32_e32 vcc, v13, v14
	v_readfirstlane_b32 s25, v15
	s_mul_i32 s24, s24, s25
	s_mul_hi_u32 s24, s25, s24
	s_add_i32 s25, s25, s24
	s_mul_hi_u32 s24, s11, s25
	s_mul_i32 s25, s24, s16
	s_sub_i32 s11, s11, s25
	s_add_i32 s28, s24, 1
	s_sub_i32 s25, s11, s16
	s_cmp_ge_u32 s11, s16
	s_cselect_b32 s24, s28, s24
	s_cselect_b32 s11, s25, s11
	s_add_i32 s25, s24, 1
	s_cmp_ge_u32 s11, s16
	s_cselect_b32 s11, s25, s24
	s_xor_b32 s11, s11, s19
	s_sub_i32 s16, s11, s19
	s_mul_i32 s11, s16, s18
	s_sub_i32 s10, s10, s11
	s_add_i32 s17, s17, s10
	v_lshl_add_u32 v16, s17, 8, v1
	v_ashrrev_i32_e32 v17, 31, v16
	v_lshlrev_b64 v[16:17], 6, v[16:17]
	v_lshl_add_u64 v[24:25], v[4:5], 0, v[16:17]
	global_load_dwordx4 v[56:59], v[24:25], off
	global_load_dwordx4 v[60:63], v[24:25], off offset:16
	s_and_saveexec_b64 s[10:11], s[4:5]
	s_ashr_i32 s18, s17, 4
	s_lshl_b32 s16, s16, 8
	s_ashr_i32 s17, s16, 31
	s_mul_hi_i32 s19, s18, 0x5800
	s_mulk_i32 s18, 0x5800
	s_add_u32 s18, s12, s18
	s_addc_u32 s19, s13, s19
	s_lshl_b64 s[16:17], s[16:17], 2
	s_add_u32 s16, s18, s16
	s_addc_u32 s17, s19, s17
	global_load_dword v64, v12, s[16:17]
	s_or_b64 exec, exec, s[10:11]
	s_add_u32 s8, s8, s33
	s_addc_u32 s9, s9, s40
	s_add_i32 s99, s99, 1
	v_cmp_gt_i64_e32 vcc, s[8:9], v[6:7]
	s_cbranch_vccnz .Lpre5_issued
	s_ashr_i32 s10, s8, 31
	s_lshr_b32 s10, s10, 29
	s_add_i32 s10, s8, s10
	s_ashr_i32 s11, s10, 3
	s_and_b32 s10, s10, -8
	s_sub_i32 s10, s8, s10
	s_cmp_lt_i32 s10, 0
	s_cselect_b32 s16, s15, 0x160
	s_mul_i32 s10, s10, s16
	s_add_i32 s10, s10, s11
	s_mul_hi_i32 s11, s10, 0x2e8ba2e9
	s_lshr_b32 s16, s11, 31
	s_ashr_i32 s11, s11, 5
	s_add_i32 s11, s11, s16
	s_lshl_b32 s17, s11, 3
	s_sub_i32 s16, 0x80, s17
	s_min_i32 s18, s16, 8
	s_abs_i32 s16, s18
	v_cvt_f32_u32_e32 v15, s16
	s_sub_i32 s24, 0, s16
	s_mulk_i32 s11, 0xb0
	s_sub_i32 s10, s10, s11
	v_rcp_iflag_f32_e32 v15, v15
	s_abs_i32 s11, s10
	s_xor_b32 s19, s10, s18
	s_ashr_i32 s19, s19, 31
	v_mul_f32_e32 v15, 0x4f7ffffe, v15
	v_cvt_u32_f32_e32 v15, v15
	v_cmp_lt_i32_e32 vcc, v13, v14
	v_readfirstlane_b32 s25, v15
	s_mul_i32 s24, s24, s25
	s_mul_hi_u32 s24, s25, s24
	s_add_i32 s25, s25, s24
	s_mul_hi_u32 s24, s11, s25
	s_mul_i32 s25, s24, s16
	s_sub_i32 s11, s11, s25
	s_add_i32 s28, s24, 1
	s_sub_i32 s25, s11, s16
	s_cmp_ge_u32 s11, s16
	s_cselect_b32 s24, s28, s24
	s_cselect_b32 s11, s25, s11
	s_add_i32 s25, s24, 1
	s_cmp_ge_u32 s11, s16
	s_cselect_b32 s11, s25, s24
	s_xor_b32 s11, s11, s19
	s_sub_i32 s16, s11, s19
	s_mul_i32 s11, s16, s18
	s_sub_i32 s10, s10, s11
	s_add_i32 s17, s17, s10
	v_lshl_add_u32 v16, s17, 8, v1
	v_ashrrev_i32_e32 v17, 31, v16
	v_lshlrev_b64 v[16:17], 6, v[16:17]
	v_lshl_add_u64 v[24:25], v[4:5], 0, v[16:17]
	global_load_dwordx4 v[68:71], v[24:25], off
	global_load_dwordx4 v[72:75], v[24:25], off offset:16
	s_and_saveexec_b64 s[10:11], s[4:5]
	s_ashr_i32 s18, s17, 4
	s_lshl_b32 s16, s16, 8
	s_ashr_i32 s17, s16, 31
	s_mul_hi_i32 s19, s18, 0x5800
	s_mulk_i32 s18, 0x5800
	s_add_u32 s18, s12, s18
	s_addc_u32 s19, s13, s19
	s_lshl_b64 s[16:17], s[16:17], 2
	s_add_u32 s16, s18, s16
	s_addc_u32 s17, s19, s17
	global_load_dword v76, v12, s[16:17]
	s_or_b64 exec, exec, s[10:11]
	s_add_u32 s8, s8, s33
	s_addc_u32 s9, s9, s40
	s_add_i32 s99, s99, 1
	v_cmp_gt_i64_e32 vcc, s[8:9], v[6:7]
	s_cbranch_vccnz .Lpre5_issued
	s_ashr_i32 s10, s8, 31
	s_lshr_b32 s10, s10, 29
	s_add_i32 s10, s8, s10
	s_ashr_i32 s11, s10, 3
	s_and_b32 s10, s10, -8
	s_sub_i32 s10, s8, s10
	s_cmp_lt_i32 s10, 0
	s_cselect_b32 s16, s15, 0x160
	s_mul_i32 s10, s10, s16
	s_add_i32 s10, s10, s11
	s_mul_hi_i32 s11, s10, 0x2e8ba2e9
	s_lshr_b32 s16, s11, 31
	s_ashr_i32 s11, s11, 5
	s_add_i32 s11, s11, s16
	s_lshl_b32 s17, s11, 3
	s_sub_i32 s16, 0x80, s17
	s_min_i32 s18, s16, 8
	s_abs_i32 s16, s18
	v_cvt_f32_u32_e32 v15, s16
	s_sub_i32 s24, 0, s16
	s_mulk_i32 s11, 0xb0
	s_sub_i32 s10, s10, s11
	v_rcp_iflag_f32_e32 v15, v15
	s_abs_i32 s11, s10
	s_xor_b32 s19, s10, s18
	s_ashr_i32 s19, s19, 31
	v_mul_f32_e32 v15, 0x4f7ffffe, v15
	v_cvt_u32_f32_e32 v15, v15
	v_cmp_lt_i32_e32 vcc, v13, v14
	v_readfirstlane_b32 s25, v15
	s_mul_i32 s24, s24, s25
	s_mul_hi_u32 s24, s25, s24
	s_add_i32 s25, s25, s24
	s_mul_hi_u32 s24, s11, s25
	s_mul_i32 s25, s24, s16
	s_sub_i32 s11, s11, s25
	s_add_i32 s28, s24, 1
	s_sub_i32 s25, s11, s16
	s_cmp_ge_u32 s11, s16
	s_cselect_b32 s24, s28, s24
	s_cselect_b32 s11, s25, s11
	s_add_i32 s25, s24, 1
	s_cmp_ge_u32 s11, s16
	s_cselect_b32 s11, s25, s24
	s_xor_b32 s11, s11, s19
	s_sub_i32 s16, s11, s19
	s_mul_i32 s11, s16, s18
	s_sub_i32 s10, s10, s11
	s_add_i32 s17, s17, s10
	v_lshl_add_u32 v16, s17, 8, v1
	v_ashrrev_i32_e32 v17, 31, v16
	v_lshlrev_b64 v[16:17], 6, v[16:17]
	v_lshl_add_u64 v[24:25], v[4:5], 0, v[16:17]
	global_load_dwordx4 v[80:83], v[24:25], off
	global_load_dwordx4 v[84:87], v[24:25], off offset:16
	s_and_saveexec_b64 s[10:11], s[4:5]
	s_ashr_i32 s18, s17, 4
	s_lshl_b32 s16, s16, 8
	s_ashr_i32 s17, s16, 31
	s_mul_hi_i32 s19, s18, 0x5800
	s_mulk_i32 s18, 0x5800
	s_add_u32 s18, s12, s18
	s_addc_u32 s19, s13, s19
	s_lshl_b64 s[16:17], s[16:17], 2
	s_add_u32 s16, s18, s16
	s_addc_u32 s17, s19, s17
	global_load_dword v88, v12, s[16:17]
	s_or_b64 exec, exec, s[10:11]
	s_add_u32 s8, s8, s33
	s_addc_u32 s9, s9, s40
	s_add_i32 s99, s99, 1
	v_cmp_gt_i64_e32 vcc, s[8:9], v[6:7]
	s_cbranch_vccnz .Lpre5_issued
	s_ashr_i32 s10, s8, 31
	s_lshr_b32 s10, s10, 29
	s_add_i32 s10, s8, s10
	s_ashr_i32 s11, s10, 3
	s_and_b32 s10, s10, -8
	s_sub_i32 s10, s8, s10
	s_cmp_lt_i32 s10, 0
	s_cselect_b32 s16, s15, 0x160
	s_mul_i32 s10, s10, s16
	s_add_i32 s10, s10, s11
	s_mul_hi_i32 s11, s10, 0x2e8ba2e9
	s_lshr_b32 s16, s11, 31
	s_ashr_i32 s11, s11, 5
	s_add_i32 s11, s11, s16
	s_lshl_b32 s17, s11, 3
	s_sub_i32 s16, 0x80, s17
	s_min_i32 s18, s16, 8
	s_abs_i32 s16, s18
	v_cvt_f32_u32_e32 v15, s16
	s_sub_i32 s24, 0, s16
	s_mulk_i32 s11, 0xb0
	s_sub_i32 s10, s10, s11
	v_rcp_iflag_f32_e32 v15, v15
	s_abs_i32 s11, s10
	s_xor_b32 s19, s10, s18
	s_ashr_i32 s19, s19, 31
	v_mul_f32_e32 v15, 0x4f7ffffe, v15
	v_cvt_u32_f32_e32 v15, v15
	v_cmp_lt_i32_e32 vcc, v13, v14
	v_readfirstlane_b32 s25, v15
	s_mul_i32 s24, s24, s25
	s_mul_hi_u32 s24, s25, s24
	s_add_i32 s25, s25, s24
	s_mul_hi_u32 s24, s11, s25
	s_mul_i32 s25, s24, s16
	s_sub_i32 s11, s11, s25
	s_add_i32 s28, s24, 1
	s_sub_i32 s25, s11, s16
	s_cmp_ge_u32 s11, s16
	s_cselect_b32 s24, s28, s24
	s_cselect_b32 s11, s25, s11
	s_add_i32 s25, s24, 1
	s_cmp_ge_u32 s11, s16
	s_cselect_b32 s11, s25, s24
	s_xor_b32 s11, s11, s19
	s_sub_i32 s16, s11, s19
	s_mul_i32 s11, s16, s18
	s_sub_i32 s10, s10, s11
	s_add_i32 s17, s17, s10
	v_lshl_add_u32 v16, s17, 8, v1
	v_ashrrev_i32_e32 v17, 31, v16
	v_lshlrev_b64 v[16:17], 6, v[16:17]
	v_lshl_add_u64 v[24:25], v[4:5], 0, v[16:17]
	global_load_dwordx4 v[92:95], v[24:25], off
	global_load_dwordx4 v[96:99], v[24:25], off offset:16
	s_and_saveexec_b64 s[10:11], s[4:5]
	s_ashr_i32 s18, s17, 4
	s_lshl_b32 s16, s16, 8
	s_ashr_i32 s17, s16, 31
	s_mul_hi_i32 s19, s18, 0x5800
	s_mulk_i32 s18, 0x5800
	s_add_u32 s18, s12, s18
	s_addc_u32 s19, s13, s19
	s_lshl_b64 s[16:17], s[16:17], 2
	s_add_u32 s16, s18, s16
	s_addc_u32 s17, s19, s17
	global_load_dword v100, v12, s[16:17]
	s_or_b64 exec, exec, s[10:11]
	s_add_u32 s8, s8, s33
	s_addc_u32 s9, s9, s40
	s_add_i32 s99, s99, 1
	v_cmp_gt_i64_e32 vcc, s[8:9], v[6:7]
	s_cbranch_vccnz .Lpre5_issued
	s_ashr_i32 s10, s8, 31
	s_lshr_b32 s10, s10, 29
	s_add_i32 s10, s8, s10
	s_ashr_i32 s11, s10, 3
	s_and_b32 s10, s10, -8
	s_sub_i32 s10, s8, s10
	s_cmp_lt_i32 s10, 0
	s_cselect_b32 s16, s15, 0x160
	s_mul_i32 s10, s10, s16
	s_add_i32 s10, s10, s11
	s_mul_hi_i32 s11, s10, 0x2e8ba2e9
	s_lshr_b32 s16, s11, 31
	s_ashr_i32 s11, s11, 5
	s_add_i32 s11, s11, s16
	s_lshl_b32 s17, s11, 3
	s_sub_i32 s16, 0x80, s17
	s_min_i32 s18, s16, 8
	s_abs_i32 s16, s18
	v_cvt_f32_u32_e32 v15, s16
	s_sub_i32 s24, 0, s16
	s_mulk_i32 s11, 0xb0
	s_sub_i32 s10, s10, s11
	v_rcp_iflag_f32_e32 v15, v15
	s_abs_i32 s11, s10
	s_xor_b32 s19, s10, s18
	s_ashr_i32 s19, s19, 31
	v_mul_f32_e32 v15, 0x4f7ffffe, v15
	v_cvt_u32_f32_e32 v15, v15
	v_cmp_lt_i32_e32 vcc, v13, v14
	v_readfirstlane_b32 s25, v15
	s_mul_i32 s24, s24, s25
	s_mul_hi_u32 s24, s25, s24
	s_add_i32 s25, s25, s24
	s_mul_hi_u32 s24, s11, s25
	s_mul_i32 s25, s24, s16
	s_sub_i32 s11, s11, s25
	s_add_i32 s28, s24, 1
	s_sub_i32 s25, s11, s16
	s_cmp_ge_u32 s11, s16
	s_cselect_b32 s24, s28, s24
	s_cselect_b32 s11, s25, s11
	s_add_i32 s25, s24, 1
	s_cmp_ge_u32 s11, s16
	s_cselect_b32 s11, s25, s24
	s_xor_b32 s11, s11, s19
	s_sub_i32 s16, s11, s19
	s_mul_i32 s11, s16, s18
	s_sub_i32 s10, s10, s11
	s_add_i32 s17, s17, s10
	v_lshl_add_u32 v16, s17, 8, v1
	v_ashrrev_i32_e32 v17, 31, v16
	v_lshlrev_b64 v[16:17], 6, v[16:17]
	v_lshl_add_u64 v[24:25], v[4:5], 0, v[16:17]
	global_load_dwordx4 v[104:107], v[24:25], off
	global_load_dwordx4 v[108:111], v[24:25], off offset:16
	s_and_saveexec_b64 s[10:11], s[4:5]
	s_ashr_i32 s18, s17, 4
	s_lshl_b32 s16, s16, 8
	s_ashr_i32 s17, s16, 31
	s_mul_hi_i32 s19, s18, 0x5800
	s_mulk_i32 s18, 0x5800
	s_add_u32 s18, s12, s18
	s_addc_u32 s19, s13, s19
	s_lshl_b64 s[16:17], s[16:17], 2
	s_add_u32 s16, s18, s16
	s_addc_u32 s17, s19, s17
	global_load_dword v112, v12, s[16:17]
	s_or_b64 exec, exec, s[10:11]
	s_add_u32 s8, s8, s33
	s_addc_u32 s9, s9, s40
	s_add_i32 s99, s99, 1
	v_cmp_gt_i64_e32 vcc, s[8:9], v[6:7]
	s_cbranch_vccnz .Lpre5_issued
	s_ashr_i32 s10, s8, 31
	s_lshr_b32 s10, s10, 29
	s_add_i32 s10, s8, s10
	s_ashr_i32 s11, s10, 3
	s_and_b32 s10, s10, -8
	s_sub_i32 s10, s8, s10
	s_cmp_lt_i32 s10, 0
	s_cselect_b32 s16, s15, 0x160
	s_mul_i32 s10, s10, s16
	s_add_i32 s10, s10, s11
	s_mul_hi_i32 s11, s10, 0x2e8ba2e9
	s_lshr_b32 s16, s11, 31
	s_ashr_i32 s11, s11, 5
	s_add_i32 s11, s11, s16
	s_lshl_b32 s17, s11, 3
	s_sub_i32 s16, 0x80, s17
	s_min_i32 s18, s16, 8
	s_abs_i32 s16, s18
	v_cvt_f32_u32_e32 v15, s16
	s_sub_i32 s24, 0, s16
	s_mulk_i32 s11, 0xb0
	s_sub_i32 s10, s10, s11
	v_rcp_iflag_f32_e32 v15, v15
	s_abs_i32 s11, s10
	s_xor_b32 s19, s10, s18
	s_ashr_i32 s19, s19, 31
	v_mul_f32_e32 v15, 0x4f7ffffe, v15
	v_cvt_u32_f32_e32 v15, v15
	v_cmp_lt_i32_e32 vcc, v13, v14
	v_readfirstlane_b32 s25, v15
	s_mul_i32 s24, s24, s25
	s_mul_hi_u32 s24, s25, s24
	s_add_i32 s25, s25, s24
	s_mul_hi_u32 s24, s11, s25
	s_mul_i32 s25, s24, s16
	s_sub_i32 s11, s11, s25
	s_add_i32 s28, s24, 1
	s_sub_i32 s25, s11, s16
	s_cmp_ge_u32 s11, s16
	s_cselect_b32 s24, s28, s24
	s_cselect_b32 s11, s25, s11
	s_add_i32 s25, s24, 1
	s_cmp_ge_u32 s11, s16
	s_cselect_b32 s11, s25, s24
	s_xor_b32 s11, s11, s19
	s_sub_i32 s16, s11, s19
	s_mul_i32 s11, s16, s18
	s_sub_i32 s10, s10, s11
	s_add_i32 s17, s17, s10
	v_lshl_add_u32 v16, s17, 8, v1
	v_ashrrev_i32_e32 v17, 31, v16
	v_lshlrev_b64 v[16:17], 6, v[16:17]
	v_lshl_add_u64 v[24:25], v[4:5], 0, v[16:17]
	global_load_dwordx4 v[116:119], v[24:25], off
	global_load_dwordx4 v[120:123], v[24:25], off offset:16
	s_and_saveexec_b64 s[10:11], s[4:5]
	s_ashr_i32 s18, s17, 4
	s_lshl_b32 s16, s16, 8
	s_ashr_i32 s17, s16, 31
	s_mul_hi_i32 s19, s18, 0x5800
	s_mulk_i32 s18, 0x5800
	s_add_u32 s18, s12, s18
	s_addc_u32 s19, s13, s19
	s_lshl_b64 s[16:17], s[16:17], 2
	s_add_u32 s16, s18, s16
	s_addc_u32 s17, s19, s17
	global_load_dword v124, v12, s[16:17]
	s_or_b64 exec, exec, s[10:11]
	s_add_u32 s8, s8, s33
	s_addc_u32 s9, s9, s40
	s_add_i32 s99, s99, 1
	v_cmp_gt_i64_e32 vcc, s[8:9], v[6:7]
	s_cbranch_vccnz .Lpre5_issued
	s_ashr_i32 s10, s8, 31
	s_lshr_b32 s10, s10, 29
	s_add_i32 s10, s8, s10
	s_ashr_i32 s11, s10, 3
	s_and_b32 s10, s10, -8
	s_sub_i32 s10, s8, s10
	s_cmp_lt_i32 s10, 0
	s_cselect_b32 s16, s15, 0x160
	s_mul_i32 s10, s10, s16
	s_add_i32 s10, s10, s11
	s_mul_hi_i32 s11, s10, 0x2e8ba2e9
	s_lshr_b32 s16, s11, 31
	s_ashr_i32 s11, s11, 5
	s_add_i32 s11, s11, s16
	s_lshl_b32 s17, s11, 3
	s_sub_i32 s16, 0x80, s17
	s_min_i32 s18, s16, 8
	s_abs_i32 s16, s18
	v_cvt_f32_u32_e32 v15, s16
	s_sub_i32 s24, 0, s16
	s_mulk_i32 s11, 0xb0
	s_sub_i32 s10, s10, s11
	v_rcp_iflag_f32_e32 v15, v15
	s_abs_i32 s11, s10
	s_xor_b32 s19, s10, s18
	s_ashr_i32 s19, s19, 31
	v_mul_f32_e32 v15, 0x4f7ffffe, v15
	v_cvt_u32_f32_e32 v15, v15
	v_cmp_lt_i32_e32 vcc, v13, v14
	v_readfirstlane_b32 s25, v15
	s_mul_i32 s24, s24, s25
	s_mul_hi_u32 s24, s25, s24
	s_add_i32 s25, s25, s24
	s_mul_hi_u32 s24, s11, s25
	s_mul_i32 s25, s24, s16
	s_sub_i32 s11, s11, s25
	s_add_i32 s28, s24, 1
	s_sub_i32 s25, s11, s16
	s_cmp_ge_u32 s11, s16
	s_cselect_b32 s24, s28, s24
	s_cselect_b32 s11, s25, s11
	s_add_i32 s25, s24, 1
	s_cmp_ge_u32 s11, s16
	s_cselect_b32 s11, s25, s24
	s_xor_b32 s11, s11, s19
	s_sub_i32 s16, s11, s19
	s_mul_i32 s11, s16, s18
	s_sub_i32 s10, s10, s11
	s_add_i32 s17, s17, s10
	v_lshl_add_u32 v16, s17, 8, v1
	v_ashrrev_i32_e32 v17, 31, v16
	v_lshlrev_b64 v[16:17], 6, v[16:17]
	v_lshl_add_u64 v[24:25], v[4:5], 0, v[16:17]
	global_load_dwordx4 v[128:131], v[24:25], off
	global_load_dwordx4 v[132:135], v[24:25], off offset:16
	s_and_saveexec_b64 s[10:11], s[4:5]
	s_ashr_i32 s18, s17, 4
	s_lshl_b32 s16, s16, 8
	s_ashr_i32 s17, s16, 31
	s_mul_hi_i32 s19, s18, 0x5800
	s_mulk_i32 s18, 0x5800
	s_add_u32 s18, s12, s18
	s_addc_u32 s19, s13, s19
	s_lshl_b64 s[16:17], s[16:17], 2
	s_add_u32 s16, s18, s16
	s_addc_u32 s17, s19, s17
	global_load_dword v136, v12, s[16:17]
	s_or_b64 exec, exec, s[10:11]
	s_add_u32 s8, s8, s33
	s_addc_u32 s9, s9, s40
	s_add_i32 s99, s99, 1
	v_cmp_gt_i64_e32 vcc, s[8:9], v[6:7]
	s_cbranch_vccnz .Lpre5_issued
	s_ashr_i32 s10, s8, 31
	s_lshr_b32 s10, s10, 29
	s_add_i32 s10, s8, s10
	s_ashr_i32 s11, s10, 3
	s_and_b32 s10, s10, -8
	s_sub_i32 s10, s8, s10
	s_cmp_lt_i32 s10, 0
	s_cselect_b32 s16, s15, 0x160
	s_mul_i32 s10, s10, s16
	s_add_i32 s10, s10, s11
	s_mul_hi_i32 s11, s10, 0x2e8ba2e9
	s_lshr_b32 s16, s11, 31
	s_ashr_i32 s11, s11, 5
	s_add_i32 s11, s11, s16
	s_lshl_b32 s17, s11, 3
	s_sub_i32 s16, 0x80, s17
	s_min_i32 s18, s16, 8
	s_abs_i32 s16, s18
	v_cvt_f32_u32_e32 v15, s16
	s_sub_i32 s24, 0, s16
	s_mulk_i32 s11, 0xb0
	s_sub_i32 s10, s10, s11
	v_rcp_iflag_f32_e32 v15, v15
	s_abs_i32 s11, s10
	s_xor_b32 s19, s10, s18
	s_ashr_i32 s19, s19, 31
	v_mul_f32_e32 v15, 0x4f7ffffe, v15
	v_cvt_u32_f32_e32 v15, v15
	v_cmp_lt_i32_e32 vcc, v13, v14
	v_readfirstlane_b32 s25, v15
	s_mul_i32 s24, s24, s25
	s_mul_hi_u32 s24, s25, s24
	s_add_i32 s25, s25, s24
	s_mul_hi_u32 s24, s11, s25
	s_mul_i32 s25, s24, s16
	s_sub_i32 s11, s11, s25
	s_add_i32 s28, s24, 1
	s_sub_i32 s25, s11, s16
	s_cmp_ge_u32 s11, s16
	s_cselect_b32 s24, s28, s24
	s_cselect_b32 s11, s25, s11
	s_add_i32 s25, s24, 1
	s_cmp_ge_u32 s11, s16
	s_cselect_b32 s11, s25, s24
	s_xor_b32 s11, s11, s19
	s_sub_i32 s16, s11, s19
	s_mul_i32 s11, s16, s18
	s_sub_i32 s10, s10, s11
	s_add_i32 s17, s17, s10
	v_lshl_add_u32 v16, s17, 8, v1
	v_ashrrev_i32_e32 v17, 31, v16
	v_lshlrev_b64 v[16:17], 6, v[16:17]
	v_lshl_add_u64 v[24:25], v[4:5], 0, v[16:17]
	global_load_dwordx4 v[140:143], v[24:25], off
	global_load_dwordx4 v[144:147], v[24:25], off offset:16
	s_and_saveexec_b64 s[10:11], s[4:5]
	s_ashr_i32 s18, s17, 4
	s_lshl_b32 s16, s16, 8
	s_ashr_i32 s17, s16, 31
	s_mul_hi_i32 s19, s18, 0x5800
	s_mulk_i32 s18, 0x5800
	s_add_u32 s18, s12, s18
	s_addc_u32 s19, s13, s19
	s_lshl_b64 s[16:17], s[16:17], 2
	s_add_u32 s16, s18, s16
	s_addc_u32 s17, s19, s17
	global_load_dword v148, v12, s[16:17]
	s_or_b64 exec, exec, s[10:11]
	s_add_u32 s8, s8, s33
	s_addc_u32 s9, s9, s40
	s_add_i32 s99, s99, 1
	v_cmp_gt_i64_e32 vcc, s[8:9], v[6:7]
	s_cbranch_vccnz .Lpre5_issued
	s_ashr_i32 s10, s8, 31
	s_lshr_b32 s10, s10, 29
	s_add_i32 s10, s8, s10
	s_ashr_i32 s11, s10, 3
	s_and_b32 s10, s10, -8
	s_sub_i32 s10, s8, s10
	s_cmp_lt_i32 s10, 0
	s_cselect_b32 s16, s15, 0x160
	s_mul_i32 s10, s10, s16
	s_add_i32 s10, s10, s11
	s_mul_hi_i32 s11, s10, 0x2e8ba2e9
	s_lshr_b32 s16, s11, 31
	s_ashr_i32 s11, s11, 5
	s_add_i32 s11, s11, s16
	s_lshl_b32 s17, s11, 3
	s_sub_i32 s16, 0x80, s17
	s_min_i32 s18, s16, 8
	s_abs_i32 s16, s18
	v_cvt_f32_u32_e32 v15, s16
	s_sub_i32 s24, 0, s16
	s_mulk_i32 s11, 0xb0
	s_sub_i32 s10, s10, s11
	v_rcp_iflag_f32_e32 v15, v15
	s_abs_i32 s11, s10
	s_xor_b32 s19, s10, s18
	s_ashr_i32 s19, s19, 31
	v_mul_f32_e32 v15, 0x4f7ffffe, v15
	v_cvt_u32_f32_e32 v15, v15
	v_cmp_lt_i32_e32 vcc, v13, v14
	v_readfirstlane_b32 s25, v15
	s_mul_i32 s24, s24, s25
	s_mul_hi_u32 s24, s25, s24
	s_add_i32 s25, s25, s24
	s_mul_hi_u32 s24, s11, s25
	s_mul_i32 s25, s24, s16
	s_sub_i32 s11, s11, s25
	s_add_i32 s28, s24, 1
	s_sub_i32 s25, s11, s16
	s_cmp_ge_u32 s11, s16
	s_cselect_b32 s24, s28, s24
	s_cselect_b32 s11, s25, s11
	s_add_i32 s25, s24, 1
	s_cmp_ge_u32 s11, s16
	s_cselect_b32 s11, s25, s24
	s_xor_b32 s11, s11, s19
	s_sub_i32 s16, s11, s19
	s_mul_i32 s11, s16, s18
	s_sub_i32 s10, s10, s11
	s_add_i32 s17, s17, s10
	v_lshl_add_u32 v16, s17, 8, v1
	v_ashrrev_i32_e32 v17, 31, v16
	v_lshlrev_b64 v[16:17], 6, v[16:17]
	v_lshl_add_u64 v[24:25], v[4:5], 0, v[16:17]
	global_load_dwordx4 v[152:155], v[24:25], off
	global_load_dwordx4 v[156:159], v[24:25], off offset:16
	s_and_saveexec_b64 s[10:11], s[4:5]
	s_ashr_i32 s18, s17, 4
	s_lshl_b32 s16, s16, 8
	s_ashr_i32 s17, s16, 31
	s_mul_hi_i32 s19, s18, 0x5800
	s_mulk_i32 s18, 0x5800
	s_add_u32 s18, s12, s18
	s_addc_u32 s19, s13, s19
	s_lshl_b64 s[16:17], s[16:17], 2
	s_add_u32 s16, s18, s16
	s_addc_u32 s17, s19, s17
	global_load_dword v160, v12, s[16:17]
	s_or_b64 exec, exec, s[10:11]
	s_add_u32 s8, s8, s33
	s_addc_u32 s9, s9, s40
	s_add_i32 s99, s99, 1
	v_cmp_gt_i64_e32 vcc, s[8:9], v[6:7]
	s_cbranch_vccnz .Lpre5_issued
	s_ashr_i32 s10, s8, 31
	s_lshr_b32 s10, s10, 29
	s_add_i32 s10, s8, s10
	s_ashr_i32 s11, s10, 3
	s_and_b32 s10, s10, -8
	s_sub_i32 s10, s8, s10
	s_cmp_lt_i32 s10, 0
	s_cselect_b32 s16, s15, 0x160
	s_mul_i32 s10, s10, s16
	s_add_i32 s10, s10, s11
	s_mul_hi_i32 s11, s10, 0x2e8ba2e9
	s_lshr_b32 s16, s11, 31
	s_ashr_i32 s11, s11, 5
	s_add_i32 s11, s11, s16
	s_lshl_b32 s17, s11, 3
	s_sub_i32 s16, 0x80, s17
	s_min_i32 s18, s16, 8
	s_abs_i32 s16, s18
	v_cvt_f32_u32_e32 v15, s16
	s_sub_i32 s24, 0, s16
	s_mulk_i32 s11, 0xb0
	s_sub_i32 s10, s10, s11
	v_rcp_iflag_f32_e32 v15, v15
	s_abs_i32 s11, s10
	s_xor_b32 s19, s10, s18
	s_ashr_i32 s19, s19, 31
	v_mul_f32_e32 v15, 0x4f7ffffe, v15
	v_cvt_u32_f32_e32 v15, v15
	v_cmp_lt_i32_e32 vcc, v13, v14
	v_readfirstlane_b32 s25, v15
	s_mul_i32 s24, s24, s25
	s_mul_hi_u32 s24, s25, s24
	s_add_i32 s25, s25, s24
	s_mul_hi_u32 s24, s11, s25
	s_mul_i32 s25, s24, s16
	s_sub_i32 s11, s11, s25
	s_add_i32 s28, s24, 1
	s_sub_i32 s25, s11, s16
	s_cmp_ge_u32 s11, s16
	s_cselect_b32 s24, s28, s24
	s_cselect_b32 s11, s25, s11
	s_add_i32 s25, s24, 1
	s_cmp_ge_u32 s11, s16
	s_cselect_b32 s11, s25, s24
	s_xor_b32 s11, s11, s19
	s_sub_i32 s16, s11, s19
	s_mul_i32 s11, s16, s18
	s_sub_i32 s10, s10, s11
	s_add_i32 s17, s17, s10
	v_lshl_add_u32 v16, s17, 8, v1
	v_ashrrev_i32_e32 v17, 31, v16
	v_lshlrev_b64 v[16:17], 6, v[16:17]
	v_lshl_add_u64 v[24:25], v[4:5], 0, v[16:17]
	global_load_dwordx4 v[164:167], v[24:25], off
	global_load_dwordx4 v[168:171], v[24:25], off offset:16
	s_and_saveexec_b64 s[10:11], s[4:5]
	s_ashr_i32 s18, s17, 4
	s_lshl_b32 s16, s16, 8
	s_ashr_i32 s17, s16, 31
	s_mul_hi_i32 s19, s18, 0x5800
	s_mulk_i32 s18, 0x5800
	s_add_u32 s18, s12, s18
	s_addc_u32 s19, s13, s19
	s_lshl_b64 s[16:17], s[16:17], 2
	s_add_u32 s16, s18, s16
	s_addc_u32 s17, s19, s17
	global_load_dword v172, v12, s[16:17]
	s_or_b64 exec, exec, s[10:11]
	s_add_u32 s8, s8, s33
	s_addc_u32 s9, s9, s40
	s_add_i32 s99, s99, 1
.Lpre5_issued:
	s_waitcnt vmcnt(0)
	v_cmp_lt_i32_e32 vcc, v13, v14
	s_nop 1
	v_cndmask_b32_e32 v24, v11, v13, vcc
	v_lshlrev_b32_e32 v24, 2, v24
	s_cmp_le_u32 s99, 0
	s_cbranch_scc1 .Lpre5_red
	v_add_f32_e32 v41, v32, v33
	v_add_f32_e32 v42, v34, v35
	v_add_f32_e32 v43, v36, v37
	v_add_f32_e32 v32, v38, v39
	v_add_f32_e32 v41, v41, v42
	v_add_f32_e32 v42, v43, v32
	v_add_f32_e32 v41, v41, v42
	ds_bpermute_b32 v42, v24, v41
	s_cmp_le_u32 s99, 1
	s_cbranch_scc1 .Lpre5_red
	v_add_f32_e32 v53, v44, v45
	v_add_f32_e32 v54, v46, v47
	v_add_f32_e32 v55, v48, v49
	v_add_f32_e32 v44, v50, v51
	v_add_f32_e32 v53, v53, v54
	v_add_f32_e32 v54, v55, v44
	v_add_f32_e32 v53, v53, v54
	ds_bpermute_b32 v54, v24, v53
	s_cmp_le_u32 s99, 2
	s_cbranch_scc1 .Lpre5_red
	v_add_f32_e32 v65, v56, v57
	v_add_f32_e32 v66, v58, v59
	v_add_f32_e32 v67, v60, v61
	v_add_f32_e32 v56, v62, v63
	v_add_f32_e32 v65, v65, v66
	v_add_f32_e32 v66, v67, v56
	v_add_f32_e32 v65, v65, v66
	ds_bpermute_b32 v66, v24, v65
	s_cmp_le_u32 s99, 3
	s_cbranch_scc1 .Lpre5_red
	v_add_f32_e32 v77, v68, v69
	v_add_f32_e32 v78, v70, v71
	v_add_f32_e32 v79, v72, v73
	v_add_f32_e32 v68, v74, v75
	v_add_f32_e32 v77, v77, v78
	v_add_f32_e32 v78, v79, v68
	v_add_f32_e32 v77, v77, v78
	ds_bpermute_b32 v78, v24, v77
	s_cmp_le_u32 s99, 4
	s_cbranch_scc1 .Lpre5_red
	v_add_f32_e32 v89, v80, v81
	v_add_f32_e32 v90, v82, v83
	v_add_f32_e32 v91, v84, v85
	v_add_f32_e32 v80, v86, v87
	v_add_f32_e32 v89, v89, v90
	v_add_f32_e32 v90, v91, v80
	v_add_f32_e32 v89, v89, v90
	ds_bpermute_b32 v90, v24, v89
	s_cmp_le_u32 s99, 5
	s_cbranch_scc1 .Lpre5_red
	v_add_f32_e32 v101, v92, v93
	v_add_f32_e32 v102, v94, v95
	v_add_f32_e32 v103, v96, v97
	v_add_f32_e32 v92, v98, v99
	v_add_f32_e32 v101, v101, v102
	v_add_f32_e32 v102, v103, v92
	v_add_f32_e32 v101, v101, v102
	ds_bpermute_b32 v102, v24, v101
	s_cmp_le_u32 s99, 6
	s_cbranch_scc1 .Lpre5_red
	v_add_f32_e32 v113, v104, v105
	v_add_f32_e32 v114, v106, v107
	v_add_f32_e32 v115, v108, v109
	v_add_f32_e32 v104, v110, v111
	v_add_f32_e32 v113, v113, v114
	v_add_f32_e32 v114, v115, v104
	v_add_f32_e32 v113, v113, v114
	ds_bpermute_b32 v114, v24, v113
	s_cmp_le_u32 s99, 7
	s_cbranch_scc1 .Lpre5_red
	v_add_f32_e32 v125, v116, v117
	v_add_f32_e32 v126, v118, v119
	v_add_f32_e32 v127, v120, v121
	v_add_f32_e32 v116, v122, v123
	v_add_f32_e32 v125, v125, v126
	v_add_f32_e32 v126, v127, v116
	v_add_f32_e32 v125, v125, v126
	ds_bpermute_b32 v126, v24, v125
	s_cmp_le_u32 s99, 8
	s_cbranch_scc1 .Lpre5_red
	v_add_f32_e32 v137, v128, v129
	v_add_f32_e32 v138, v130, v131
	v_add_f32_e32 v139, v132, v133
	v_add_f32_e32 v128, v134, v135
	v_add_f32_e32 v137, v137, v138
	v_add_f32_e32 v138, v139, v128
	v_add_f32_e32 v137, v137, v138
	ds_bpermute_b32 v138, v24, v137
	s_cmp_le_u32 s99, 9
	s_cbranch_scc1 .Lpre5_red
	v_add_f32_e32 v149, v140, v141
	v_add_f32_e32 v150, v142, v143
	v_add_f32_e32 v151, v144, v145
	v_add_f32_e32 v140, v146, v147
	v_add_f32_e32 v149, v149, v150
	v_add_f32_e32 v150, v151, v140
	v_add_f32_e32 v149, v149, v150
	ds_bpermute_b32 v150, v24, v149
	s_cmp_le_u32 s99, 10
	s_cbranch_scc1 .Lpre5_red
	v_add_f32_e32 v161, v152, v153
	v_add_f32_e32 v162, v154, v155
	v_add_f32_e32 v163, v156, v157
	v_add_f32_e32 v152, v158, v159
	v_add_f32_e32 v161, v161, v162
	v_add_f32_e32 v162, v163, v152
	v_add_f32_e32 v161, v161, v162
	ds_bpermute_b32 v162, v24, v161
	s_cmp_le_u32 s99, 11
	s_cbranch_scc1 .Lpre5_red
	v_add_f32_e32 v173, v164, v165
	v_add_f32_e32 v174, v166, v167
	v_add_f32_e32 v175, v168, v169
	v_add_f32_e32 v164, v170, v171
	v_add_f32_e32 v173, v173, v174
	v_add_f32_e32 v174, v175, v164
	v_add_f32_e32 v173, v173, v174
	ds_bpermute_b32 v174, v24, v173
.Lpre5_red:
	s_waitcnt lgkmcnt(0)
	s_cmp_le_u32 s99, 0
	s_cbranch_scc1 .Lpre5_done
	s_and_saveexec_b64 s[10:11], s[0:1]
	v_add_f32_e32 v41, v41, v42
	v_fmamk_f32 v41, v41, 0x3a800000, v10
	v_rsq_f32_e32 v41, v41
	s_nop 0
	ds_write_b32 v8, v41 offset:0
	s_or_b64 exec, exec, s[10:11]
	s_and_saveexec_b64 s[10:11], s[4:5]
	ds_write_b32 v9, v40 offset:0
	s_or_b64 exec, exec, s[10:11]
	s_cmp_le_u32 s99, 1
	s_cbranch_scc1 .Lpre5_done
	s_and_saveexec_b64 s[10:11], s[0:1]
	v_add_f32_e32 v53, v53, v54
	v_fmamk_f32 v53, v53, 0x3a800000, v10
	v_rsq_f32_e32 v53, v53
	s_nop 0
	ds_write_b32 v8, v53 offset:1024
	s_or_b64 exec, exec, s[10:11]
	s_and_saveexec_b64 s[10:11], s[4:5]
	ds_write_b32 v9, v52 offset:1024
	s_or_b64 exec, exec, s[10:11]
	s_cmp_le_u32 s99, 2
	s_cbranch_scc1 .Lpre5_done
	s_and_saveexec_b64 s[10:11], s[0:1]
	v_add_f32_e32 v65, v65, v66
	v_fmamk_f32 v65, v65, 0x3a800000, v10
	v_rsq_f32_e32 v65, v65
	s_nop 0
	ds_write_b32 v8, v65 offset:2048
	s_or_b64 exec, exec, s[10:11]
	s_and_saveexec_b64 s[10:11], s[4:5]
	ds_write_b32 v9, v64 offset:2048
	s_or_b64 exec, exec, s[10:11]
	s_cmp_le_u32 s99, 3
	s_cbranch_scc1 .Lpre5_done
	s_and_saveexec_b64 s[10:11], s[0:1]
	v_add_f32_e32 v77, v77, v78
	v_fmamk_f32 v77, v77, 0x3a800000, v10
	v_rsq_f32_e32 v77, v77
	s_nop 0
	ds_write_b32 v8, v77 offset:3072
	s_or_b64 exec, exec, s[10:11]
	s_and_saveexec_b64 s[10:11], s[4:5]
	ds_write_b32 v9, v76 offset:3072
	s_or_b64 exec, exec, s[10:11]
	s_cmp_le_u32 s99, 4
	s_cbranch_scc1 .Lpre5_done
	s_and_saveexec_b64 s[10:11], s[0:1]
	v_add_f32_e32 v89, v89, v90
	v_fmamk_f32 v89, v89, 0x3a800000, v10
	v_rsq_f32_e32 v89, v89
	s_nop 0
	ds_write_b32 v8, v89 offset:4096
	s_or_b64 exec, exec, s[10:11]
	s_and_saveexec_b64 s[10:11], s[4:5]
	ds_write_b32 v9, v88 offset:4096
	s_or_b64 exec, exec, s[10:11]
	s_cmp_le_u32 s99, 5
	s_cbranch_scc1 .Lpre5_done
	s_and_saveexec_b64 s[10:11], s[0:1]
	v_add_f32_e32 v101, v101, v102
	v_fmamk_f32 v101, v101, 0x3a800000, v10
	v_rsq_f32_e32 v101, v101
	s_nop 0
	ds_write_b32 v8, v101 offset:5120
	s_or_b64 exec, exec, s[10:11]
	s_and_saveexec_b64 s[10:11], s[4:5]
	ds_write_b32 v9, v100 offset:5120
	s_or_b64 exec, exec, s[10:11]
	s_cmp_le_u32 s99, 6
	s_cbranch_scc1 .Lpre5_done
	s_and_saveexec_b64 s[10:11], s[0:1]
	v_add_f32_e32 v113, v113, v114
	v_fmamk_f32 v113, v113, 0x3a800000, v10
	v_rsq_f32_e32 v113, v113
	s_nop 0
	ds_write_b32 v8, v113 offset:6144
	s_or_b64 exec, exec, s[10:11]
	s_and_saveexec_b64 s[10:11], s[4:5]
	ds_write_b32 v9, v112 offset:6144
	s_or_b64 exec, exec, s[10:11]
	s_cmp_le_u32 s99, 7
	s_cbranch_scc1 .Lpre5_done
	s_and_saveexec_b64 s[10:11], s[0:1]
	v_add_f32_e32 v125, v125, v126
	v_fmamk_f32 v125, v125, 0x3a800000, v10
	v_rsq_f32_e32 v125, v125
	s_nop 0
	ds_write_b32 v8, v125 offset:7168
	s_or_b64 exec, exec, s[10:11]
	s_and_saveexec_b64 s[10:11], s[4:5]
	ds_write_b32 v9, v124 offset:7168
	s_or_b64 exec, exec, s[10:11]
	s_cmp_le_u32 s99, 8
	s_cbranch_scc1 .Lpre5_done
	s_and_saveexec_b64 s[10:11], s[0:1]
	v_add_f32_e32 v137, v137, v138
	v_fmamk_f32 v137, v137, 0x3a800000, v10
	v_rsq_f32_e32 v137, v137
	s_nop 0
	ds_write_b32 v8, v137 offset:8192
	s_or_b64 exec, exec, s[10:11]
	s_and_saveexec_b64 s[10:11], s[4:5]
	ds_write_b32 v9, v136 offset:8192
	s_or_b64 exec, exec, s[10:11]
	s_cmp_le_u32 s99, 9
	s_cbranch_scc1 .Lpre5_done
	s_and_saveexec_b64 s[10:11], s[0:1]
	v_add_f32_e32 v149, v149, v150
	v_fmamk_f32 v149, v149, 0x3a800000, v10
	v_rsq_f32_e32 v149, v149
	s_nop 0
	ds_write_b32 v8, v149 offset:9216
	s_or_b64 exec, exec, s[10:11]
	s_and_saveexec_b64 s[10:11], s[4:5]
	ds_write_b32 v9, v148 offset:9216
	s_or_b64 exec, exec, s[10:11]
	s_cmp_le_u32 s99, 10
	s_cbranch_scc1 .Lpre5_done
	s_and_saveexec_b64 s[10:11], s[0:1]
	v_add_f32_e32 v161, v161, v162
	v_fmamk_f32 v161, v161, 0x3a800000, v10
	v_rsq_f32_e32 v161, v161
	s_nop 0
	ds_write_b32 v8, v161 offset:10240
	s_or_b64 exec, exec, s[10:11]
	s_and_saveexec_b64 s[10:11], s[4:5]
	ds_write_b32 v9, v160 offset:10240
	s_or_b64 exec, exec, s[10:11]
	s_cmp_le_u32 s99, 11
	s_cbranch_scc1 .Lpre5_done
	s_and_saveexec_b64 s[10:11], s[0:1]
	v_add_f32_e32 v173, v173, v174
	v_fmamk_f32 v173, v173, 0x3a800000, v10
	v_rsq_f32_e32 v173, v173
	s_nop 0
	ds_write_b32 v8, v173 offset:11264
	s_or_b64 exec, exec, s[10:11]
	s_and_saveexec_b64 s[10:11], s[4:5]
	ds_write_b32 v9, v172 offset:11264
	s_or_b64 exec, exec, s[10:11]
.Lpre5_done:
	s_branch .LBB0_575

.LBB0_1069:
	s_cmp_lt_i32 s58, 14
	s_cselect_b64 s[6:7], -1, 0
	s_and_b64 s[0:1], s[6:7], s[0:1]
	s_andn2_b64 vcc, exec, s[0:1]
	s_cbranch_vccnz .LBB0_1094
	s_waitcnt vmcnt(0)
	v_lshlrev_b32_e32 v2, 5, v211
	s_waitcnt lgkmcnt(0)
	v_mov_b32_e32 v3, 0
	v_lshl_add_u64 v[2:3], s[56:57], 0, v[2:3]
	s_mov_b64 s[0:1], 0x1ecb4000
	v_lshl_add_u64 v[4:5], v[2:3], 0, s[0:1]
	v_and_b32_e32 v2, 0x3ff, v0
	v_mbcnt_lo_u32_b32 v11, -1, 0
	s_add_u32 s12, s56, 0x1eee0000
	v_lshlrev_b32_e32 v3, 2, v2
	v_mbcnt_hi_u32_b32 v11, -1, v11
	s_addc_u32 s13, s57, 0
	s_ashr_i32 s3, s2, 31
	s_movk_i32 s4, 0x100
	v_add_u32_e32 v6, 0, v3
	v_and_b32_e32 v12, 64, v11
	s_ashr_i32 s36, s33, 31
	s_mov_b32 s14, 0
	v_cmp_eq_u32_e64 s[0:1], 0, v211
	v_cmp_gt_u32_e64 s[4:5], s4, v2
	v_add_u32_e32 v8, 0x20000, v210
	v_add_u32_e32 v9, 0x23000, v6
	v_mov_b64_e32 v[6:7], 0xaff
	s_movk_i32 s15, 0x161
	v_mov_b32_e32 v10, 0x358637bd
	v_xor_b32_e32 v13, 1, v11
	v_add_u32_e32 v14, 64, v12
	v_lshlrev_b32_e32 v12, 2, v2
	s_mov_b64 s[8:9], s[2:3]
	s_mov_b32 s99, 0
	v_cmp_gt_i64_e32 vcc, s[8:9], v[6:7]
	s_cbranch_vccnz .Lpre13_issued
	s_ashr_i32 s10, s8, 31
	s_lshr_b32 s10, s10, 29
	s_add_i32 s10, s8, s10
	s_ashr_i32 s11, s10, 3
	s_and_b32 s10, s10, -8
	s_sub_i32 s10, s8, s10
	s_cmp_lt_i32 s10, 0
	s_cselect_b32 s16, s15, 0x160
	s_mul_i32 s10, s10, s16
	s_add_i32 s10, s10, s11
	s_mul_hi_i32 s11, s10, 0x2e8ba2e9
	s_lshr_b32 s16, s11, 31
	s_ashr_i32 s11, s11, 5
	s_add_i32 s11, s11, s16
	s_lshl_b32 s17, s11, 3
	s_sub_i32 s16, 0x80, s17
	s_min_i32 s18, s16, 8
	s_abs_i32 s16, s18
	v_cvt_f32_u32_e32 v15, s16
	s_sub_i32 s22, 0, s16
	s_mulk_i32 s11, 0xb0
	s_sub_i32 s10, s10, s11
	v_rcp_iflag_f32_e32 v15, v15
	s_abs_i32 s11, s10
	s_xor_b32 s19, s10, s18
	s_ashr_i32 s19, s19, 31
	v_mul_f32_e32 v15, 0x4f7ffffe, v15
	v_cvt_u32_f32_e32 v15, v15
	v_cmp_lt_i32_e32 vcc, v13, v14
	v_readfirstlane_b32 s23, v15
	s_mul_i32 s22, s22, s23
	s_mul_hi_u32 s22, s23, s22
	s_add_i32 s23, s23, s22
	s_mul_hi_u32 s22, s11, s23
	s_mul_i32 s23, s22, s16
	s_sub_i32 s11, s11, s23
	s_add_i32 s24, s22, 1
	s_sub_i32 s23, s11, s16
	s_cmp_ge_u32 s11, s16
	s_cselect_b32 s22, s24, s22
	s_cselect_b32 s11, s23, s11
	s_add_i32 s23, s22, 1
	s_cmp_ge_u32 s11, s16
	s_cselect_b32 s11, s23, s22
	s_xor_b32 s11, s11, s19
	s_sub_i32 s16, s11, s19
	s_mul_i32 s11, s16, s18
	s_sub_i32 s10, s10, s11
	s_add_i32 s17, s17, s10
	v_lshl_add_u32 v16, s17, 8, v1
	v_ashrrev_i32_e32 v17, 31, v16
	v_lshlrev_b64 v[16:17], 6, v[16:17]
	v_lshl_add_u64 v[24:25], v[4:5], 0, v[16:17]
	global_load_dwordx4 v[32:35], v[24:25], off
	global_load_dwordx4 v[36:39], v[24:25], off offset:16
	s_and_saveexec_b64 s[10:11], s[4:5]
	s_ashr_i32 s18, s17, 4
	s_lshl_b32 s16, s16, 8
	s_ashr_i32 s17, s16, 31
	s_mul_hi_i32 s19, s18, 0x5800
	s_mulk_i32 s18, 0x5800
	s_add_u32 s18, s12, s18
	s_addc_u32 s19, s13, s19
	s_lshl_b64 s[16:17], s[16:17], 2
	s_add_u32 s16, s18, s16
	s_addc_u32 s17, s19, s17
	global_load_dword v40, v12, s[16:17]
	s_or_b64 exec, exec, s[10:11]
	s_add_u32 s8, s8, s33
	s_addc_u32 s9, s9, s36
	s_add_i32 s99, s99, 1
	v_cmp_gt_i64_e32 vcc, s[8:9], v[6:7]
	s_cbranch_vccnz .Lpre13_issued
	s_ashr_i32 s10, s8, 31
	s_lshr_b32 s10, s10, 29
	s_add_i32 s10, s8, s10
	s_ashr_i32 s11, s10, 3
	s_and_b32 s10, s10, -8
	s_sub_i32 s10, s8, s10
	s_cmp_lt_i32 s10, 0
	s_cselect_b32 s16, s15, 0x160
	s_mul_i32 s10, s10, s16
	s_add_i32 s10, s10, s11
	s_mul_hi_i32 s11, s10, 0x2e8ba2e9
	s_lshr_b32 s16, s11, 31
	s_ashr_i32 s11, s11, 5
	s_add_i32 s11, s11, s16
	s_lshl_b32 s17, s11, 3
	s_sub_i32 s16, 0x80, s17
	s_min_i32 s18, s16, 8
	s_abs_i32 s16, s18
	v_cvt_f32_u32_e32 v15, s16
	s_sub_i32 s22, 0, s16
	s_mulk_i32 s11, 0xb0
	s_sub_i32 s10, s10, s11
	v_rcp_iflag_f32_e32 v15, v15
	s_abs_i32 s11, s10
	s_xor_b32 s19, s10, s18
	s_ashr_i32 s19, s19, 31
	v_mul_f32_e32 v15, 0x4f7ffffe, v15
	v_cvt_u32_f32_e32 v15, v15
	v_cmp_lt_i32_e32 vcc, v13, v14
	v_readfirstlane_b32 s23, v15
	s_mul_i32 s22, s22, s23
	s_mul_hi_u32 s22, s23, s22
	s_add_i32 s23, s23, s22
	s_mul_hi_u32 s22, s11, s23
	s_mul_i32 s23, s22, s16
	s_sub_i32 s11, s11, s23
	s_add_i32 s24, s22, 1
	s_sub_i32 s23, s11, s16
	s_cmp_ge_u32 s11, s16
	s_cselect_b32 s22, s24, s22
	s_cselect_b32 s11, s23, s11
	s_add_i32 s23, s22, 1
	s_cmp_ge_u32 s11, s16
	s_cselect_b32 s11, s23, s22
	s_xor_b32 s11, s11, s19
	s_sub_i32 s16, s11, s19
	s_mul_i32 s11, s16, s18
	s_sub_i32 s10, s10, s11
	s_add_i32 s17, s17, s10
	v_lshl_add_u32 v16, s17, 8, v1
	v_ashrrev_i32_e32 v17, 31, v16
	v_lshlrev_b64 v[16:17], 6, v[16:17]
	v_lshl_add_u64 v[24:25], v[4:5], 0, v[16:17]
	global_load_dwordx4 v[44:47], v[24:25], off
	global_load_dwordx4 v[48:51], v[24:25], off offset:16
	s_and_saveexec_b64 s[10:11], s[4:5]
	s_ashr_i32 s18, s17, 4
	s_lshl_b32 s16, s16, 8
	s_ashr_i32 s17, s16, 31
	s_mul_hi_i32 s19, s18, 0x5800
	s_mulk_i32 s18, 0x5800
	s_add_u32 s18, s12, s18
	s_addc_u32 s19, s13, s19
	s_lshl_b64 s[16:17], s[16:17], 2
	s_add_u32 s16, s18, s16
	s_addc_u32 s17, s19, s17
	global_load_dword v52, v12, s[16:17]
	s_or_b64 exec, exec, s[10:11]
	s_add_u32 s8, s8, s33
	s_addc_u32 s9, s9, s36
	s_add_i32 s99, s99, 1
	v_cmp_gt_i64_e32 vcc, s[8:9], v[6:7]
	s_cbranch_vccnz .Lpre13_issued
	s_ashr_i32 s10, s8, 31
	s_lshr_b32 s10, s10, 29
	s_add_i32 s10, s8, s10
	s_ashr_i32 s11, s10, 3
	s_and_b32 s10, s10, -8
	s_sub_i32 s10, s8, s10
	s_cmp_lt_i32 s10, 0
	s_cselect_b32 s16, s15, 0x160
	s_mul_i32 s10, s10, s16
	s_add_i32 s10, s10, s11
	s_mul_hi_i32 s11, s10, 0x2e8ba2e9
	s_lshr_b32 s16, s11, 31
	s_ashr_i32 s11, s11, 5
	s_add_i32 s11, s11, s16
	s_lshl_b32 s17, s11, 3
	s_sub_i32 s16, 0x80, s17
	s_min_i32 s18, s16, 8
	s_abs_i32 s16, s18
	v_cvt_f32_u32_e32 v15, s16
	s_sub_i32 s22, 0, s16
	s_mulk_i32 s11, 0xb0
	s_sub_i32 s10, s10, s11
	v_rcp_iflag_f32_e32 v15, v15
	s_abs_i32 s11, s10
	s_xor_b32 s19, s10, s18
	s_ashr_i32 s19, s19, 31
	v_mul_f32_e32 v15, 0x4f7ffffe, v15
	v_cvt_u32_f32_e32 v15, v15
	v_cmp_lt_i32_e32 vcc, v13, v14
	v_readfirstlane_b32 s23, v15
	s_mul_i32 s22, s22, s23
	s_mul_hi_u32 s22, s23, s22
	s_add_i32 s23, s23, s22
	s_mul_hi_u32 s22, s11, s23
	s_mul_i32 s23, s22, s16
	s_sub_i32 s11, s11, s23
	s_add_i32 s24, s22, 1
	s_sub_i32 s23, s11, s16
	s_cmp_ge_u32 s11, s16
	s_cselect_b32 s22, s24, s22
	s_cselect_b32 s11, s23, s11
	s_add_i32 s23, s22, 1
	s_cmp_ge_u32 s11, s16
	s_cselect_b32 s11, s23, s22
	s_xor_b32 s11, s11, s19
	s_sub_i32 s16, s11, s19
	s_mul_i32 s11, s16, s18
	s_sub_i32 s10, s10, s11
	s_add_i32 s17, s17, s10
	v_lshl_add_u32 v16, s17, 8, v1
	v_ashrrev_i32_e32 v17, 31, v16
	v_lshlrev_b64 v[16:17], 6, v[16:17]
	v_lshl_add_u64 v[24:25], v[4:5], 0, v[16:17]
	global_load_dwordx4 v[56:59], v[24:25], off
	global_load_dwordx4 v[60:63], v[24:25], off offset:16
	s_and_saveexec_b64 s[10:11], s[4:5]
	s_ashr_i32 s18, s17, 4
	s_lshl_b32 s16, s16, 8
	s_ashr_i32 s17, s16, 31
	s_mul_hi_i32 s19, s18, 0x5800
	s_mulk_i32 s18, 0x5800
	s_add_u32 s18, s12, s18
	s_addc_u32 s19, s13, s19
	s_lshl_b64 s[16:17], s[16:17], 2
	s_add_u32 s16, s18, s16
	s_addc_u32 s17, s19, s17
	global_load_dword v64, v12, s[16:17]
	s_or_b64 exec, exec, s[10:11]
	s_add_u32 s8, s8, s33
	s_addc_u32 s9, s9, s36
	s_add_i32 s99, s99, 1
	v_cmp_gt_i64_e32 vcc, s[8:9], v[6:7]
	s_cbranch_vccnz .Lpre13_issued
	s_ashr_i32 s10, s8, 31
	s_lshr_b32 s10, s10, 29
	s_add_i32 s10, s8, s10
	s_ashr_i32 s11, s10, 3
	s_and_b32 s10, s10, -8
	s_sub_i32 s10, s8, s10
	s_cmp_lt_i32 s10, 0
	s_cselect_b32 s16, s15, 0x160
	s_mul_i32 s10, s10, s16
	s_add_i32 s10, s10, s11
	s_mul_hi_i32 s11, s10, 0x2e8ba2e9
	s_lshr_b32 s16, s11, 31
	s_ashr_i32 s11, s11, 5
	s_add_i32 s11, s11, s16
	s_lshl_b32 s17, s11, 3
	s_sub_i32 s16, 0x80, s17
	s_min_i32 s18, s16, 8
	s_abs_i32 s16, s18
	v_cvt_f32_u32_e32 v15, s16
	s_sub_i32 s22, 0, s16
	s_mulk_i32 s11, 0xb0
	s_sub_i32 s10, s10, s11
	v_rcp_iflag_f32_e32 v15, v15
	s_abs_i32 s11, s10
	s_xor_b32 s19, s10, s18
	s_ashr_i32 s19, s19, 31
	v_mul_f32_e32 v15, 0x4f7ffffe, v15
	v_cvt_u32_f32_e32 v15, v15
	v_cmp_lt_i32_e32 vcc, v13, v14
	v_readfirstlane_b32 s23, v15
	s_mul_i32 s22, s22, s23
	s_mul_hi_u32 s22, s23, s22
	s_add_i32 s23, s23, s22
	s_mul_hi_u32 s22, s11, s23
	s_mul_i32 s23, s22, s16
	s_sub_i32 s11, s11, s23
	s_add_i32 s24, s22, 1
	s_sub_i32 s23, s11, s16
	s_cmp_ge_u32 s11, s16
	s_cselect_b32 s22, s24, s22
	s_cselect_b32 s11, s23, s11
	s_add_i32 s23, s22, 1
	s_cmp_ge_u32 s11, s16
	s_cselect_b32 s11, s23, s22
	s_xor_b32 s11, s11, s19
	s_sub_i32 s16, s11, s19
	s_mul_i32 s11, s16, s18
	s_sub_i32 s10, s10, s11
	s_add_i32 s17, s17, s10
	v_lshl_add_u32 v16, s17, 8, v1
	v_ashrrev_i32_e32 v17, 31, v16
	v_lshlrev_b64 v[16:17], 6, v[16:17]
	v_lshl_add_u64 v[24:25], v[4:5], 0, v[16:17]
	global_load_dwordx4 v[68:71], v[24:25], off
	global_load_dwordx4 v[72:75], v[24:25], off offset:16
	s_and_saveexec_b64 s[10:11], s[4:5]
	s_ashr_i32 s18, s17, 4
	s_lshl_b32 s16, s16, 8
	s_ashr_i32 s17, s16, 31
	s_mul_hi_i32 s19, s18, 0x5800
	s_mulk_i32 s18, 0x5800
	s_add_u32 s18, s12, s18
	s_addc_u32 s19, s13, s19
	s_lshl_b64 s[16:17], s[16:17], 2
	s_add_u32 s16, s18, s16
	s_addc_u32 s17, s19, s17
	global_load_dword v76, v12, s[16:17]
	s_or_b64 exec, exec, s[10:11]
	s_add_u32 s8, s8, s33
	s_addc_u32 s9, s9, s36
	s_add_i32 s99, s99, 1
	v_cmp_gt_i64_e32 vcc, s[8:9], v[6:7]
	s_cbranch_vccnz .Lpre13_issued
	s_ashr_i32 s10, s8, 31
	s_lshr_b32 s10, s10, 29
	s_add_i32 s10, s8, s10
	s_ashr_i32 s11, s10, 3
	s_and_b32 s10, s10, -8
	s_sub_i32 s10, s8, s10
	s_cmp_lt_i32 s10, 0
	s_cselect_b32 s16, s15, 0x160
	s_mul_i32 s10, s10, s16
	s_add_i32 s10, s10, s11
	s_mul_hi_i32 s11, s10, 0x2e8ba2e9
	s_lshr_b32 s16, s11, 31
	s_ashr_i32 s11, s11, 5
	s_add_i32 s11, s11, s16
	s_lshl_b32 s17, s11, 3
	s_sub_i32 s16, 0x80, s17
	s_min_i32 s18, s16, 8
	s_abs_i32 s16, s18
	v_cvt_f32_u32_e32 v15, s16
	s_sub_i32 s22, 0, s16
	s_mulk_i32 s11, 0xb0
	s_sub_i32 s10, s10, s11
	v_rcp_iflag_f32_e32 v15, v15
	s_abs_i32 s11, s10
	s_xor_b32 s19, s10, s18
	s_ashr_i32 s19, s19, 31
	v_mul_f32_e32 v15, 0x4f7ffffe, v15
	v_cvt_u32_f32_e32 v15, v15
	v_cmp_lt_i32_e32 vcc, v13, v14
	v_readfirstlane_b32 s23, v15
	s_mul_i32 s22, s22, s23
	s_mul_hi_u32 s22, s23, s22
	s_add_i32 s23, s23, s22
	s_mul_hi_u32 s22, s11, s23
	s_mul_i32 s23, s22, s16
	s_sub_i32 s11, s11, s23
	s_add_i32 s24, s22, 1
	s_sub_i32 s23, s11, s16
	s_cmp_ge_u32 s11, s16
	s_cselect_b32 s22, s24, s22
	s_cselect_b32 s11, s23, s11
	s_add_i32 s23, s22, 1
	s_cmp_ge_u32 s11, s16
	s_cselect_b32 s11, s23, s22
	s_xor_b32 s11, s11, s19
	s_sub_i32 s16, s11, s19
	s_mul_i32 s11, s16, s18
	s_sub_i32 s10, s10, s11
	s_add_i32 s17, s17, s10
	v_lshl_add_u32 v16, s17, 8, v1
	v_ashrrev_i32_e32 v17, 31, v16
	v_lshlrev_b64 v[16:17], 6, v[16:17]
	v_lshl_add_u64 v[24:25], v[4:5], 0, v[16:17]
	global_load_dwordx4 v[80:83], v[24:25], off
	global_load_dwordx4 v[84:87], v[24:25], off offset:16
	s_and_saveexec_b64 s[10:11], s[4:5]
	s_ashr_i32 s18, s17, 4
	s_lshl_b32 s16, s16, 8
	s_ashr_i32 s17, s16, 31
	s_mul_hi_i32 s19, s18, 0x5800
	s_mulk_i32 s18, 0x5800
	s_add_u32 s18, s12, s18
	s_addc_u32 s19, s13, s19
	s_lshl_b64 s[16:17], s[16:17], 2
	s_add_u32 s16, s18, s16
	s_addc_u32 s17, s19, s17
	global_load_dword v88, v12, s[16:17]
	s_or_b64 exec, exec, s[10:11]
	s_add_u32 s8, s8, s33
	s_addc_u32 s9, s9, s36
	s_add_i32 s99, s99, 1
	v_cmp_gt_i64_e32 vcc, s[8:9], v[6:7]
	s_cbranch_vccnz .Lpre13_issued
	s_ashr_i32 s10, s8, 31
	s_lshr_b32 s10, s10, 29
	s_add_i32 s10, s8, s10
	s_ashr_i32 s11, s10, 3
	s_and_b32 s10, s10, -8
	s_sub_i32 s10, s8, s10
	s_cmp_lt_i32 s10, 0
	s_cselect_b32 s16, s15, 0x160
	s_mul_i32 s10, s10, s16
	s_add_i32 s10, s10, s11
	s_mul_hi_i32 s11, s10, 0x2e8ba2e9
	s_lshr_b32 s16, s11, 31
	s_ashr_i32 s11, s11, 5
	s_add_i32 s11, s11, s16
	s_lshl_b32 s17, s11, 3
	s_sub_i32 s16, 0x80, s17
	s_min_i32 s18, s16, 8
	s_abs_i32 s16, s18
	v_cvt_f32_u32_e32 v15, s16
	s_sub_i32 s22, 0, s16
	s_mulk_i32 s11, 0xb0
	s_sub_i32 s10, s10, s11
	v_rcp_iflag_f32_e32 v15, v15
	s_abs_i32 s11, s10
	s_xor_b32 s19, s10, s18
	s_ashr_i32 s19, s19, 31
	v_mul_f32_e32 v15, 0x4f7ffffe, v15
	v_cvt_u32_f32_e32 v15, v15
	v_cmp_lt_i32_e32 vcc, v13, v14
	v_readfirstlane_b32 s23, v15
	s_mul_i32 s22, s22, s23
	s_mul_hi_u32 s22, s23, s22
	s_add_i32 s23, s23, s22
	s_mul_hi_u32 s22, s11, s23
	s_mul_i32 s23, s22, s16
	s_sub_i32 s11, s11, s23
	s_add_i32 s24, s22, 1
	s_sub_i32 s23, s11, s16
	s_cmp_ge_u32 s11, s16
	s_cselect_b32 s22, s24, s22
	s_cselect_b32 s11, s23, s11
	s_add_i32 s23, s22, 1
	s_cmp_ge_u32 s11, s16
	s_cselect_b32 s11, s23, s22
	s_xor_b32 s11, s11, s19
	s_sub_i32 s16, s11, s19
	s_mul_i32 s11, s16, s18
	s_sub_i32 s10, s10, s11
	s_add_i32 s17, s17, s10
	v_lshl_add_u32 v16, s17, 8, v1
	v_ashrrev_i32_e32 v17, 31, v16
	v_lshlrev_b64 v[16:17], 6, v[16:17]
	v_lshl_add_u64 v[24:25], v[4:5], 0, v[16:17]
	global_load_dwordx4 v[92:95], v[24:25], off
	global_load_dwordx4 v[96:99], v[24:25], off offset:16
	s_and_saveexec_b64 s[10:11], s[4:5]
	s_ashr_i32 s18, s17, 4
	s_lshl_b32 s16, s16, 8
	s_ashr_i32 s17, s16, 31
	s_mul_hi_i32 s19, s18, 0x5800
	s_mulk_i32 s18, 0x5800
	s_add_u32 s18, s12, s18
	s_addc_u32 s19, s13, s19
	s_lshl_b64 s[16:17], s[16:17], 2
	s_add_u32 s16, s18, s16
	s_addc_u32 s17, s19, s17
	global_load_dword v100, v12, s[16:17]
	s_or_b64 exec, exec, s[10:11]
	s_add_u32 s8, s8, s33
	s_addc_u32 s9, s9, s36
	s_add_i32 s99, s99, 1
	v_cmp_gt_i64_e32 vcc, s[8:9], v[6:7]
	s_cbranch_vccnz .Lpre13_issued
	s_ashr_i32 s10, s8, 31
	s_lshr_b32 s10, s10, 29
	s_add_i32 s10, s8, s10
	s_ashr_i32 s11, s10, 3
	s_and_b32 s10, s10, -8
	s_sub_i32 s10, s8, s10
	s_cmp_lt_i32 s10, 0
	s_cselect_b32 s16, s15, 0x160
	s_mul_i32 s10, s10, s16
	s_add_i32 s10, s10, s11
	s_mul_hi_i32 s11, s10, 0x2e8ba2e9
	s_lshr_b32 s16, s11, 31
	s_ashr_i32 s11, s11, 5
	s_add_i32 s11, s11, s16
	s_lshl_b32 s17, s11, 3
	s_sub_i32 s16, 0x80, s17
	s_min_i32 s18, s16, 8
	s_abs_i32 s16, s18
	v_cvt_f32_u32_e32 v15, s16
	s_sub_i32 s22, 0, s16
	s_mulk_i32 s11, 0xb0
	s_sub_i32 s10, s10, s11
	v_rcp_iflag_f32_e32 v15, v15
	s_abs_i32 s11, s10
	s_xor_b32 s19, s10, s18
	s_ashr_i32 s19, s19, 31
	v_mul_f32_e32 v15, 0x4f7ffffe, v15
	v_cvt_u32_f32_e32 v15, v15
	v_cmp_lt_i32_e32 vcc, v13, v14
	v_readfirstlane_b32 s23, v15
	s_mul_i32 s22, s22, s23
	s_mul_hi_u32 s22, s23, s22
	s_add_i32 s23, s23, s22
	s_mul_hi_u32 s22, s11, s23
	s_mul_i32 s23, s22, s16
	s_sub_i32 s11, s11, s23
	s_add_i32 s24, s22, 1
	s_sub_i32 s23, s11, s16
	s_cmp_ge_u32 s11, s16
	s_cselect_b32 s22, s24, s22
	s_cselect_b32 s11, s23, s11
	s_add_i32 s23, s22, 1
	s_cmp_ge_u32 s11, s16
	s_cselect_b32 s11, s23, s22
	s_xor_b32 s11, s11, s19
	s_sub_i32 s16, s11, s19
	s_mul_i32 s11, s16, s18
	s_sub_i32 s10, s10, s11
	s_add_i32 s17, s17, s10
	v_lshl_add_u32 v16, s17, 8, v1
	v_ashrrev_i32_e32 v17, 31, v16
	v_lshlrev_b64 v[16:17], 6, v[16:17]
	v_lshl_add_u64 v[24:25], v[4:5], 0, v[16:17]
	global_load_dwordx4 v[104:107], v[24:25], off
	global_load_dwordx4 v[108:111], v[24:25], off offset:16
	s_and_saveexec_b64 s[10:11], s[4:5]
	s_ashr_i32 s18, s17, 4
	s_lshl_b32 s16, s16, 8
	s_ashr_i32 s17, s16, 31
	s_mul_hi_i32 s19, s18, 0x5800
	s_mulk_i32 s18, 0x5800
	s_add_u32 s18, s12, s18
	s_addc_u32 s19, s13, s19
	s_lshl_b64 s[16:17], s[16:17], 2
	s_add_u32 s16, s18, s16
	s_addc_u32 s17, s19, s17
	global_load_dword v112, v12, s[16:17]
	s_or_b64 exec, exec, s[10:11]
	s_add_u32 s8, s8, s33
	s_addc_u32 s9, s9, s36
	s_add_i32 s99, s99, 1
	v_cmp_gt_i64_e32 vcc, s[8:9], v[6:7]
	s_cbranch_vccnz .Lpre13_issued
	s_ashr_i32 s10, s8, 31
	s_lshr_b32 s10, s10, 29
	s_add_i32 s10, s8, s10
	s_ashr_i32 s11, s10, 3
	s_and_b32 s10, s10, -8
	s_sub_i32 s10, s8, s10
	s_cmp_lt_i32 s10, 0
	s_cselect_b32 s16, s15, 0x160
	s_mul_i32 s10, s10, s16
	s_add_i32 s10, s10, s11
	s_mul_hi_i32 s11, s10, 0x2e8ba2e9
	s_lshr_b32 s16, s11, 31
	s_ashr_i32 s11, s11, 5
	s_add_i32 s11, s11, s16
	s_lshl_b32 s17, s11, 3
	s_sub_i32 s16, 0x80, s17
	s_min_i32 s18, s16, 8
	s_abs_i32 s16, s18
	v_cvt_f32_u32_e32 v15, s16
	s_sub_i32 s22, 0, s16
	s_mulk_i32 s11, 0xb0
	s_sub_i32 s10, s10, s11
	v_rcp_iflag_f32_e32 v15, v15
	s_abs_i32 s11, s10
	s_xor_b32 s19, s10, s18
	s_ashr_i32 s19, s19, 31
	v_mul_f32_e32 v15, 0x4f7ffffe, v15
	v_cvt_u32_f32_e32 v15, v15
	v_cmp_lt_i32_e32 vcc, v13, v14
	v_readfirstlane_b32 s23, v15
	s_mul_i32 s22, s22, s23
	s_mul_hi_u32 s22, s23, s22
	s_add_i32 s23, s23, s22
	s_mul_hi_u32 s22, s11, s23
	s_mul_i32 s23, s22, s16
	s_sub_i32 s11, s11, s23
	s_add_i32 s24, s22, 1
	s_sub_i32 s23, s11, s16
	s_cmp_ge_u32 s11, s16
	s_cselect_b32 s22, s24, s22
	s_cselect_b32 s11, s23, s11
	s_add_i32 s23, s22, 1
	s_cmp_ge_u32 s11, s16
	s_cselect_b32 s11, s23, s22
	s_xor_b32 s11, s11, s19
	s_sub_i32 s16, s11, s19
	s_mul_i32 s11, s16, s18
	s_sub_i32 s10, s10, s11
	s_add_i32 s17, s17, s10
	v_lshl_add_u32 v16, s17, 8, v1
	v_ashrrev_i32_e32 v17, 31, v16
	v_lshlrev_b64 v[16:17], 6, v[16:17]
	v_lshl_add_u64 v[24:25], v[4:5], 0, v[16:17]
	global_load_dwordx4 v[116:119], v[24:25], off
	global_load_dwordx4 v[120:123], v[24:25], off offset:16
	s_and_saveexec_b64 s[10:11], s[4:5]
	s_ashr_i32 s18, s17, 4
	s_lshl_b32 s16, s16, 8
	s_ashr_i32 s17, s16, 31
	s_mul_hi_i32 s19, s18, 0x5800
	s_mulk_i32 s18, 0x5800
	s_add_u32 s18, s12, s18
	s_addc_u32 s19, s13, s19
	s_lshl_b64 s[16:17], s[16:17], 2
	s_add_u32 s16, s18, s16
	s_addc_u32 s17, s19, s17
	global_load_dword v124, v12, s[16:17]
	s_or_b64 exec, exec, s[10:11]
	s_add_u32 s8, s8, s33
	s_addc_u32 s9, s9, s36
	s_add_i32 s99, s99, 1
	v_cmp_gt_i64_e32 vcc, s[8:9], v[6:7]
	s_cbranch_vccnz .Lpre13_issued
	s_ashr_i32 s10, s8, 31
	s_lshr_b32 s10, s10, 29
	s_add_i32 s10, s8, s10
	s_ashr_i32 s11, s10, 3
	s_and_b32 s10, s10, -8
	s_sub_i32 s10, s8, s10
	s_cmp_lt_i32 s10, 0
	s_cselect_b32 s16, s15, 0x160
	s_mul_i32 s10, s10, s16
	s_add_i32 s10, s10, s11
	s_mul_hi_i32 s11, s10, 0x2e8ba2e9
	s_lshr_b32 s16, s11, 31
	s_ashr_i32 s11, s11, 5
	s_add_i32 s11, s11, s16
	s_lshl_b32 s17, s11, 3
	s_sub_i32 s16, 0x80, s17
	s_min_i32 s18, s16, 8
	s_abs_i32 s16, s18
	v_cvt_f32_u32_e32 v15, s16
	s_sub_i32 s22, 0, s16
	s_mulk_i32 s11, 0xb0
	s_sub_i32 s10, s10, s11
	v_rcp_iflag_f32_e32 v15, v15
	s_abs_i32 s11, s10
	s_xor_b32 s19, s10, s18
	s_ashr_i32 s19, s19, 31
	v_mul_f32_e32 v15, 0x4f7ffffe, v15
	v_cvt_u32_f32_e32 v15, v15
	v_cmp_lt_i32_e32 vcc, v13, v14
	v_readfirstlane_b32 s23, v15
	s_mul_i32 s22, s22, s23
	s_mul_hi_u32 s22, s23, s22
	s_add_i32 s23, s23, s22
	s_mul_hi_u32 s22, s11, s23
	s_mul_i32 s23, s22, s16
	s_sub_i32 s11, s11, s23
	s_add_i32 s24, s22, 1
	s_sub_i32 s23, s11, s16
	s_cmp_ge_u32 s11, s16
	s_cselect_b32 s22, s24, s22
	s_cselect_b32 s11, s23, s11
	s_add_i32 s23, s22, 1
	s_cmp_ge_u32 s11, s16
	s_cselect_b32 s11, s23, s22
	s_xor_b32 s11, s11, s19
	s_sub_i32 s16, s11, s19
	s_mul_i32 s11, s16, s18
	s_sub_i32 s10, s10, s11
	s_add_i32 s17, s17, s10
	v_lshl_add_u32 v16, s17, 8, v1
	v_ashrrev_i32_e32 v17, 31, v16
	v_lshlrev_b64 v[16:17], 6, v[16:17]
	v_lshl_add_u64 v[24:25], v[4:5], 0, v[16:17]
	global_load_dwordx4 v[128:131], v[24:25], off
	global_load_dwordx4 v[132:135], v[24:25], off offset:16
	s_and_saveexec_b64 s[10:11], s[4:5]
	s_ashr_i32 s18, s17, 4
	s_lshl_b32 s16, s16, 8
	s_ashr_i32 s17, s16, 31
	s_mul_hi_i32 s19, s18, 0x5800
	s_mulk_i32 s18, 0x5800
	s_add_u32 s18, s12, s18
	s_addc_u32 s19, s13, s19
	s_lshl_b64 s[16:17], s[16:17], 2
	s_add_u32 s16, s18, s16
	s_addc_u32 s17, s19, s17
	global_load_dword v136, v12, s[16:17]
	s_or_b64 exec, exec, s[10:11]
	s_add_u32 s8, s8, s33
	s_addc_u32 s9, s9, s36
	s_add_i32 s99, s99, 1
	v_cmp_gt_i64_e32 vcc, s[8:9], v[6:7]
	s_cbranch_vccnz .Lpre13_issued
	s_ashr_i32 s10, s8, 31
	s_lshr_b32 s10, s10, 29
	s_add_i32 s10, s8, s10
	s_ashr_i32 s11, s10, 3
	s_and_b32 s10, s10, -8
	s_sub_i32 s10, s8, s10
	s_cmp_lt_i32 s10, 0
	s_cselect_b32 s16, s15, 0x160
	s_mul_i32 s10, s10, s16
	s_add_i32 s10, s10, s11
	s_mul_hi_i32 s11, s10, 0x2e8ba2e9
	s_lshr_b32 s16, s11, 31
	s_ashr_i32 s11, s11, 5
	s_add_i32 s11, s11, s16
	s_lshl_b32 s17, s11, 3
	s_sub_i32 s16, 0x80, s17
	s_min_i32 s18, s16, 8
	s_abs_i32 s16, s18
	v_cvt_f32_u32_e32 v15, s16
	s_sub_i32 s22, 0, s16
	s_mulk_i32 s11, 0xb0
	s_sub_i32 s10, s10, s11
	v_rcp_iflag_f32_e32 v15, v15
	s_abs_i32 s11, s10
	s_xor_b32 s19, s10, s18
	s_ashr_i32 s19, s19, 31
	v_mul_f32_e32 v15, 0x4f7ffffe, v15
	v_cvt_u32_f32_e32 v15, v15
	v_cmp_lt_i32_e32 vcc, v13, v14
	v_readfirstlane_b32 s23, v15
	s_mul_i32 s22, s22, s23
	s_mul_hi_u32 s22, s23, s22
	s_add_i32 s23, s23, s22
	s_mul_hi_u32 s22, s11, s23
	s_mul_i32 s23, s22, s16
	s_sub_i32 s11, s11, s23
	s_add_i32 s24, s22, 1
	s_sub_i32 s23, s11, s16
	s_cmp_ge_u32 s11, s16
	s_cselect_b32 s22, s24, s22
	s_cselect_b32 s11, s23, s11
	s_add_i32 s23, s22, 1
	s_cmp_ge_u32 s11, s16
	s_cselect_b32 s11, s23, s22
	s_xor_b32 s11, s11, s19
	s_sub_i32 s16, s11, s19
	s_mul_i32 s11, s16, s18
	s_sub_i32 s10, s10, s11
	s_add_i32 s17, s17, s10
	v_lshl_add_u32 v16, s17, 8, v1
	v_ashrrev_i32_e32 v17, 31, v16
	v_lshlrev_b64 v[16:17], 6, v[16:17]
	v_lshl_add_u64 v[24:25], v[4:5], 0, v[16:17]
	global_load_dwordx4 v[140:143], v[24:25], off
	global_load_dwordx4 v[144:147], v[24:25], off offset:16
	s_and_saveexec_b64 s[10:11], s[4:5]
	s_ashr_i32 s18, s17, 4
	s_lshl_b32 s16, s16, 8
	s_ashr_i32 s17, s16, 31
	s_mul_hi_i32 s19, s18, 0x5800
	s_mulk_i32 s18, 0x5800
	s_add_u32 s18, s12, s18
	s_addc_u32 s19, s13, s19
	s_lshl_b64 s[16:17], s[16:17], 2
	s_add_u32 s16, s18, s16
	s_addc_u32 s17, s19, s17
	global_load_dword v148, v12, s[16:17]
	s_or_b64 exec, exec, s[10:11]
	s_add_u32 s8, s8, s33
	s_addc_u32 s9, s9, s36
	s_add_i32 s99, s99, 1
	v_cmp_gt_i64_e32 vcc, s[8:9], v[6:7]
	s_cbranch_vccnz .Lpre13_issued
	s_ashr_i32 s10, s8, 31
	s_lshr_b32 s10, s10, 29
	s_add_i32 s10, s8, s10
	s_ashr_i32 s11, s10, 3
	s_and_b32 s10, s10, -8
	s_sub_i32 s10, s8, s10
	s_cmp_lt_i32 s10, 0
	s_cselect_b32 s16, s15, 0x160
	s_mul_i32 s10, s10, s16
	s_add_i32 s10, s10, s11
	s_mul_hi_i32 s11, s10, 0x2e8ba2e9
	s_lshr_b32 s16, s11, 31
	s_ashr_i32 s11, s11, 5
	s_add_i32 s11, s11, s16
	s_lshl_b32 s17, s11, 3
	s_sub_i32 s16, 0x80, s17
	s_min_i32 s18, s16, 8
	s_abs_i32 s16, s18
	v_cvt_f32_u32_e32 v15, s16
	s_sub_i32 s22, 0, s16
	s_mulk_i32 s11, 0xb0
	s_sub_i32 s10, s10, s11
	v_rcp_iflag_f32_e32 v15, v15
	s_abs_i32 s11, s10
	s_xor_b32 s19, s10, s18
	s_ashr_i32 s19, s19, 31
	v_mul_f32_e32 v15, 0x4f7ffffe, v15
	v_cvt_u32_f32_e32 v15, v15
	v_cmp_lt_i32_e32 vcc, v13, v14
	v_readfirstlane_b32 s23, v15
	s_mul_i32 s22, s22, s23
	s_mul_hi_u32 s22, s23, s22
	s_add_i32 s23, s23, s22
	s_mul_hi_u32 s22, s11, s23
	s_mul_i32 s23, s22, s16
	s_sub_i32 s11, s11, s23
	s_add_i32 s24, s22, 1
	s_sub_i32 s23, s11, s16
	s_cmp_ge_u32 s11, s16
	s_cselect_b32 s22, s24, s22
	s_cselect_b32 s11, s23, s11
	s_add_i32 s23, s22, 1
	s_cmp_ge_u32 s11, s16
	s_cselect_b32 s11, s23, s22
	s_xor_b32 s11, s11, s19
	s_sub_i32 s16, s11, s19
	s_mul_i32 s11, s16, s18
	s_sub_i32 s10, s10, s11
	s_add_i32 s17, s17, s10
	v_lshl_add_u32 v16, s17, 8, v1
	v_ashrrev_i32_e32 v17, 31, v16
	v_lshlrev_b64 v[16:17], 6, v[16:17]
	v_lshl_add_u64 v[24:25], v[4:5], 0, v[16:17]
	global_load_dwordx4 v[152:155], v[24:25], off
	global_load_dwordx4 v[156:159], v[24:25], off offset:16
	s_and_saveexec_b64 s[10:11], s[4:5]
	s_ashr_i32 s18, s17, 4
	s_lshl_b32 s16, s16, 8
	s_ashr_i32 s17, s16, 31
	s_mul_hi_i32 s19, s18, 0x5800
	s_mulk_i32 s18, 0x5800
	s_add_u32 s18, s12, s18
	s_addc_u32 s19, s13, s19
	s_lshl_b64 s[16:17], s[16:17], 2
	s_add_u32 s16, s18, s16
	s_addc_u32 s17, s19, s17
	global_load_dword v160, v12, s[16:17]
	s_or_b64 exec, exec, s[10:11]
	s_add_u32 s8, s8, s33
	s_addc_u32 s9, s9, s36
	s_add_i32 s99, s99, 1
	v_cmp_gt_i64_e32 vcc, s[8:9], v[6:7]
	s_cbranch_vccnz .Lpre13_issued
	s_ashr_i32 s10, s8, 31
	s_lshr_b32 s10, s10, 29
	s_add_i32 s10, s8, s10
	s_ashr_i32 s11, s10, 3
	s_and_b32 s10, s10, -8
	s_sub_i32 s10, s8, s10
	s_cmp_lt_i32 s10, 0
	s_cselect_b32 s16, s15, 0x160
	s_mul_i32 s10, s10, s16
	s_add_i32 s10, s10, s11
	s_mul_hi_i32 s11, s10, 0x2e8ba2e9
	s_lshr_b32 s16, s11, 31
	s_ashr_i32 s11, s11, 5
	s_add_i32 s11, s11, s16
	s_lshl_b32 s17, s11, 3
	s_sub_i32 s16, 0x80, s17
	s_min_i32 s18, s16, 8
	s_abs_i32 s16, s18
	v_cvt_f32_u32_e32 v15, s16
	s_sub_i32 s22, 0, s16
	s_mulk_i32 s11, 0xb0
	s_sub_i32 s10, s10, s11
	v_rcp_iflag_f32_e32 v15, v15
	s_abs_i32 s11, s10
	s_xor_b32 s19, s10, s18
	s_ashr_i32 s19, s19, 31
	v_mul_f32_e32 v15, 0x4f7ffffe, v15
	v_cvt_u32_f32_e32 v15, v15
	v_cmp_lt_i32_e32 vcc, v13, v14
	v_readfirstlane_b32 s23, v15
	s_mul_i32 s22, s22, s23
	s_mul_hi_u32 s22, s23, s22
	s_add_i32 s23, s23, s22
	s_mul_hi_u32 s22, s11, s23
	s_mul_i32 s23, s22, s16
	s_sub_i32 s11, s11, s23
	s_add_i32 s24, s22, 1
	s_sub_i32 s23, s11, s16
	s_cmp_ge_u32 s11, s16
	s_cselect_b32 s22, s24, s22
	s_cselect_b32 s11, s23, s11
	s_add_i32 s23, s22, 1
	s_cmp_ge_u32 s11, s16
	s_cselect_b32 s11, s23, s22
	s_xor_b32 s11, s11, s19
	s_sub_i32 s16, s11, s19
	s_mul_i32 s11, s16, s18
	s_sub_i32 s10, s10, s11
	s_add_i32 s17, s17, s10
	v_lshl_add_u32 v16, s17, 8, v1
	v_ashrrev_i32_e32 v17, 31, v16
	v_lshlrev_b64 v[16:17], 6, v[16:17]
	v_lshl_add_u64 v[24:25], v[4:5], 0, v[16:17]
	global_load_dwordx4 v[164:167], v[24:25], off
	global_load_dwordx4 v[168:171], v[24:25], off offset:16
	s_and_saveexec_b64 s[10:11], s[4:5]
	s_ashr_i32 s18, s17, 4
	s_lshl_b32 s16, s16, 8
	s_ashr_i32 s17, s16, 31
	s_mul_hi_i32 s19, s18, 0x5800
	s_mulk_i32 s18, 0x5800
	s_add_u32 s18, s12, s18
	s_addc_u32 s19, s13, s19
	s_lshl_b64 s[16:17], s[16:17], 2
	s_add_u32 s16, s18, s16
	s_addc_u32 s17, s19, s17
	global_load_dword v172, v12, s[16:17]
	s_or_b64 exec, exec, s[10:11]
	s_add_u32 s8, s8, s33
	s_addc_u32 s9, s9, s36
	s_add_i32 s99, s99, 1
